# v16 + a priority dip (s_setprio 0 / s_setprio 1) after every 8 MFMAs of the K-loop MFMA segments (was every 16)
# speedup vs baseline: 1.0091x; 1.0007x over previous
; #define GAS __attribute__((address_space(1)))
; #define PG8_STAGE(bufoff, gbase, voff) do { _Pragma("unroll") for (int _i = 0; _i < 2; ++_i) \
;         __builtin_amdgcn_global_load_lds((const GAS unsigned*)((const GAS char*)(gbase) + (voff)[_i]), (LAS unsigned*)(lds + (bufoff) + ldsw + _i * 8192), 16, 0, 0); } while (0)
; #define PG8_LDA(dst, b, h) do { _Pragma("unroll") for (int m = 0; m < 4; ++m) _Pragma("unroll") for (int k = 0; k < 2; ++k) dst[m][k] = *(const LAS bf16x8*)(lds + PG8_SA(b, h) + aoff + m * 2048 + k * 1024); } while (0)
; #define PG8_LDB(dst, b, h) do { _Pragma("unroll") for (int n = 0; n < 2; ++n) _Pragma("unroll") for (int k = 0; k < 2; ++k) dst[n][k] = *(const LAS bf16x8*)(lds + PG8_SB(b, h) + boff + n * 2048 + k * 1024); } while (0)
; #define PG8_MMA(ai, bj, At, Bt) do { __builtin_amdgcn_s_setprio(1); _Pragma("unroll") for (int m = 0; m < 4; ++m) _Pragma("unroll") for (int n = 0; n < 2; ++n) _Pragma("unroll") for (int k = 0; k < 2; ++k) \
;         acc[ai][bj][m][n] = __builtin_amdgcn_mfma_f32_16x16x32_bf16(Bt[n][k], At[m][k], acc[ai][bj][m][n], 0, 0, 0); __builtin_amdgcn_s_setprio(0); } while (0)
; #define PG8_WAIT_V(n) asm volatile("s_waitcnt vmcnt(" #n ")" ::: "memory")
; #define PG8_WAIT_L(n) asm volatile("s_waitcnt lgkmcnt(" #n ")" ::: "memory")
; #define PG8_BAR __builtin_amdgcn_s_barrier()
; #define PG8_SCHED __builtin_amdgcn_sched_barrier(0)
; template <class Epi, class Sched, bool ALIGN_EPI>
; __device__ __forceinline__ void gemm_phase(LAS unsigned char* lds, const Gemm g, const Sched& S, const Epi& E, int wave_id) {
;     ...
;             const bool last = (t == nt - 2);
;             const GAS char* a1 = cA + (size_t)(t + 1) * kstep;
;             const GAS char* a2 = last ? nA : cA + (size_t)(t + 2) * kstep; const GAS char* b2 = last ? nB : cB + (size_t)(t + 2) * kstep;
;             const GAS char* a3 = a2 + kstep; const GAS char* b3 = b2 + kstep;
;             PG8_LDB(B0, 0, 0); PG8_LDB(B1, 0, 1); PG8_SCHED; PG8_LDA(At, 0, 0); PG8_STAGE(PG8_SA(1, 1), a1 + hsA, voffA);
;             PG8_WAIT_V(8); PG8_WAIT_L(0); PG8_BAR; PG8_MMA(0, 0, At, B0); PG8_MMA(0, 1, At, B1); PG8_BAR; PG8_SCHED;
;             PG8_LDA(At, 0, 1); PG8_STAGE(PG8_SB(0, 0), b2, voffB); PG8_STAGE(PG8_SB(0, 1), b2 + hsB, voffB); PG8_STAGE(PG8_SA(0, 0), a2, voffA);
.LBB0_1117:
	s_add_u32 s58, s0, 0xfff80080
	s_addc_u32 s59, s1, -1
	s_cmp_eq_u32 s76, 28
	s_cselect_b32 s61, s33, s59
	s_cselect_b32 s60, s47, s58
	s_cselect_b32 s59, s49, s74
	s_cselect_b32 s58, s57, s71
	s_mov_b32 m0, s87
	v_lshl_add_u64 v[206:207], s[0:1], 0, v[204:205]
	global_load_lds_dwordx4 v[206:207], off
	v_lshl_add_u64 v[206:207], s[0:1], 0, v[202:203]
	s_mov_b32 m0, s88
	s_nop 0
	global_load_lds_dwordx4 v[206:207], off
	v_add_u32_e32 v0, 0x10400, v250
	ds_read_b128 v[130:133], v0
	ds_read_b128 v[134:137], v0 offset:1024
	ds_read_b128 v[138:141], v0 offset:2048
	ds_read_b128 v[142:145], v0 offset:3072
	v_add_u32_e32 v0, 0x14400, v250
	ds_read_b128 v[146:149], v0
	ds_read_b128 v[150:153], v0 offset:1024
	ds_read_b128 v[154:157], v0 offset:2048
	ds_read_b128 v[158:161], v0 offset:3072
	ds_read_b128 v[162:165], v253 offset:1024
	ds_read_b128 v[166:169], v253 offset:2048
	ds_read_b128 v[170:173], v253 offset:3072
	ds_read_b128 v[174:177], v253 offset:4096
	ds_read_b128 v[178:181], v253 offset:5120
	ds_read_b128 v[182:185], v253 offset:6144
	ds_read_b128 v[186:189], v253 offset:7168
	ds_read_b128 v[190:193], v253 offset:8192
	s_waitcnt vmcnt(8)
	s_waitcnt lgkmcnt(0)
	s_setprio 1
	s_barrier
	v_mfma_f32_16x16x32_bf16 v[126:129], v[130:133], v[162:165], v[126:129]
	v_mfma_f32_16x16x32_bf16 v[122:125], v[138:141], v[162:165], v[122:125]
	v_mfma_f32_16x16x32_bf16 v[110:113], v[130:133], v[170:173], v[110:113]
	v_mfma_f32_16x16x32_bf16 v[106:109], v[138:141], v[170:173], v[106:109]
	v_mfma_f32_16x16x32_bf16 v[94:97], v[130:133], v[178:181], v[94:97]
	v_mfma_f32_16x16x32_bf16 v[90:93], v[138:141], v[178:181], v[90:93]
	v_mfma_f32_16x16x32_bf16 v[78:81], v[130:133], v[186:189], v[78:81]
	v_mfma_f32_16x16x32_bf16 v[74:77], v[138:141], v[186:189], v[74:77]
	s_setprio 0
	s_setprio 1
	v_mfma_f32_16x16x32_bf16 v[126:129], v[134:137], v[166:169], v[126:129]
	v_mfma_f32_16x16x32_bf16 v[122:125], v[142:145], v[166:169], v[122:125]
	v_mfma_f32_16x16x32_bf16 v[110:113], v[134:137], v[174:177], v[110:113]
	v_mfma_f32_16x16x32_bf16 v[106:109], v[142:145], v[174:177], v[106:109]
	v_mfma_f32_16x16x32_bf16 v[94:97], v[134:137], v[182:185], v[94:97]
	v_mfma_f32_16x16x32_bf16 v[90:93], v[142:145], v[182:185], v[90:93]
	v_mfma_f32_16x16x32_bf16 v[78:81], v[134:137], v[190:193], v[78:81]
	v_mfma_f32_16x16x32_bf16 v[74:77], v[142:145], v[190:193], v[74:77]
	s_setprio 0
	s_setprio 1
	v_mfma_f32_16x16x32_bf16 v[118:121], v[146:149], v[162:165], v[118:121]
	v_mfma_f32_16x16x32_bf16 v[114:117], v[154:157], v[162:165], v[114:117]
	v_mfma_f32_16x16x32_bf16 v[102:105], v[146:149], v[170:173], v[102:105]
	v_mfma_f32_16x16x32_bf16 v[98:101], v[154:157], v[170:173], v[98:101]
	v_mfma_f32_16x16x32_bf16 v[86:89], v[146:149], v[178:181], v[86:89]
	v_mfma_f32_16x16x32_bf16 v[82:85], v[154:157], v[178:181], v[82:85]
	v_mfma_f32_16x16x32_bf16 v[70:73], v[146:149], v[186:189], v[70:73]
	v_mfma_f32_16x16x32_bf16 v[66:69], v[154:157], v[186:189], v[66:69]
	s_setprio 0
	s_setprio 1
	v_mfma_f32_16x16x32_bf16 v[118:121], v[150:153], v[166:169], v[118:121]
	v_mfma_f32_16x16x32_bf16 v[114:117], v[158:161], v[166:169], v[114:117]
	v_mfma_f32_16x16x32_bf16 v[102:105], v[150:153], v[174:177], v[102:105]
	v_mfma_f32_16x16x32_bf16 v[98:101], v[158:161], v[174:177], v[98:101]
	v_mfma_f32_16x16x32_bf16 v[86:89], v[150:153], v[182:185], v[86:89]
	v_mfma_f32_16x16x32_bf16 v[82:85], v[158:161], v[182:185], v[82:85]
	v_mfma_f32_16x16x32_bf16 v[70:73], v[150:153], v[190:193], v[70:73]
	v_mfma_f32_16x16x32_bf16 v[66:69], v[158:161], v[190:193], v[66:69]
	s_setprio 0
	s_barrier
	s_mov_b32 m0, s15
	v_lshl_add_u64 v[206:207], s[58:59], 0, v[196:197]
	s_add_u32 vcc_lo, s58, 0x80000
	global_load_lds_dwordx4 v[206:207], off
	v_lshl_add_u64 v[208:209], s[58:59], 0, v[200:201]
	s_mov_b32 m0, s73
	s_addc_u32 vcc_hi, s59, 0
	global_load_lds_dwordx4 v[208:209], off
	v_lshl_add_u64 v[210:211], vcc, 0, v[196:197]
	s_mov_b32 m0, s75
	v_lshl_add_u64 v[212:213], s[60:61], 0, v[198:199]
	global_load_lds_dwordx4 v[210:211], off
	v_lshl_add_u64 v[210:211], vcc, 0, v[200:201]
	s_mov_b32 m0, s80
	s_nop 0
	global_load_lds_dwordx4 v[210:211], off
	v_lshl_add_u64 v[210:211], s[60:61], 0, v[194:195]
	s_mov_b32 m0, s81
	s_nop 0
	global_load_lds_dwordx4 v[210:211], off
	s_mov_b32 m0, s82
	s_nop 0
	global_load_lds_dwordx4 v[212:213], off
	ds_read_b128 v[162:165], v253 offset:17408
	ds_read_b128 v[166:169], v253 offset:18432
	ds_read_b128 v[170:173], v253 offset:19456
	ds_read_b128 v[174:177], v253 offset:20480
	ds_read_b128 v[178:181], v253 offset:21504
	ds_read_b128 v[182:185], v253 offset:22528
	ds_read_b128 v[186:189], v253 offset:23552
	ds_read_b128 v[190:193], v253 offset:24576
	s_waitcnt vmcnt(8)
	s_waitcnt lgkmcnt(0)
	s_setprio 1
	s_barrier
; #define PG8_STAGE(bufoff, gbase, voff) do { _Pragma("unroll") for (int _i = 0; _i < 2; ++_i) \
;         __builtin_amdgcn_global_load_lds((const GAS unsigned*)((const GAS char*)(gbase) + (voff)[_i]), (LAS unsigned*)(lds + (bufoff) + ldsw + _i * 8192), 16, 0, 0); } while (0)
; #define PG8_LDA(dst, b, h) do { _Pragma("unroll") for (int m = 0; m < 4; ++m) _Pragma("unroll") for (int k = 0; k < 2; ++k) dst[m][k] = *(const LAS bf16x8*)(lds + PG8_SA(b, h) + aoff + m * 2048 + k * 1024); } while (0)
; #define PG8_LDB(dst, b, h) do { _Pragma("unroll") for (int n = 0; n < 2; ++n) _Pragma("unroll") for (int k = 0; k < 2; ++k) dst[n][k] = *(const LAS bf16x8*)(lds + PG8_SB(b, h) + boff + n * 2048 + k * 1024); } while (0)
; #define PG8_MMA(ai, bj, At, Bt) do { __builtin_amdgcn_s_setprio(1); _Pragma("unroll") for (int m = 0; m < 4; ++m) _Pragma("unroll") for (int n = 0; n < 2; ++n) _Pragma("unroll") for (int k = 0; k < 2; ++k) \
;         acc[ai][bj][m][n] = __builtin_amdgcn_mfma_f32_16x16x32_bf16(Bt[n][k], At[m][k], acc[ai][bj][m][n], 0, 0, 0); __builtin_amdgcn_s_setprio(0); } while (0)
; #define PG8_WAIT_V(n) asm volatile("s_waitcnt vmcnt(" #n ")" ::: "memory")
; #define PG8_WAIT_L(n) asm volatile("s_waitcnt lgkmcnt(" #n ")" ::: "memory")
; #define PG8_BAR __builtin_amdgcn_s_barrier()
; #define PG8_SCHED __builtin_amdgcn_sched_barrier(0)
; template <class Epi, class Sched, bool ALIGN_EPI>
; __device__ __forceinline__ void gemm_phase(LAS unsigned char* lds, const Gemm g, const Sched& S, const Epi& E, int wave_id) {
;     ...
;             PG8_WAIT_V(8); PG8_WAIT_L(0); PG8_BAR; PG8_MMA(1, 0, At, B0); PG8_MMA(1, 1, At, B1); PG8_BAR; PG8_SCHED;
;             PG8_LDB(B0, 1, 0); PG8_LDB(B1, 1, 1); PG8_SCHED; PG8_LDA(At, 1, 0); PG8_STAGE(PG8_SA(0, 1), a2 + hsA, voffA);
;             PG8_WAIT_V(8); PG8_WAIT_L(0); PG8_BAR; PG8_MMA(0, 0, At, B0); PG8_MMA(0, 1, At, B1); PG8_BAR; PG8_SCHED;
	v_mfma_f32_16x16x32_bf16 v[62:65], v[130:133], v[162:165], v[62:65]
	v_mfma_f32_16x16x32_bf16 v[58:61], v[138:141], v[162:165], v[58:61]
	v_mfma_f32_16x16x32_bf16 v[46:49], v[130:133], v[170:173], v[46:49]
	v_mfma_f32_16x16x32_bf16 v[42:45], v[138:141], v[170:173], v[42:45]
	v_mfma_f32_16x16x32_bf16 v[30:33], v[130:133], v[178:181], v[30:33]
	v_mfma_f32_16x16x32_bf16 v[26:29], v[138:141], v[178:181], v[26:29]
	v_mfma_f32_16x16x32_bf16 v[14:17], v[130:133], v[186:189], v[14:17]
	v_mfma_f32_16x16x32_bf16 v[10:13], v[138:141], v[186:189], v[10:13]
	s_setprio 0
	s_setprio 1
	v_mfma_f32_16x16x32_bf16 v[62:65], v[134:137], v[166:169], v[62:65]
	v_mfma_f32_16x16x32_bf16 v[58:61], v[142:145], v[166:169], v[58:61]
	v_mfma_f32_16x16x32_bf16 v[46:49], v[134:137], v[174:177], v[46:49]
	v_mfma_f32_16x16x32_bf16 v[42:45], v[142:145], v[174:177], v[42:45]
	v_mfma_f32_16x16x32_bf16 v[30:33], v[134:137], v[182:185], v[30:33]
	v_mfma_f32_16x16x32_bf16 v[26:29], v[142:145], v[182:185], v[26:29]
	v_mfma_f32_16x16x32_bf16 v[14:17], v[134:137], v[190:193], v[14:17]
	v_mfma_f32_16x16x32_bf16 v[10:13], v[142:145], v[190:193], v[10:13]
	s_setprio 0
	s_setprio 1
	v_mfma_f32_16x16x32_bf16 v[54:57], v[146:149], v[162:165], v[54:57]
	v_mfma_f32_16x16x32_bf16 v[50:53], v[154:157], v[162:165], v[50:53]
	v_mfma_f32_16x16x32_bf16 v[38:41], v[146:149], v[170:173], v[38:41]
	v_mfma_f32_16x16x32_bf16 v[34:37], v[154:157], v[170:173], v[34:37]
	v_mfma_f32_16x16x32_bf16 v[22:25], v[146:149], v[178:181], v[22:25]
	v_mfma_f32_16x16x32_bf16 v[18:21], v[154:157], v[178:181], v[18:21]
	v_mfma_f32_16x16x32_bf16 v[6:9], v[146:149], v[186:189], v[6:9]
	v_mfma_f32_16x16x32_bf16 v[2:5], v[154:157], v[186:189], v[2:5]
	s_setprio 0
	s_setprio 1
	v_mfma_f32_16x16x32_bf16 v[54:57], v[150:153], v[166:169], v[54:57]
	v_mfma_f32_16x16x32_bf16 v[50:53], v[158:161], v[166:169], v[50:53]
	v_mfma_f32_16x16x32_bf16 v[38:41], v[150:153], v[174:177], v[38:41]
	v_mfma_f32_16x16x32_bf16 v[34:37], v[158:161], v[174:177], v[34:37]
	v_mfma_f32_16x16x32_bf16 v[22:25], v[150:153], v[182:185], v[22:25]
	v_mfma_f32_16x16x32_bf16 v[18:21], v[158:161], v[182:185], v[18:21]
	v_mfma_f32_16x16x32_bf16 v[6:9], v[150:153], v[190:193], v[6:9]
	v_mfma_f32_16x16x32_bf16 v[2:5], v[158:161], v[190:193], v[2:5]
	s_setprio 0
	s_barrier
	s_add_u32 s60, s60, 0x80000
	s_addc_u32 s61, s61, 0
	s_mov_b32 m0, s83
	v_lshl_add_u64 v[214:215], s[60:61], 0, v[194:195]
	global_load_lds_dwordx4 v[214:215], off
	v_lshl_add_u64 v[214:215], s[60:61], 0, v[198:199]
	s_mov_b32 m0, s84
	s_nop 0
	global_load_lds_dwordx4 v[214:215], off
	v_add_u32_e32 v0, 0x18400, v250
	ds_read_b128 v[130:133], v0
	ds_read_b128 v[134:137], v0 offset:1024
	ds_read_b128 v[138:141], v0 offset:2048
	ds_read_b128 v[142:145], v0 offset:3072
	v_add_u32_e32 v0, 0x1c400, v250
	ds_read_b128 v[146:149], v0
	ds_read_b128 v[150:153], v0 offset:1024
	ds_read_b128 v[154:157], v0 offset:2048
	ds_read_b128 v[158:161], v0 offset:3072
	ds_read_b128 v[162:165], v253 offset:33792
	ds_read_b128 v[166:169], v253 offset:34816
	ds_read_b128 v[170:173], v253 offset:35840
	ds_read_b128 v[174:177], v253 offset:36864
	ds_read_b128 v[178:181], v253 offset:37888
	ds_read_b128 v[182:185], v253 offset:38912
	ds_read_b128 v[186:189], v253 offset:39936
	ds_read_b128 v[190:193], v253 offset:40960
	s_waitcnt vmcnt(8)
	s_waitcnt lgkmcnt(0)
	s_setprio 1
	s_barrier
	v_mfma_f32_16x16x32_bf16 v[126:129], v[130:133], v[162:165], v[126:129]
	v_mfma_f32_16x16x32_bf16 v[122:125], v[138:141], v[162:165], v[122:125]
	v_mfma_f32_16x16x32_bf16 v[110:113], v[130:133], v[170:173], v[110:113]
	v_mfma_f32_16x16x32_bf16 v[106:109], v[138:141], v[170:173], v[106:109]
	v_mfma_f32_16x16x32_bf16 v[94:97], v[130:133], v[178:181], v[94:97]
	v_mfma_f32_16x16x32_bf16 v[90:93], v[138:141], v[178:181], v[90:93]
	v_mfma_f32_16x16x32_bf16 v[78:81], v[130:133], v[186:189], v[78:81]
	v_mfma_f32_16x16x32_bf16 v[74:77], v[138:141], v[186:189], v[74:77]
	s_setprio 0
	s_setprio 1
	v_mfma_f32_16x16x32_bf16 v[126:129], v[134:137], v[166:169], v[126:129]
	v_mfma_f32_16x16x32_bf16 v[122:125], v[142:145], v[166:169], v[122:125]
	v_mfma_f32_16x16x32_bf16 v[110:113], v[134:137], v[174:177], v[110:113]
	v_mfma_f32_16x16x32_bf16 v[106:109], v[142:145], v[174:177], v[106:109]
	v_mfma_f32_16x16x32_bf16 v[94:97], v[134:137], v[182:185], v[94:97]
	v_mfma_f32_16x16x32_bf16 v[90:93], v[142:145], v[182:185], v[90:93]
	v_mfma_f32_16x16x32_bf16 v[78:81], v[134:137], v[190:193], v[78:81]
	v_mfma_f32_16x16x32_bf16 v[74:77], v[142:145], v[190:193], v[74:77]
	s_setprio 0
	s_setprio 1
	v_mfma_f32_16x16x32_bf16 v[118:121], v[146:149], v[162:165], v[118:121]
	v_mfma_f32_16x16x32_bf16 v[114:117], v[154:157], v[162:165], v[114:117]
	v_mfma_f32_16x16x32_bf16 v[102:105], v[146:149], v[170:173], v[102:105]
	v_mfma_f32_16x16x32_bf16 v[98:101], v[154:157], v[170:173], v[98:101]
	v_mfma_f32_16x16x32_bf16 v[86:89], v[146:149], v[178:181], v[86:89]
	v_mfma_f32_16x16x32_bf16 v[82:85], v[154:157], v[178:181], v[82:85]
	v_mfma_f32_16x16x32_bf16 v[70:73], v[146:149], v[186:189], v[70:73]
	v_mfma_f32_16x16x32_bf16 v[66:69], v[154:157], v[186:189], v[66:69]
	s_setprio 0
	s_setprio 1
	v_mfma_f32_16x16x32_bf16 v[118:121], v[150:153], v[166:169], v[118:121]
	v_mfma_f32_16x16x32_bf16 v[114:117], v[158:161], v[166:169], v[114:117]
	v_mfma_f32_16x16x32_bf16 v[102:105], v[150:153], v[174:177], v[102:105]
	v_mfma_f32_16x16x32_bf16 v[98:101], v[158:161], v[174:177], v[98:101]
	v_mfma_f32_16x16x32_bf16 v[86:89], v[150:153], v[182:185], v[86:89]
	v_mfma_f32_16x16x32_bf16 v[82:85], v[158:161], v[182:185], v[82:85]
	v_mfma_f32_16x16x32_bf16 v[70:73], v[150:153], v[190:193], v[70:73]
	v_mfma_f32_16x16x32_bf16 v[66:69], v[158:161], v[190:193], v[66:69]
	s_setprio 0
	s_barrier
; #define PG8_STAGE(bufoff, gbase, voff) do { _Pragma("unroll") for (int _i = 0; _i < 2; ++_i) \
;         __builtin_amdgcn_global_load_lds((const GAS unsigned*)((const GAS char*)(gbase) + (voff)[_i]), (LAS unsigned*)(lds + (bufoff) + ldsw + _i * 8192), 16, 0, 0); } while (0)
; #define PG8_LDA(dst, b, h) do { _Pragma("unroll") for (int m = 0; m < 4; ++m) _Pragma("unroll") for (int k = 0; k < 2; ++k) dst[m][k] = *(const LAS bf16x8*)(lds + PG8_SA(b, h) + aoff + m * 2048 + k * 1024); } while (0)
; #define PG8_MMA(ai, bj, At, Bt) do { __builtin_amdgcn_s_setprio(1); _Pragma("unroll") for (int m = 0; m < 4; ++m) _Pragma("unroll") for (int n = 0; n < 2; ++n) _Pragma("unroll") for (int k = 0; k < 2; ++k) \
;         acc[ai][bj][m][n] = __builtin_amdgcn_mfma_f32_16x16x32_bf16(Bt[n][k], At[m][k], acc[ai][bj][m][n], 0, 0, 0); __builtin_amdgcn_s_setprio(0); } while (0)
; #define PG8_WAIT_V(n) asm volatile("s_waitcnt vmcnt(" #n ")" ::: "memory")
; #define PG8_WAIT_L(n) asm volatile("s_waitcnt lgkmcnt(" #n ")" ::: "memory")
; #define PG8_BAR __builtin_amdgcn_s_barrier()
; #define PG8_SCHED __builtin_amdgcn_sched_barrier(0)
; template <class Epi, class Sched, bool ALIGN_EPI>
; __device__ __forceinline__ void gemm_phase(LAS unsigned char* lds, const Gemm g, const Sched& S, const Epi& E, int wave_id) {
;     ...
;             PG8_LDA(At, 1, 1); PG8_STAGE(PG8_SB(1, 0), b3, voffB); PG8_STAGE(PG8_SB(1, 1), b3 + hsB, voffB); PG8_STAGE(PG8_SA(1, 0), a3, voffA);
;             PG8_WAIT_V(8); PG8_WAIT_L(0); PG8_BAR; PG8_MMA(1, 0, At, B0); PG8_MMA(1, 1, At, B1); PG8_BAR; PG8_SCHED;
;         }
;         if constexpr (ALIGN_EPI) { if (wr == 0) PG8_BAR; }
	s_mov_b32 m0, s95
	v_lshl_add_u64 v[206:207], v[206:207], 0, s[92:93]
	s_add_u32 s58, s58, 0x80080
	global_load_lds_dwordx4 v[206:207], off
	v_lshl_add_u64 v[206:207], v[208:209], 0, s[92:93]
	s_mov_b32 m0, s96
	s_addc_u32 s59, s59, 0
	global_load_lds_dwordx4 v[206:207], off
	v_lshl_add_u64 v[206:207], s[58:59], 0, v[196:197]
	s_mov_b32 m0, s17
	s_nop 0
	global_load_lds_dwordx4 v[206:207], off
	v_lshl_add_u64 v[206:207], s[58:59], 0, v[200:201]
	s_mov_b32 m0, s18
	s_nop 0
	global_load_lds_dwordx4 v[206:207], off
	v_lshl_add_u64 v[206:207], v[210:211], 0, s[92:93]
	s_mov_b32 m0, s97
	s_nop 0
	global_load_lds_dwordx4 v[206:207], off
	v_lshl_add_u64 v[206:207], v[212:213], 0, s[92:93]
	s_mov_b32 m0, s16
	s_nop 0
	global_load_lds_dwordx4 v[206:207], off
	ds_read_b128 v[162:165], v253 offset:50176
	ds_read_b128 v[166:169], v253 offset:51200
	ds_read_b128 v[170:173], v253 offset:52224
	ds_read_b128 v[174:177], v253 offset:53248
	ds_read_b128 v[178:181], v253 offset:54272
	ds_read_b128 v[182:185], v253 offset:55296
	ds_read_b128 v[186:189], v253 offset:56320
	ds_read_b128 v[190:193], v253 offset:57344
	s_waitcnt vmcnt(8)
	s_waitcnt lgkmcnt(0)
	s_setprio 1
	s_barrier
	v_mfma_f32_16x16x32_bf16 v[62:65], v[130:133], v[162:165], v[62:65]
	v_mfma_f32_16x16x32_bf16 v[58:61], v[138:141], v[162:165], v[58:61]
	v_mfma_f32_16x16x32_bf16 v[46:49], v[130:133], v[170:173], v[46:49]
	v_mfma_f32_16x16x32_bf16 v[42:45], v[138:141], v[170:173], v[42:45]
	v_mfma_f32_16x16x32_bf16 v[30:33], v[130:133], v[178:181], v[30:33]
	v_mfma_f32_16x16x32_bf16 v[26:29], v[138:141], v[178:181], v[26:29]
	v_mfma_f32_16x16x32_bf16 v[14:17], v[130:133], v[186:189], v[14:17]
	v_mfma_f32_16x16x32_bf16 v[10:13], v[138:141], v[186:189], v[10:13]
	s_setprio 0
	s_setprio 1
	v_mfma_f32_16x16x32_bf16 v[62:65], v[134:137], v[166:169], v[62:65]
	v_mfma_f32_16x16x32_bf16 v[58:61], v[142:145], v[166:169], v[58:61]
	v_mfma_f32_16x16x32_bf16 v[46:49], v[134:137], v[174:177], v[46:49]
	v_mfma_f32_16x16x32_bf16 v[42:45], v[142:145], v[174:177], v[42:45]
	v_mfma_f32_16x16x32_bf16 v[30:33], v[134:137], v[182:185], v[30:33]
	v_mfma_f32_16x16x32_bf16 v[26:29], v[142:145], v[182:185], v[26:29]
	v_mfma_f32_16x16x32_bf16 v[14:17], v[134:137], v[190:193], v[14:17]
	v_mfma_f32_16x16x32_bf16 v[10:13], v[142:145], v[190:193], v[10:13]
	s_setprio 0
	s_setprio 1
	v_mfma_f32_16x16x32_bf16 v[54:57], v[146:149], v[162:165], v[54:57]
	v_mfma_f32_16x16x32_bf16 v[50:53], v[154:157], v[162:165], v[50:53]
	v_mfma_f32_16x16x32_bf16 v[38:41], v[146:149], v[170:173], v[38:41]
	v_mfma_f32_16x16x32_bf16 v[34:37], v[154:157], v[170:173], v[34:37]
	v_mfma_f32_16x16x32_bf16 v[22:25], v[146:149], v[178:181], v[22:25]
	v_mfma_f32_16x16x32_bf16 v[18:21], v[154:157], v[178:181], v[18:21]
	v_mfma_f32_16x16x32_bf16 v[6:9], v[146:149], v[186:189], v[6:9]
	v_mfma_f32_16x16x32_bf16 v[2:5], v[154:157], v[186:189], v[2:5]
	s_setprio 0
	s_setprio 1
	v_mfma_f32_16x16x32_bf16 v[54:57], v[150:153], v[166:169], v[54:57]
	v_mfma_f32_16x16x32_bf16 v[50:53], v[158:161], v[166:169], v[50:53]
	v_mfma_f32_16x16x32_bf16 v[38:41], v[150:153], v[174:177], v[38:41]
	v_mfma_f32_16x16x32_bf16 v[34:37], v[158:161], v[174:177], v[34:37]
	v_mfma_f32_16x16x32_bf16 v[22:25], v[150:153], v[182:185], v[22:25]
	v_mfma_f32_16x16x32_bf16 v[18:21], v[158:161], v[182:185], v[18:21]
	v_mfma_f32_16x16x32_bf16 v[6:9], v[150:153], v[190:193], v[6:9]
	v_mfma_f32_16x16x32_bf16 v[2:5], v[158:161], v[190:193], v[2:5]
	s_setprio 0
	s_barrier
	s_add_i32 s76, s76, 2
	s_add_u32 s71, s71, 0x100
	s_addc_u32 s74, s74, 0
	s_add_u32 s0, s0, 0x100
	s_addc_u32 s1, s1, 0
	s_cmp_gt_u32 s76, 29
	s_cbranch_scc0 .LBB0_1117
	s_and_b64 vcc, exec, s[44:45]
	s_cbranch_vccz .LBB0_1120
	s_barrier

; #define GAS __attribute__((address_space(1)))
; #define PG8_STAGE(bufoff, gbase, voff) do { _Pragma("unroll") for (int _i = 0; _i < 2; ++_i) \
;         __builtin_amdgcn_global_load_lds((const GAS unsigned*)((const GAS char*)(gbase) + (voff)[_i]), (LAS unsigned*)(lds + (bufoff) + ldsw + _i * 8192), 16, 0, 0); } while (0)
; #define PG8_LDA(dst, b, h) do { _Pragma("unroll") for (int m = 0; m < 4; ++m) _Pragma("unroll") for (int k = 0; k < 2; ++k) dst[m][k] = *(const LAS bf16x8*)(lds + PG8_SA(b, h) + aoff + m * 2048 + k * 1024); } while (0)
; #define PG8_LDB(dst, b, h) do { _Pragma("unroll") for (int n = 0; n < 2; ++n) _Pragma("unroll") for (int k = 0; k < 2; ++k) dst[n][k] = *(const LAS bf16x8*)(lds + PG8_SB(b, h) + boff + n * 2048 + k * 1024); } while (0)
; #define PG8_MMA(ai, bj, At, Bt) do { __builtin_amdgcn_s_setprio(1); _Pragma("unroll") for (int m = 0; m < 4; ++m) _Pragma("unroll") for (int n = 0; n < 2; ++n) _Pragma("unroll") for (int k = 0; k < 2; ++k) \
;         acc[ai][bj][m][n] = __builtin_amdgcn_mfma_f32_16x16x32_bf16(Bt[n][k], At[m][k], acc[ai][bj][m][n], 0, 0, 0); __builtin_amdgcn_s_setprio(0); } while (0)
; #define PG8_WAIT_V(n) asm volatile("s_waitcnt vmcnt(" #n ")" ::: "memory")
; #define PG8_WAIT_L(n) asm volatile("s_waitcnt lgkmcnt(" #n ")" ::: "memory")
; #define PG8_BAR __builtin_amdgcn_s_barrier()
; template <class Epi, class Sched, bool ALIGN_EPI>
; __device__ __forceinline__ void gemm_phase(LAS unsigned char* lds, const Gemm g, const Sched& S, const Epi& E, int wave_id) {
;     ...
;             const bool last = (t == nt - 2);
;             const GAS char* a1 = cA + (size_t)(t + 1) * kstep;
;             const GAS char* a2 = last ? nA : cA + (size_t)(t + 2) * kstep; const GAS char* b2 = last ? nB : cB + (size_t)(t + 2) * kstep;
;             const GAS char* a3 = a2 + kstep; const GAS char* b3 = b2 + kstep;
;             PG8_LDB(B0, 0, 0); PG8_LDB(B1, 0, 1); PG8_SCHED; PG8_LDA(At, 0, 0); PG8_STAGE(PG8_SA(1, 1), a1 + hsA, voffA);
;             PG8_WAIT_V(8); PG8_WAIT_L(0); PG8_BAR; PG8_MMA(0, 0, At, B0); PG8_MMA(0, 1, At, B1); PG8_BAR; PG8_SCHED;
;             PG8_LDA(At, 0, 1); PG8_STAGE(PG8_SB(0, 0), b2, voffB); PG8_STAGE(PG8_SB(0, 1), b2 + hsB, voffB); PG8_STAGE(PG8_SA(0, 0), a2, voffA);
;             PG8_WAIT_V(8); PG8_WAIT_L(0); PG8_BAR; PG8_MMA(1, 0, At, B0); PG8_MMA(1, 1, At, B1); PG8_BAR; PG8_SCHED;
.LBB0_1335:
	s_add_u32 s34, s12, s26
	s_addc_u32 s35, s13, s27
	s_add_u32 s30, s34, 0x100
	s_addc_u32 s31, s35, 0
	s_and_b64 s[28:29], s[24:25], exec
	s_cselect_b32 s29, s17, s31
	s_cselect_b32 s28, s16, s30
	s_add_u32 s26, s10, s26
	s_addc_u32 s27, s11, s27
	s_add_u32 s26, s26, 0x100
	s_addc_u32 s27, s27, 0
	s_and_b64 s[24:25], s[24:25], exec
	s_cselect_b32 s31, s60, s27
	s_cselect_b32 s30, s61, s26
	s_add_u32 s36, s34, 0x18080
	s_addc_u32 s37, s35, 0
	s_add_i32 m0, s40, 0xc400
	s_add_i32 s62, s40, 0xe400
	s_add_u32 s34, s30, 0x10000
	s_addc_u32 s35, s31, 0
	s_add_u32 s26, s28, 0x18000
	s_addc_u32 s27, s29, 0
	s_add_u32 s24, s30, 0x10080
	s_addc_u32 s25, s31, 0
	v_lshl_add_u64 v[122:123], s[36:37], 0, v[70:71]
	global_load_lds_dwordx4 v[122:123], off
	v_lshl_add_u64 v[122:123], s[36:37], 0, v[68:69]
	s_mov_b32 m0, s62
	s_nop 0
	global_load_lds_dwordx4 v[122:123], off
	v_add_u32_e32 v86, 0x10400, v73
	ds_read_b128 v[74:77], v86
	ds_read_b128 v[78:81], v86 offset:1024
	ds_read_b128 v[82:85], v86 offset:2048
	ds_read_b128 v[86:89], v86 offset:3072
	ds_read_b128 v[90:93], v72 offset:1024
	ds_read_b128 v[94:97], v72 offset:2048
	ds_read_b128 v[98:101], v72 offset:3072
	ds_read_b128 v[102:105], v72 offset:4096
	ds_read_b128 v[106:109], v72 offset:5120
	ds_read_b128 v[110:113], v72 offset:6144
	ds_read_b128 v[114:117], v72 offset:7168
	ds_read_b128 v[118:121], v72 offset:8192
	s_waitcnt vmcnt(8)
	s_waitcnt lgkmcnt(0)
	s_setprio 1
	s_barrier
	v_mfma_f32_16x16x32_bf16 v[62:65], v[74:77], v[90:93], v[62:65]
	v_mfma_f32_16x16x32_bf16 v[58:61], v[82:85], v[90:93], v[58:61]
	v_mfma_f32_16x16x32_bf16 v[54:57], v[74:77], v[98:101], v[54:57]
	v_mfma_f32_16x16x32_bf16 v[50:53], v[82:85], v[98:101], v[50:53]
	v_mfma_f32_16x16x32_bf16 v[46:49], v[74:77], v[106:109], v[46:49]
	v_mfma_f32_16x16x32_bf16 v[42:45], v[82:85], v[106:109], v[42:45]
	v_mfma_f32_16x16x32_bf16 v[38:41], v[74:77], v[114:117], v[38:41]
	v_mfma_f32_16x16x32_bf16 v[34:37], v[82:85], v[114:117], v[34:37]
	s_setprio 0
	s_setprio 1
	v_mfma_f32_16x16x32_bf16 v[62:65], v[78:81], v[94:97], v[62:65]
	v_mfma_f32_16x16x32_bf16 v[58:61], v[86:89], v[94:97], v[58:61]
	v_mfma_f32_16x16x32_bf16 v[54:57], v[78:81], v[102:105], v[54:57]
	v_mfma_f32_16x16x32_bf16 v[50:53], v[86:89], v[102:105], v[50:53]
	v_mfma_f32_16x16x32_bf16 v[46:49], v[78:81], v[110:113], v[46:49]
	v_mfma_f32_16x16x32_bf16 v[42:45], v[86:89], v[110:113], v[42:45]
	v_mfma_f32_16x16x32_bf16 v[38:41], v[78:81], v[118:121], v[38:41]
	v_mfma_f32_16x16x32_bf16 v[34:37], v[86:89], v[118:121], v[34:37]
	s_setprio 0
	s_setprio 1
	s_setprio 0
	s_barrier
	s_mov_b32 m0, s41
	v_lshl_add_u64 v[122:123], s[30:31], 0, v[0:1]
	global_load_lds_dwordx4 v[122:123], off
	v_lshl_add_u64 v[124:125], s[30:31], 0, v[66:67]
	s_mov_b32 m0, s42
	v_lshl_add_u64 v[126:127], s[34:35], 0, v[0:1]
	global_load_lds_dwordx4 v[124:125], off
	s_mov_b32 m0, s43
	v_lshl_add_u64 v[128:129], s[28:29], 0, v[68:69]
	global_load_lds_dwordx4 v[126:127], off
	v_lshl_add_u64 v[126:127], s[34:35], 0, v[66:67]
	s_mov_b32 m0, s44
	s_nop 0
	global_load_lds_dwordx4 v[126:127], off
	v_lshl_add_u64 v[126:127], s[28:29], 0, v[70:71]
	s_mov_b32 m0, s45
	s_nop 0
	global_load_lds_dwordx4 v[126:127], off
	s_mov_b32 m0, s46
	s_nop 0
	global_load_lds_dwordx4 v[128:129], off
	ds_read_b128 v[90:93], v72 offset:17408
	ds_read_b128 v[94:97], v72 offset:18432
	ds_read_b128 v[98:101], v72 offset:19456
	ds_read_b128 v[102:105], v72 offset:20480
	ds_read_b128 v[106:109], v72 offset:21504
	ds_read_b128 v[110:113], v72 offset:22528
	ds_read_b128 v[114:117], v72 offset:23552
	ds_read_b128 v[118:121], v72 offset:24576
	s_waitcnt vmcnt(8)
	s_waitcnt lgkmcnt(0)
	s_setprio 1
	s_barrier
	v_mfma_f32_16x16x32_bf16 v[30:33], v[74:77], v[90:93], v[30:33]
	v_mfma_f32_16x16x32_bf16 v[26:29], v[82:85], v[90:93], v[26:29]
	v_mfma_f32_16x16x32_bf16 v[22:25], v[74:77], v[98:101], v[22:25]
	v_mfma_f32_16x16x32_bf16 v[18:21], v[82:85], v[98:101], v[18:21]
	v_mfma_f32_16x16x32_bf16 v[14:17], v[74:77], v[106:109], v[14:17]
	v_mfma_f32_16x16x32_bf16 v[10:13], v[82:85], v[106:109], v[10:13]
	v_mfma_f32_16x16x32_bf16 v[6:9], v[74:77], v[114:117], v[6:9]
	v_mfma_f32_16x16x32_bf16 v[2:5], v[82:85], v[114:117], v[2:5]
	s_setprio 0
	s_setprio 1
	v_mfma_f32_16x16x32_bf16 v[30:33], v[78:81], v[94:97], v[30:33]
	v_mfma_f32_16x16x32_bf16 v[26:29], v[86:89], v[94:97], v[26:29]
	v_mfma_f32_16x16x32_bf16 v[22:25], v[78:81], v[102:105], v[22:25]
	v_mfma_f32_16x16x32_bf16 v[18:21], v[86:89], v[102:105], v[18:21]
	v_mfma_f32_16x16x32_bf16 v[14:17], v[78:81], v[110:113], v[14:17]
	v_mfma_f32_16x16x32_bf16 v[10:13], v[86:89], v[110:113], v[10:13]
	v_mfma_f32_16x16x32_bf16 v[6:9], v[78:81], v[118:121], v[6:9]
	v_mfma_f32_16x16x32_bf16 v[2:5], v[86:89], v[118:121], v[2:5]
	s_setprio 0
	s_setprio 1
	s_setprio 0
	s_barrier
; #define PG8_STAGE(bufoff, gbase, voff) do { _Pragma("unroll") for (int _i = 0; _i < 2; ++_i) \
;         __builtin_amdgcn_global_load_lds((const GAS unsigned*)((const GAS char*)(gbase) + (voff)[_i]), (LAS unsigned*)(lds + (bufoff) + ldsw + _i * 8192), 16, 0, 0); } while (0)
; #define PG8_LDA(dst, b, h) do { _Pragma("unroll") for (int m = 0; m < 4; ++m) _Pragma("unroll") for (int k = 0; k < 2; ++k) dst[m][k] = *(const LAS bf16x8*)(lds + PG8_SA(b, h) + aoff + m * 2048 + k * 1024); } while (0)
; #define PG8_LDB(dst, b, h) do { _Pragma("unroll") for (int n = 0; n < 2; ++n) _Pragma("unroll") for (int k = 0; k < 2; ++k) dst[n][k] = *(const LAS bf16x8*)(lds + PG8_SB(b, h) + boff + n * 2048 + k * 1024); } while (0)
; #define PG8_MMA(ai, bj, At, Bt) do { __builtin_amdgcn_s_setprio(1); _Pragma("unroll") for (int m = 0; m < 4; ++m) _Pragma("unroll") for (int n = 0; n < 2; ++n) _Pragma("unroll") for (int k = 0; k < 2; ++k) \
;         acc[ai][bj][m][n] = __builtin_amdgcn_mfma_f32_16x16x32_bf16(Bt[n][k], At[m][k], acc[ai][bj][m][n], 0, 0, 0); __builtin_amdgcn_s_setprio(0); } while (0)
; #define PG8_WAIT_V(n) asm volatile("s_waitcnt vmcnt(" #n ")" ::: "memory")
; #define PG8_WAIT_L(n) asm volatile("s_waitcnt lgkmcnt(" #n ")" ::: "memory")
; #define PG8_BAR __builtin_amdgcn_s_barrier()
; #define PG8_SCHED __builtin_amdgcn_sched_barrier(0)
; template <class Epi, class Sched, bool ALIGN_EPI>
; __device__ __forceinline__ void gemm_phase(LAS unsigned char* lds, const Gemm g, const Sched& S, const Epi& E, int wave_id) {
;     ...
;             PG8_LDB(B0, 1, 0); PG8_LDB(B1, 1, 1); PG8_SCHED; PG8_LDA(At, 1, 0); PG8_STAGE(PG8_SA(0, 1), a2 + hsA, voffA);
;             PG8_WAIT_V(8); PG8_WAIT_L(0); PG8_BAR; PG8_MMA(0, 0, At, B0); PG8_MMA(0, 1, At, B1); PG8_BAR; PG8_SCHED;
;             PG8_LDA(At, 1, 1); PG8_STAGE(PG8_SB(1, 0), b3, voffB); PG8_STAGE(PG8_SB(1, 1), b3 + hsB, voffB); PG8_STAGE(PG8_SA(1, 0), a3, voffA);
;             PG8_WAIT_V(8); PG8_WAIT_L(0); PG8_BAR; PG8_MMA(1, 0, At, B0); PG8_MMA(1, 1, At, B1); PG8_BAR; PG8_SCHED;
;         }
;         if constexpr (ALIGN_EPI) { if (wr == 0) PG8_BAR; }
	s_mov_b32 m0, s47
	v_lshl_add_u64 v[130:131], s[26:27], 0, v[70:71]
	global_load_lds_dwordx4 v[130:131], off
	v_lshl_add_u64 v[130:131], s[26:27], 0, v[68:69]
	s_mov_b32 m0, s48
	s_nop 0
	global_load_lds_dwordx4 v[130:131], off
	v_add_u32_e32 v86, 0x18400, v73
	ds_read_b128 v[74:77], v86
	ds_read_b128 v[78:81], v86 offset:1024
	ds_read_b128 v[82:85], v86 offset:2048
	ds_read_b128 v[86:89], v86 offset:3072
	ds_read_b128 v[90:93], v72 offset:33792
	ds_read_b128 v[94:97], v72 offset:34816
	ds_read_b128 v[98:101], v72 offset:35840
	ds_read_b128 v[102:105], v72 offset:36864
	ds_read_b128 v[106:109], v72 offset:37888
	ds_read_b128 v[110:113], v72 offset:38912
	ds_read_b128 v[114:117], v72 offset:39936
	ds_read_b128 v[118:121], v72 offset:40960
	s_waitcnt vmcnt(8)
	s_waitcnt lgkmcnt(0)
	s_setprio 1
	s_barrier
	v_mfma_f32_16x16x32_bf16 v[62:65], v[74:77], v[90:93], v[62:65]
	v_mfma_f32_16x16x32_bf16 v[58:61], v[82:85], v[90:93], v[58:61]
	v_mfma_f32_16x16x32_bf16 v[54:57], v[74:77], v[98:101], v[54:57]
	v_mfma_f32_16x16x32_bf16 v[50:53], v[82:85], v[98:101], v[50:53]
	v_mfma_f32_16x16x32_bf16 v[46:49], v[74:77], v[106:109], v[46:49]
	v_mfma_f32_16x16x32_bf16 v[42:45], v[82:85], v[106:109], v[42:45]
	v_mfma_f32_16x16x32_bf16 v[38:41], v[74:77], v[114:117], v[38:41]
	v_mfma_f32_16x16x32_bf16 v[34:37], v[82:85], v[114:117], v[34:37]
	s_setprio 0
	s_setprio 1
	v_mfma_f32_16x16x32_bf16 v[62:65], v[78:81], v[94:97], v[62:65]
	v_mfma_f32_16x16x32_bf16 v[58:61], v[86:89], v[94:97], v[58:61]
	v_mfma_f32_16x16x32_bf16 v[54:57], v[78:81], v[102:105], v[54:57]
	v_mfma_f32_16x16x32_bf16 v[50:53], v[86:89], v[102:105], v[50:53]
	v_mfma_f32_16x16x32_bf16 v[46:49], v[78:81], v[110:113], v[46:49]
	v_mfma_f32_16x16x32_bf16 v[42:45], v[86:89], v[110:113], v[42:45]
	v_mfma_f32_16x16x32_bf16 v[38:41], v[78:81], v[118:121], v[38:41]
	v_mfma_f32_16x16x32_bf16 v[34:37], v[86:89], v[118:121], v[34:37]
	s_setprio 0
	s_setprio 1
	s_setprio 0
	s_barrier
	s_mov_b32 m0, s51
	v_lshl_add_u64 v[122:123], v[122:123], 0, s[92:93]
	global_load_lds_dwordx4 v[122:123], off
	v_lshl_add_u64 v[122:123], v[124:125], 0, s[92:93]
	s_mov_b32 m0, s52
	s_nop 0
	global_load_lds_dwordx4 v[122:123], off
	v_lshl_add_u64 v[122:123], s[24:25], 0, v[0:1]
	s_mov_b32 m0, s55
	s_nop 0
	global_load_lds_dwordx4 v[122:123], off
	v_lshl_add_u64 v[122:123], s[24:25], 0, v[66:67]
	s_mov_b32 m0, s56
	s_nop 0
	global_load_lds_dwordx4 v[122:123], off
	v_lshl_add_u64 v[122:123], v[126:127], 0, s[92:93]
	s_mov_b32 m0, s53
	s_nop 0
	global_load_lds_dwordx4 v[122:123], off
	v_lshl_add_u64 v[122:123], v[128:129], 0, s[92:93]
	s_mov_b32 m0, s54
	s_nop 0
	global_load_lds_dwordx4 v[122:123], off
	ds_read_b128 v[90:93], v72 offset:50176
	ds_read_b128 v[94:97], v72 offset:51200
	ds_read_b128 v[98:101], v72 offset:52224
	ds_read_b128 v[102:105], v72 offset:53248
	ds_read_b128 v[106:109], v72 offset:54272
	ds_read_b128 v[110:113], v72 offset:55296
	ds_read_b128 v[114:117], v72 offset:56320
	ds_read_b128 v[118:121], v72 offset:57344
	s_waitcnt vmcnt(8)
	s_waitcnt lgkmcnt(0)
	s_setprio 1
	s_barrier
	v_mfma_f32_16x16x32_bf16 v[30:33], v[74:77], v[90:93], v[30:33]
	v_mfma_f32_16x16x32_bf16 v[26:29], v[82:85], v[90:93], v[26:29]
	v_mfma_f32_16x16x32_bf16 v[22:25], v[74:77], v[98:101], v[22:25]
	v_mfma_f32_16x16x32_bf16 v[18:21], v[82:85], v[98:101], v[18:21]
	v_mfma_f32_16x16x32_bf16 v[14:17], v[74:77], v[106:109], v[14:17]
	v_mfma_f32_16x16x32_bf16 v[10:13], v[82:85], v[106:109], v[10:13]
	v_mfma_f32_16x16x32_bf16 v[6:9], v[74:77], v[114:117], v[6:9]
	v_mfma_f32_16x16x32_bf16 v[2:5], v[82:85], v[114:117], v[2:5]
	s_setprio 0
	s_setprio 1
	v_mfma_f32_16x16x32_bf16 v[30:33], v[78:81], v[94:97], v[30:33]
	v_mfma_f32_16x16x32_bf16 v[26:29], v[86:89], v[94:97], v[26:29]
	v_mfma_f32_16x16x32_bf16 v[22:25], v[78:81], v[102:105], v[22:25]
	v_mfma_f32_16x16x32_bf16 v[18:21], v[86:89], v[102:105], v[18:21]
	v_mfma_f32_16x16x32_bf16 v[14:17], v[78:81], v[110:113], v[14:17]
	v_mfma_f32_16x16x32_bf16 v[10:13], v[86:89], v[110:113], v[10:13]
	v_mfma_f32_16x16x32_bf16 v[6:9], v[78:81], v[118:121], v[6:9]
	v_mfma_f32_16x16x32_bf16 v[2:5], v[86:89], v[118:121], v[2:5]
	s_setprio 0
	s_setprio 1
	s_setprio 0
	s_barrier
	s_andn2_b64 vcc, exec, s[22:23]
	s_mov_b64 s[24:25], -1
	s_mov_b64 s[22:23], 0
	s_mov_b64 s[26:27], 0x100
	s_cbranch_vccz .LBB0_1335
	s_and_b64 vcc, exec, s[14:15]
	s_cbranch_vccz .LBB0_1338
	s_barrier

; #define GAS __attribute__((address_space(1)))
; #define PG8_STAGE(bufoff, gbase, voff) do { _Pragma("unroll") for (int _i = 0; _i < 2; ++_i) \
;         __builtin_amdgcn_global_load_lds((const GAS unsigned*)((const GAS char*)(gbase) + (voff)[_i]), (LAS unsigned*)(lds + (bufoff) + ldsw + _i * 8192), 16, 0, 0); } while (0)
; #define PG8_LDA(dst, b, h) do { _Pragma("unroll") for (int m = 0; m < 4; ++m) _Pragma("unroll") for (int k = 0; k < 2; ++k) dst[m][k] = *(const LAS bf16x8*)(lds + PG8_SA(b, h) + aoff + m * 2048 + k * 1024); } while (0)
; #define PG8_LDB(dst, b, h) do { _Pragma("unroll") for (int n = 0; n < 2; ++n) _Pragma("unroll") for (int k = 0; k < 2; ++k) dst[n][k] = *(const LAS bf16x8*)(lds + PG8_SB(b, h) + boff + n * 2048 + k * 1024); } while (0)
; #define PG8_MMA(ai, bj, At, Bt) do { __builtin_amdgcn_s_setprio(1); _Pragma("unroll") for (int m = 0; m < 4; ++m) _Pragma("unroll") for (int n = 0; n < 2; ++n) _Pragma("unroll") for (int k = 0; k < 2; ++k) \
;         acc[ai][bj][m][n] = __builtin_amdgcn_mfma_f32_16x16x32_bf16(Bt[n][k], At[m][k], acc[ai][bj][m][n], 0, 0, 0); __builtin_amdgcn_s_setprio(0); } while (0)
; #define PG8_WAIT_V(n) asm volatile("s_waitcnt vmcnt(" #n ")" ::: "memory")
; #define PG8_WAIT_L(n) asm volatile("s_waitcnt lgkmcnt(" #n ")" ::: "memory")
; #define PG8_BAR __builtin_amdgcn_s_barrier()
; template <class Epi, class Sched, bool ALIGN_EPI>
; __device__ __forceinline__ void gemm_phase(LAS unsigned char* lds, const Gemm g, const Sched& S, const Epi& E, int wave_id) {
;     ...
;             const bool last = (t == nt - 2);
;             const GAS char* a1 = cA + (size_t)(t + 1) * kstep;
;             const GAS char* a2 = last ? nA : cA + (size_t)(t + 2) * kstep; const GAS char* b2 = last ? nB : cB + (size_t)(t + 2) * kstep;
;             const GAS char* a3 = a2 + kstep; const GAS char* b3 = b2 + kstep;
;             PG8_LDB(B0, 0, 0); PG8_LDB(B1, 0, 1); PG8_SCHED; PG8_LDA(At, 0, 0); PG8_STAGE(PG8_SA(1, 1), a1 + hsA, voffA);
;             PG8_WAIT_V(8); PG8_WAIT_L(0); PG8_BAR; PG8_MMA(0, 0, At, B0); PG8_MMA(0, 1, At, B1); PG8_BAR; PG8_SCHED;
;             PG8_LDA(At, 0, 1); PG8_STAGE(PG8_SB(0, 0), b2, voffB); PG8_STAGE(PG8_SB(0, 1), b2 + hsB, voffB); PG8_STAGE(PG8_SA(0, 0), a2, voffA);
;             PG8_WAIT_V(8); PG8_WAIT_L(0); PG8_BAR; PG8_MMA(1, 0, At, B0); PG8_MMA(1, 1, At, B1); PG8_BAR; PG8_SCHED;
.LBB0_1458:
	s_add_u32 s21, s26, s34
	s_addc_u32 s33, s27, s35
	s_add_u32 s38, s21, 0x100
	s_addc_u32 s39, s33, 0
	s_and_b64 s[36:37], s[30:31], exec
	s_cselect_b32 s37, s3, s39
	s_cselect_b32 s36, s5, s38
	s_add_u32 s34, s6, s34
	s_addc_u32 s35, s7, s35
	s_add_u32 s34, s34, 0x100
	s_addc_u32 s35, s35, 0
	s_and_b64 s[30:31], s[30:31], exec
	s_cselect_b32 s39, s9, s35
	s_cselect_b32 s38, s19, s34
	s_add_u32 s42, s21, 0x10080
	s_addc_u32 s43, s33, 0
	s_add_i32 m0, s49, 0xc400
	s_add_i32 s21, s49, 0xe400
	s_add_u32 s40, s38, 0x10000
	s_addc_u32 s41, s39, 0
	s_add_u32 s34, s36, 0x10000
	s_addc_u32 s35, s37, 0
	s_add_u32 s30, s38, 0x10080
	s_addc_u32 s31, s39, 0
	v_lshl_add_u64 v[2:3], s[42:43], 0, v[140:141]
	global_load_lds_dwordx4 v[2:3], off
	v_lshl_add_u64 v[2:3], s[42:43], 0, v[144:145]
	s_mov_b32 m0, s21
	s_nop 0
	global_load_lds_dwordx4 v[2:3], off
	v_add_u32_e32 v0, 0x10400, v159
	ds_read_b128 v[100:103], v0
	ds_read_b128 v[108:111], v0 offset:1024
	ds_read_b128 v[148:151], v0 offset:2048
	ds_read_b128 v[152:155], v0 offset:3072
	v_add_u32_e32 v0, 0x14400, v159
	ds_read_b128 v[160:163], v0
	ds_read_b128 v[164:167], v0 offset:1024
	ds_read_b128 v[168:171], v0 offset:2048
	ds_read_b128 v[172:175], v0 offset:3072
	ds_read_b128 v[176:179], v158 offset:1024
	ds_read_b128 v[180:183], v158 offset:2048
	ds_read_b128 v[184:187], v158 offset:3072
	ds_read_b128 v[188:191], v158 offset:4096
	ds_read_b128 v[192:195], v158 offset:5120
	ds_read_b128 v[196:199], v158 offset:6144
	ds_read_b128 v[200:203], v158 offset:7168
	ds_read_b128 v[204:207], v158 offset:8192
	s_waitcnt vmcnt(8)
	s_waitcnt lgkmcnt(0)
	s_setprio 1
	s_barrier
	v_mfma_f32_16x16x32_bf16 v[136:139], v[100:103], v[176:179], v[136:139]
	v_mfma_f32_16x16x32_bf16 v[132:135], v[148:151], v[176:179], v[132:135]
	v_mfma_f32_16x16x32_bf16 v[128:131], v[100:103], v[184:187], v[128:131]
	v_mfma_f32_16x16x32_bf16 v[124:127], v[148:151], v[184:187], v[124:127]
	v_mfma_f32_16x16x32_bf16 v[120:123], v[100:103], v[192:195], v[120:123]
	v_mfma_f32_16x16x32_bf16 v[116:119], v[148:151], v[192:195], v[116:119]
	v_mfma_f32_16x16x32_bf16 v[112:115], v[100:103], v[200:203], v[112:115]
	v_mfma_f32_16x16x32_bf16 v[104:107], v[148:151], v[200:203], v[104:107]
	s_setprio 0
	s_setprio 1
	v_mfma_f32_16x16x32_bf16 v[136:139], v[108:111], v[180:183], v[136:139]
	v_mfma_f32_16x16x32_bf16 v[132:135], v[152:155], v[180:183], v[132:135]
	v_mfma_f32_16x16x32_bf16 v[128:131], v[108:111], v[188:191], v[128:131]
	v_mfma_f32_16x16x32_bf16 v[124:127], v[152:155], v[188:191], v[124:127]
	v_mfma_f32_16x16x32_bf16 v[120:123], v[108:111], v[196:199], v[120:123]
	v_mfma_f32_16x16x32_bf16 v[116:119], v[152:155], v[196:199], v[116:119]
	v_mfma_f32_16x16x32_bf16 v[112:115], v[108:111], v[204:207], v[112:115]
	v_mfma_f32_16x16x32_bf16 v[104:107], v[152:155], v[204:207], v[104:107]
	s_setprio 0
	s_setprio 1
	v_mfma_f32_16x16x32_bf16 v[64:67], v[160:163], v[176:179], v[64:67]
	v_mfma_f32_16x16x32_bf16 v[60:63], v[168:171], v[176:179], v[60:63]
	v_mfma_f32_16x16x32_bf16 v[56:59], v[160:163], v[184:187], v[56:59]
	v_mfma_f32_16x16x32_bf16 v[52:55], v[168:171], v[184:187], v[52:55]
	v_mfma_f32_16x16x32_bf16 v[48:51], v[160:163], v[192:195], v[48:51]
	v_mfma_f32_16x16x32_bf16 v[44:47], v[168:171], v[192:195], v[44:47]
	v_mfma_f32_16x16x32_bf16 v[40:43], v[160:163], v[200:203], v[40:43]
	v_mfma_f32_16x16x32_bf16 v[36:39], v[168:171], v[200:203], v[36:39]
	s_setprio 0
	s_setprio 1
	v_mfma_f32_16x16x32_bf16 v[64:67], v[164:167], v[180:183], v[64:67]
	v_mfma_f32_16x16x32_bf16 v[60:63], v[172:175], v[180:183], v[60:63]
	v_mfma_f32_16x16x32_bf16 v[56:59], v[164:167], v[188:191], v[56:59]
	v_mfma_f32_16x16x32_bf16 v[52:55], v[172:175], v[188:191], v[52:55]
	v_mfma_f32_16x16x32_bf16 v[48:51], v[164:167], v[196:199], v[48:51]
	v_mfma_f32_16x16x32_bf16 v[44:47], v[172:175], v[196:199], v[44:47]
	v_mfma_f32_16x16x32_bf16 v[40:43], v[164:167], v[204:207], v[40:43]
	v_mfma_f32_16x16x32_bf16 v[36:39], v[172:175], v[204:207], v[36:39]
	s_setprio 0
	s_barrier
	s_mov_b32 m0, s50
	v_lshl_add_u64 v[156:157], s[38:39], 0, v[142:143]
	global_load_lds_dwordx4 v[156:157], off
	v_lshl_add_u64 v[208:209], s[38:39], 0, v[146:147]
	s_mov_b32 m0, s51
	v_lshl_add_u64 v[2:3], s[40:41], 0, v[142:143]
	global_load_lds_dwordx4 v[208:209], off
	s_mov_b32 m0, s52
	v_lshl_add_u64 v[210:211], s[36:37], 0, v[140:141]
	global_load_lds_dwordx4 v[2:3], off
	v_lshl_add_u64 v[2:3], s[40:41], 0, v[146:147]
	s_mov_b32 m0, s53
	v_lshl_add_u64 v[212:213], s[36:37], 0, v[144:145]
	global_load_lds_dwordx4 v[2:3], off
	s_mov_b32 m0, s54
	s_nop 0
	global_load_lds_dwordx4 v[210:211], off
	s_mov_b32 m0, s55
	s_nop 0
	global_load_lds_dwordx4 v[212:213], off
	ds_read_b128 v[176:179], v158 offset:17408
	ds_read_b128 v[180:183], v158 offset:18432
	ds_read_b128 v[184:187], v158 offset:19456
	ds_read_b128 v[188:191], v158 offset:20480
	ds_read_b128 v[192:195], v158 offset:21504
	ds_read_b128 v[196:199], v158 offset:22528
	ds_read_b128 v[200:203], v158 offset:23552
	ds_read_b128 v[204:207], v158 offset:24576
	s_waitcnt vmcnt(8)
	s_waitcnt lgkmcnt(0)
	s_setprio 1
	s_barrier
; #define PG8_STAGE(bufoff, gbase, voff) do { _Pragma("unroll") for (int _i = 0; _i < 2; ++_i) \
;         __builtin_amdgcn_global_load_lds((const GAS unsigned*)((const GAS char*)(gbase) + (voff)[_i]), (LAS unsigned*)(lds + (bufoff) + ldsw + _i * 8192), 16, 0, 0); } while (0)
; #define PG8_LDA(dst, b, h) do { _Pragma("unroll") for (int m = 0; m < 4; ++m) _Pragma("unroll") for (int k = 0; k < 2; ++k) dst[m][k] = *(const LAS bf16x8*)(lds + PG8_SA(b, h) + aoff + m * 2048 + k * 1024); } while (0)
; #define PG8_LDB(dst, b, h) do { _Pragma("unroll") for (int n = 0; n < 2; ++n) _Pragma("unroll") for (int k = 0; k < 2; ++k) dst[n][k] = *(const LAS bf16x8*)(lds + PG8_SB(b, h) + boff + n * 2048 + k * 1024); } while (0)
; #define PG8_MMA(ai, bj, At, Bt) do { __builtin_amdgcn_s_setprio(1); _Pragma("unroll") for (int m = 0; m < 4; ++m) _Pragma("unroll") for (int n = 0; n < 2; ++n) _Pragma("unroll") for (int k = 0; k < 2; ++k) \
;         acc[ai][bj][m][n] = __builtin_amdgcn_mfma_f32_16x16x32_bf16(Bt[n][k], At[m][k], acc[ai][bj][m][n], 0, 0, 0); __builtin_amdgcn_s_setprio(0); } while (0)
; #define PG8_WAIT_V(n) asm volatile("s_waitcnt vmcnt(" #n ")" ::: "memory")
; #define PG8_WAIT_L(n) asm volatile("s_waitcnt lgkmcnt(" #n ")" ::: "memory")
; #define PG8_BAR __builtin_amdgcn_s_barrier()
; #define PG8_SCHED __builtin_amdgcn_sched_barrier(0)
; template <class Epi, class Sched, bool ALIGN_EPI>
; __device__ __forceinline__ void gemm_phase(LAS unsigned char* lds, const Gemm g, const Sched& S, const Epi& E, int wave_id) {
;     ...
;             PG8_WAIT_V(8); PG8_WAIT_L(0); PG8_BAR; PG8_MMA(1, 0, At, B0); PG8_MMA(1, 1, At, B1); PG8_BAR; PG8_SCHED;
;             PG8_LDB(B0, 1, 0); PG8_LDB(B1, 1, 1); PG8_SCHED; PG8_LDA(At, 1, 0); PG8_STAGE(PG8_SA(0, 1), a2 + hsA, voffA);
;             PG8_WAIT_V(8); PG8_WAIT_L(0); PG8_BAR; PG8_MMA(0, 0, At, B0); PG8_MMA(0, 1, At, B1); PG8_BAR; PG8_SCHED;
	v_mfma_f32_16x16x32_bf16 v[96:99], v[100:103], v[176:179], v[96:99]
	v_mfma_f32_16x16x32_bf16 v[92:95], v[148:151], v[176:179], v[92:95]
	v_mfma_f32_16x16x32_bf16 v[88:91], v[100:103], v[184:187], v[88:91]
	v_mfma_f32_16x16x32_bf16 v[84:87], v[148:151], v[184:187], v[84:87]
	v_mfma_f32_16x16x32_bf16 v[80:83], v[100:103], v[192:195], v[80:83]
	v_mfma_f32_16x16x32_bf16 v[76:79], v[148:151], v[192:195], v[76:79]
	v_mfma_f32_16x16x32_bf16 v[72:75], v[100:103], v[200:203], v[72:75]
	v_mfma_f32_16x16x32_bf16 v[68:71], v[148:151], v[200:203], v[68:71]
	s_setprio 0
	s_setprio 1
	v_mfma_f32_16x16x32_bf16 v[96:99], v[108:111], v[180:183], v[96:99]
	v_mfma_f32_16x16x32_bf16 v[92:95], v[152:155], v[180:183], v[92:95]
	v_mfma_f32_16x16x32_bf16 v[88:91], v[108:111], v[188:191], v[88:91]
	v_mfma_f32_16x16x32_bf16 v[84:87], v[152:155], v[188:191], v[84:87]
	v_mfma_f32_16x16x32_bf16 v[80:83], v[108:111], v[196:199], v[80:83]
	v_mfma_f32_16x16x32_bf16 v[76:79], v[152:155], v[196:199], v[76:79]
	v_mfma_f32_16x16x32_bf16 v[72:75], v[108:111], v[204:207], v[72:75]
	v_mfma_f32_16x16x32_bf16 v[68:71], v[152:155], v[204:207], v[68:71]
	s_setprio 0
	s_setprio 1
	v_mfma_f32_16x16x32_bf16 v[32:35], v[160:163], v[176:179], v[32:35]
	v_mfma_f32_16x16x32_bf16 v[28:31], v[168:171], v[176:179], v[28:31]
	v_mfma_f32_16x16x32_bf16 v[24:27], v[160:163], v[184:187], v[24:27]
	v_mfma_f32_16x16x32_bf16 v[20:23], v[168:171], v[184:187], v[20:23]
	v_mfma_f32_16x16x32_bf16 v[16:19], v[160:163], v[192:195], v[16:19]
	v_mfma_f32_16x16x32_bf16 v[12:15], v[168:171], v[192:195], v[12:15]
	v_mfma_f32_16x16x32_bf16 v[8:11], v[160:163], v[200:203], v[8:11]
	v_mfma_f32_16x16x32_bf16 v[2:5], v[168:171], v[200:203], v[4:7]
	s_setprio 0
	s_setprio 1
	v_mfma_f32_16x16x32_bf16 v[32:35], v[164:167], v[180:183], v[32:35]
	v_mfma_f32_16x16x32_bf16 v[28:31], v[172:175], v[180:183], v[28:31]
	v_mfma_f32_16x16x32_bf16 v[24:27], v[164:167], v[188:191], v[24:27]
	v_mfma_f32_16x16x32_bf16 v[20:23], v[172:175], v[188:191], v[20:23]
	v_mfma_f32_16x16x32_bf16 v[16:19], v[164:167], v[196:199], v[16:19]
	v_mfma_f32_16x16x32_bf16 v[12:15], v[172:175], v[196:199], v[12:15]
	v_mfma_f32_16x16x32_bf16 v[8:11], v[164:167], v[204:207], v[8:11]
	v_mfma_f32_16x16x32_bf16 v[2:5], v[172:175], v[204:207], v[2:5]
	s_setprio 0
	s_barrier
	s_mov_b32 m0, s56
	v_lshl_add_u64 v[6:7], s[34:35], 0, v[140:141]
	global_load_lds_dwordx4 v[6:7], off
	v_lshl_add_u64 v[6:7], s[34:35], 0, v[144:145]
	s_mov_b32 m0, s57
	s_nop 0
	global_load_lds_dwordx4 v[6:7], off
	v_add_u32_e32 v0, 0x18400, v159
	ds_read_b128 v[100:103], v0
	ds_read_b128 v[108:111], v0 offset:1024
	ds_read_b128 v[148:151], v0 offset:2048
	ds_read_b128 v[152:155], v0 offset:3072
	v_add_u32_e32 v0, 0x1c400, v159
	ds_read_b128 v[160:163], v0
	ds_read_b128 v[164:167], v0 offset:1024
	ds_read_b128 v[168:171], v0 offset:2048
	ds_read_b128 v[172:175], v0 offset:3072
	ds_read_b128 v[176:179], v158 offset:33792
	ds_read_b128 v[180:183], v158 offset:34816
	ds_read_b128 v[184:187], v158 offset:35840
	ds_read_b128 v[188:191], v158 offset:36864
	ds_read_b128 v[192:195], v158 offset:37888
	ds_read_b128 v[196:199], v158 offset:38912
	ds_read_b128 v[200:203], v158 offset:39936
	ds_read_b128 v[204:207], v158 offset:40960
	s_waitcnt vmcnt(8)
	s_waitcnt lgkmcnt(0)
	s_setprio 1
	s_barrier
	v_mfma_f32_16x16x32_bf16 v[136:139], v[100:103], v[176:179], v[136:139]
	v_mfma_f32_16x16x32_bf16 v[132:135], v[148:151], v[176:179], v[132:135]
	v_mfma_f32_16x16x32_bf16 v[128:131], v[100:103], v[184:187], v[128:131]
	v_mfma_f32_16x16x32_bf16 v[124:127], v[148:151], v[184:187], v[124:127]
	v_mfma_f32_16x16x32_bf16 v[120:123], v[100:103], v[192:195], v[120:123]
	v_mfma_f32_16x16x32_bf16 v[116:119], v[148:151], v[192:195], v[116:119]
	v_mfma_f32_16x16x32_bf16 v[112:115], v[100:103], v[200:203], v[112:115]
	v_mfma_f32_16x16x32_bf16 v[104:107], v[148:151], v[200:203], v[104:107]
	s_setprio 0
	s_setprio 1
	v_mfma_f32_16x16x32_bf16 v[136:139], v[108:111], v[180:183], v[136:139]
	v_mfma_f32_16x16x32_bf16 v[132:135], v[152:155], v[180:183], v[132:135]
	v_mfma_f32_16x16x32_bf16 v[128:131], v[108:111], v[188:191], v[128:131]
	v_mfma_f32_16x16x32_bf16 v[124:127], v[152:155], v[188:191], v[124:127]
	v_mfma_f32_16x16x32_bf16 v[120:123], v[108:111], v[196:199], v[120:123]
	v_mfma_f32_16x16x32_bf16 v[116:119], v[152:155], v[196:199], v[116:119]
	v_mfma_f32_16x16x32_bf16 v[112:115], v[108:111], v[204:207], v[112:115]
	v_mfma_f32_16x16x32_bf16 v[104:107], v[152:155], v[204:207], v[104:107]
	s_setprio 0
	s_setprio 1
	v_mfma_f32_16x16x32_bf16 v[64:67], v[160:163], v[176:179], v[64:67]
	v_mfma_f32_16x16x32_bf16 v[60:63], v[168:171], v[176:179], v[60:63]
	v_mfma_f32_16x16x32_bf16 v[56:59], v[160:163], v[184:187], v[56:59]
	v_mfma_f32_16x16x32_bf16 v[52:55], v[168:171], v[184:187], v[52:55]
	v_mfma_f32_16x16x32_bf16 v[48:51], v[160:163], v[192:195], v[48:51]
	v_mfma_f32_16x16x32_bf16 v[44:47], v[168:171], v[192:195], v[44:47]
	v_mfma_f32_16x16x32_bf16 v[40:43], v[160:163], v[200:203], v[40:43]
	v_mfma_f32_16x16x32_bf16 v[36:39], v[168:171], v[200:203], v[36:39]
	s_setprio 0
	s_setprio 1
	v_mfma_f32_16x16x32_bf16 v[64:67], v[164:167], v[180:183], v[64:67]
	v_mfma_f32_16x16x32_bf16 v[60:63], v[172:175], v[180:183], v[60:63]
	v_mfma_f32_16x16x32_bf16 v[56:59], v[164:167], v[188:191], v[56:59]
	v_mfma_f32_16x16x32_bf16 v[52:55], v[172:175], v[188:191], v[52:55]
	v_mfma_f32_16x16x32_bf16 v[48:51], v[164:167], v[196:199], v[48:51]
	v_mfma_f32_16x16x32_bf16 v[44:47], v[172:175], v[196:199], v[44:47]
	v_mfma_f32_16x16x32_bf16 v[40:43], v[164:167], v[204:207], v[40:43]
	v_mfma_f32_16x16x32_bf16 v[36:39], v[172:175], v[204:207], v[36:39]
	s_setprio 0
	s_barrier
; #define PG8_STAGE(bufoff, gbase, voff) do { _Pragma("unroll") for (int _i = 0; _i < 2; ++_i) \
;         __builtin_amdgcn_global_load_lds((const GAS unsigned*)((const GAS char*)(gbase) + (voff)[_i]), (LAS unsigned*)(lds + (bufoff) + ldsw + _i * 8192), 16, 0, 0); } while (0)
; #define PG8_LDA(dst, b, h) do { _Pragma("unroll") for (int m = 0; m < 4; ++m) _Pragma("unroll") for (int k = 0; k < 2; ++k) dst[m][k] = *(const LAS bf16x8*)(lds + PG8_SA(b, h) + aoff + m * 2048 + k * 1024); } while (0)
; #define PG8_MMA(ai, bj, At, Bt) do { __builtin_amdgcn_s_setprio(1); _Pragma("unroll") for (int m = 0; m < 4; ++m) _Pragma("unroll") for (int n = 0; n < 2; ++n) _Pragma("unroll") for (int k = 0; k < 2; ++k) \
;         acc[ai][bj][m][n] = __builtin_amdgcn_mfma_f32_16x16x32_bf16(Bt[n][k], At[m][k], acc[ai][bj][m][n], 0, 0, 0); __builtin_amdgcn_s_setprio(0); } while (0)
; #define PG8_WAIT_V(n) asm volatile("s_waitcnt vmcnt(" #n ")" ::: "memory")
; #define PG8_WAIT_L(n) asm volatile("s_waitcnt lgkmcnt(" #n ")" ::: "memory")
; #define PG8_BAR __builtin_amdgcn_s_barrier()
; #define PG8_SCHED __builtin_amdgcn_sched_barrier(0)
; template <class Epi, class Sched, bool ALIGN_EPI>
; __device__ __forceinline__ void gemm_phase(LAS unsigned char* lds, const Gemm g, const Sched& S, const Epi& E, int wave_id) {
;     ...
;             PG8_LDA(At, 1, 1); PG8_STAGE(PG8_SB(1, 0), b3, voffB); PG8_STAGE(PG8_SB(1, 1), b3 + hsB, voffB); PG8_STAGE(PG8_SA(1, 0), a3, voffA);
;             PG8_WAIT_V(8); PG8_WAIT_L(0); PG8_BAR; PG8_MMA(1, 0, At, B0); PG8_MMA(1, 1, At, B1); PG8_BAR; PG8_SCHED;
;         }
;         if constexpr (ALIGN_EPI) { if (wr == 0) PG8_BAR; }
	s_mov_b32 m0, s63
	v_lshl_add_u64 v[6:7], v[156:157], 0, s[92:93]
	global_load_lds_dwordx4 v[6:7], off
	v_lshl_add_u64 v[6:7], v[208:209], 0, s[92:93]
	s_mov_b32 m0, s64
	s_nop 0
	global_load_lds_dwordx4 v[6:7], off
	v_lshl_add_u64 v[6:7], s[30:31], 0, v[142:143]
	s_mov_b32 m0, s67
	s_nop 0
	global_load_lds_dwordx4 v[6:7], off
	v_lshl_add_u64 v[6:7], s[30:31], 0, v[146:147]
	s_mov_b32 m0, s72
	s_nop 0
	global_load_lds_dwordx4 v[6:7], off
	v_lshl_add_u64 v[6:7], v[210:211], 0, s[92:93]
	s_mov_b32 m0, s65
	s_nop 0
	global_load_lds_dwordx4 v[6:7], off
	v_lshl_add_u64 v[6:7], v[212:213], 0, s[92:93]
	s_mov_b32 m0, s66
	s_nop 0
	global_load_lds_dwordx4 v[6:7], off
	ds_read_b128 v[176:179], v158 offset:50176
	ds_read_b128 v[180:183], v158 offset:51200
	ds_read_b128 v[184:187], v158 offset:52224
	ds_read_b128 v[188:191], v158 offset:53248
	ds_read_b128 v[192:195], v158 offset:54272
	ds_read_b128 v[196:199], v158 offset:55296
	ds_read_b128 v[200:203], v158 offset:56320
	ds_read_b128 v[204:207], v158 offset:57344
	s_waitcnt vmcnt(8)
	s_waitcnt lgkmcnt(0)
	s_setprio 1
	s_barrier
	v_mfma_f32_16x16x32_bf16 v[96:99], v[100:103], v[176:179], v[96:99]
	v_mfma_f32_16x16x32_bf16 v[92:95], v[148:151], v[176:179], v[92:95]
	v_mfma_f32_16x16x32_bf16 v[88:91], v[100:103], v[184:187], v[88:91]
	v_mfma_f32_16x16x32_bf16 v[84:87], v[148:151], v[184:187], v[84:87]
	v_mfma_f32_16x16x32_bf16 v[80:83], v[100:103], v[192:195], v[80:83]
	v_mfma_f32_16x16x32_bf16 v[76:79], v[148:151], v[192:195], v[76:79]
	v_mfma_f32_16x16x32_bf16 v[72:75], v[100:103], v[200:203], v[72:75]
	v_mfma_f32_16x16x32_bf16 v[68:71], v[148:151], v[200:203], v[68:71]
	s_setprio 0
	s_setprio 1
	v_mfma_f32_16x16x32_bf16 v[96:99], v[108:111], v[180:183], v[96:99]
	v_mfma_f32_16x16x32_bf16 v[92:95], v[152:155], v[180:183], v[92:95]
	v_mfma_f32_16x16x32_bf16 v[88:91], v[108:111], v[188:191], v[88:91]
	v_mfma_f32_16x16x32_bf16 v[84:87], v[152:155], v[188:191], v[84:87]
	v_mfma_f32_16x16x32_bf16 v[80:83], v[108:111], v[196:199], v[80:83]
	v_mfma_f32_16x16x32_bf16 v[76:79], v[152:155], v[196:199], v[76:79]
	v_mfma_f32_16x16x32_bf16 v[72:75], v[108:111], v[204:207], v[72:75]
	v_mfma_f32_16x16x32_bf16 v[68:71], v[152:155], v[204:207], v[68:71]
	s_setprio 0
	s_setprio 1
	v_mfma_f32_16x16x32_bf16 v[32:35], v[160:163], v[176:179], v[32:35]
	v_mfma_f32_16x16x32_bf16 v[28:31], v[168:171], v[176:179], v[28:31]
	v_mfma_f32_16x16x32_bf16 v[24:27], v[160:163], v[184:187], v[24:27]
	v_mfma_f32_16x16x32_bf16 v[20:23], v[168:171], v[184:187], v[20:23]
	v_mfma_f32_16x16x32_bf16 v[16:19], v[160:163], v[192:195], v[16:19]
	v_mfma_f32_16x16x32_bf16 v[12:15], v[168:171], v[192:195], v[12:15]
	v_mfma_f32_16x16x32_bf16 v[6:9], v[160:163], v[200:203], v[8:11]
	v_mfma_f32_16x16x32_bf16 v[2:5], v[168:171], v[200:203], v[2:5]
	s_setprio 0
	s_setprio 1
	v_mfma_f32_16x16x32_bf16 v[32:35], v[164:167], v[180:183], v[32:35]
	v_mfma_f32_16x16x32_bf16 v[28:31], v[172:175], v[180:183], v[28:31]
	v_mfma_f32_16x16x32_bf16 v[24:27], v[164:167], v[188:191], v[24:27]
	v_mfma_f32_16x16x32_bf16 v[20:23], v[172:175], v[188:191], v[20:23]
	v_mfma_f32_16x16x32_bf16 v[16:19], v[164:167], v[196:199], v[16:19]
	v_mfma_f32_16x16x32_bf16 v[12:15], v[172:175], v[196:199], v[12:15]
	v_mfma_f32_16x16x32_bf16 v[8:11], v[164:167], v[204:207], v[6:9]
	v_mfma_f32_16x16x32_bf16 v[4:7], v[172:175], v[204:207], v[2:5]
	s_setprio 0
	s_barrier
	s_andn2_b64 vcc, exec, s[28:29]
	s_mov_b64 s[30:31], -1
	s_mov_b64 s[28:29], 0
	s_mov_b64 s[34:35], 0x100
	s_cbranch_vccz .LBB0_1458
	s_and_b64 vcc, exec, s[16:17]
	s_cbranch_vccz .LBB0_1461
	s_barrier

; #define GAS __attribute__((address_space(1)))
; #define PG8_STAGE(bufoff, gbase, voff) do { _Pragma("unroll") for (int _i = 0; _i < 2; ++_i) \
;         __builtin_amdgcn_global_load_lds((const GAS unsigned*)((const GAS char*)(gbase) + (voff)[_i]), (LAS unsigned*)(lds + (bufoff) + ldsw + _i * 8192), 16, 0, 0); } while (0)
; #define PG8_LDA(dst, b, h) do { _Pragma("unroll") for (int m = 0; m < 4; ++m) _Pragma("unroll") for (int k = 0; k < 2; ++k) dst[m][k] = *(const LAS bf16x8*)(lds + PG8_SA(b, h) + aoff + m * 2048 + k * 1024); } while (0)
; #define PG8_LDB(dst, b, h) do { _Pragma("unroll") for (int n = 0; n < 2; ++n) _Pragma("unroll") for (int k = 0; k < 2; ++k) dst[n][k] = *(const LAS bf16x8*)(lds + PG8_SB(b, h) + boff + n * 2048 + k * 1024); } while (0)
; #define PG8_MMA(ai, bj, At, Bt) do { __builtin_amdgcn_s_setprio(1); _Pragma("unroll") for (int m = 0; m < 4; ++m) _Pragma("unroll") for (int n = 0; n < 2; ++n) _Pragma("unroll") for (int k = 0; k < 2; ++k) \
;         acc[ai][bj][m][n] = __builtin_amdgcn_mfma_f32_16x16x32_bf16(Bt[n][k], At[m][k], acc[ai][bj][m][n], 0, 0, 0); __builtin_amdgcn_s_setprio(0); } while (0)
; #define PG8_WAIT_V(n) asm volatile("s_waitcnt vmcnt(" #n ")" ::: "memory")
; #define PG8_WAIT_L(n) asm volatile("s_waitcnt lgkmcnt(" #n ")" ::: "memory")
; #define PG8_BAR __builtin_amdgcn_s_barrier()
; template <class Epi, class Sched, bool ALIGN_EPI>
; __device__ __forceinline__ void gemm_phase(LAS unsigned char* lds, const Gemm g, const Sched& S, const Epi& E, int wave_id) {
;     ...
;             const bool last = (t == nt - 2);
;             const GAS char* a1 = cA + (size_t)(t + 1) * kstep;
;             const GAS char* a2 = last ? nA : cA + (size_t)(t + 2) * kstep; const GAS char* b2 = last ? nB : cB + (size_t)(t + 2) * kstep;
;             const GAS char* a3 = a2 + kstep; const GAS char* b3 = b2 + kstep;
;             PG8_LDB(B0, 0, 0); PG8_LDB(B1, 0, 1); PG8_SCHED; PG8_LDA(At, 0, 0); PG8_STAGE(PG8_SA(1, 1), a1 + hsA, voffA);
;             PG8_WAIT_V(8); PG8_WAIT_L(0); PG8_BAR; PG8_MMA(0, 0, At, B0); PG8_MMA(0, 1, At, B1); PG8_BAR; PG8_SCHED;
;             PG8_LDA(At, 0, 1); PG8_STAGE(PG8_SB(0, 0), b2, voffB); PG8_STAGE(PG8_SB(0, 1), b2 + hsB, voffB); PG8_STAGE(PG8_SA(0, 0), a2, voffA);
;             PG8_WAIT_V(8); PG8_WAIT_L(0); PG8_BAR; PG8_MMA(1, 0, At, B0); PG8_MMA(1, 1, At, B1); PG8_BAR; PG8_SCHED;
.LBB0_1645:
	s_add_u32 s20, s18, 0x100
	s_addc_u32 s21, s19, 0
	s_cmp_eq_u32 s55, 2
	s_cselect_b32 s25, s15, s21
	s_cselect_b32 s24, s14, s20
	s_cselect_b32 s23, s17, s54
	s_cselect_b32 s22, s16, s53
	v_lshl_add_u64 v[192:193], s[18:19], 0, v[170:171]
	s_add_i32 m0, s31, 0xc400
	s_nop 0
	global_load_lds_dwordx4 v[192:193], off
	v_lshl_add_u64 v[192:193], s[18:19], 0, v[168:169]
	s_add_i32 m0, s31, 0xe400
	s_nop 0
	global_load_lds_dwordx4 v[192:193], off
	v_add_u32_e32 v134, 0x10400, v195
	v_add_u32_e32 v158, 0x14400, v195
	ds_read_b128 v[114:117], v134
	ds_read_b128 v[118:121], v134 offset:1024
	ds_read_b128 v[130:133], v134 offset:2048
	ds_read_b128 v[134:137], v134 offset:3072
	ds_read_b128 v[146:149], v158
	ds_read_b128 v[150:153], v158 offset:1024
	ds_read_b128 v[154:157], v158 offset:2048
	ds_read_b128 v[158:161], v158 offset:3072
	ds_read_b128 v[172:175], v194 offset:1024
	ds_read_b128 v[176:179], v194 offset:2048
	ds_read_b128 v[180:183], v194 offset:3072
	ds_read_b128 v[184:187], v194 offset:4096
	ds_read_b128 v[188:191], v194 offset:5120
	ds_read_b128 v[196:199], v194 offset:6144
	ds_read_b128 v[200:203], v194 offset:7168
	ds_read_b128 v[204:207], v194 offset:8192
	s_waitcnt vmcnt(8)
	s_waitcnt lgkmcnt(0)
	s_setprio 1
	s_barrier
	v_mfma_f32_16x16x32_bf16 v[142:145], v[114:117], v[172:175], v[142:145]
	v_mfma_f32_16x16x32_bf16 v[138:141], v[130:133], v[172:175], v[138:141]
	v_mfma_f32_16x16x32_bf16 v[126:129], v[114:117], v[180:183], v[126:129]
	v_mfma_f32_16x16x32_bf16 v[122:125], v[130:133], v[180:183], v[122:125]
	v_mfma_f32_16x16x32_bf16 v[110:113], v[114:117], v[188:191], v[110:113]
	v_mfma_f32_16x16x32_bf16 v[106:109], v[130:133], v[188:191], v[106:109]
	v_mfma_f32_16x16x32_bf16 v[102:105], v[114:117], v[200:203], v[102:105]
	v_mfma_f32_16x16x32_bf16 v[98:101], v[130:133], v[200:203], v[98:101]
	s_setprio 0
	s_setprio 1
	v_mfma_f32_16x16x32_bf16 v[142:145], v[118:121], v[176:179], v[142:145]
	v_mfma_f32_16x16x32_bf16 v[138:141], v[134:137], v[176:179], v[138:141]
	v_mfma_f32_16x16x32_bf16 v[126:129], v[118:121], v[184:187], v[126:129]
	v_mfma_f32_16x16x32_bf16 v[122:125], v[134:137], v[184:187], v[122:125]
	v_mfma_f32_16x16x32_bf16 v[110:113], v[118:121], v[196:199], v[110:113]
	v_mfma_f32_16x16x32_bf16 v[106:109], v[134:137], v[196:199], v[106:109]
	v_mfma_f32_16x16x32_bf16 v[102:105], v[118:121], v[204:207], v[102:105]
	v_mfma_f32_16x16x32_bf16 v[98:101], v[134:137], v[204:207], v[98:101]
	s_setprio 0
	s_setprio 1
	v_mfma_f32_16x16x32_bf16 v[62:65], v[146:149], v[172:175], v[62:65]
	v_mfma_f32_16x16x32_bf16 v[58:61], v[154:157], v[172:175], v[58:61]
	v_mfma_f32_16x16x32_bf16 v[54:57], v[146:149], v[180:183], v[54:57]
	v_mfma_f32_16x16x32_bf16 v[50:53], v[154:157], v[180:183], v[50:53]
	v_mfma_f32_16x16x32_bf16 v[46:49], v[146:149], v[188:191], v[46:49]
	v_mfma_f32_16x16x32_bf16 v[42:45], v[154:157], v[188:191], v[42:45]
	v_mfma_f32_16x16x32_bf16 v[38:41], v[146:149], v[200:203], v[38:41]
	v_mfma_f32_16x16x32_bf16 v[34:37], v[154:157], v[200:203], v[34:37]
	s_setprio 0
	s_setprio 1
	v_mfma_f32_16x16x32_bf16 v[62:65], v[150:153], v[176:179], v[62:65]
	v_mfma_f32_16x16x32_bf16 v[58:61], v[158:161], v[176:179], v[58:61]
	v_mfma_f32_16x16x32_bf16 v[54:57], v[150:153], v[184:187], v[54:57]
	v_mfma_f32_16x16x32_bf16 v[50:53], v[158:161], v[184:187], v[50:53]
	v_mfma_f32_16x16x32_bf16 v[46:49], v[150:153], v[196:199], v[46:49]
	v_mfma_f32_16x16x32_bf16 v[42:45], v[158:161], v[196:199], v[42:45]
	v_mfma_f32_16x16x32_bf16 v[38:41], v[150:153], v[204:207], v[38:41]
	v_mfma_f32_16x16x32_bf16 v[34:37], v[158:161], v[204:207], v[34:37]
	s_setprio 0
	s_barrier
	s_mov_b32 m0, s34
	v_lshl_add_u64 v[192:193], s[22:23], 0, v[0:1]
	s_add_u32 s18, s22, 0x18000
	global_load_lds_dwordx4 v[192:193], off
	v_lshl_add_u64 v[208:209], s[22:23], 0, v[162:163]
	s_mov_b32 m0, s35
	s_addc_u32 s19, s23, 0
	global_load_lds_dwordx4 v[208:209], off
	v_lshl_add_u64 v[210:211], s[18:19], 0, v[0:1]
	s_mov_b32 m0, s36
	v_lshl_add_u64 v[212:213], s[24:25], 0, v[164:165]
	global_load_lds_dwordx4 v[210:211], off
	v_lshl_add_u64 v[210:211], s[18:19], 0, v[162:163]
	s_mov_b32 m0, s37
	s_nop 0
	global_load_lds_dwordx4 v[210:211], off
	v_lshl_add_u64 v[210:211], s[24:25], 0, v[166:167]
	s_mov_b32 m0, s38
	s_nop 0
	global_load_lds_dwordx4 v[210:211], off
	s_mov_b32 m0, s39
	s_nop 0
	global_load_lds_dwordx4 v[212:213], off
	ds_read_b128 v[172:175], v194 offset:17408
	ds_read_b128 v[176:179], v194 offset:18432
	ds_read_b128 v[180:183], v194 offset:19456
	ds_read_b128 v[184:187], v194 offset:20480
	ds_read_b128 v[188:191], v194 offset:21504
	ds_read_b128 v[196:199], v194 offset:22528
	ds_read_b128 v[200:203], v194 offset:23552
	ds_read_b128 v[204:207], v194 offset:24576
	s_waitcnt vmcnt(8)
	s_waitcnt lgkmcnt(0)
	s_setprio 1
	s_barrier
; #define PG8_STAGE(bufoff, gbase, voff) do { _Pragma("unroll") for (int _i = 0; _i < 2; ++_i) \
;         __builtin_amdgcn_global_load_lds((const GAS unsigned*)((const GAS char*)(gbase) + (voff)[_i]), (LAS unsigned*)(lds + (bufoff) + ldsw + _i * 8192), 16, 0, 0); } while (0)
; #define PG8_LDA(dst, b, h) do { _Pragma("unroll") for (int m = 0; m < 4; ++m) _Pragma("unroll") for (int k = 0; k < 2; ++k) dst[m][k] = *(const LAS bf16x8*)(lds + PG8_SA(b, h) + aoff + m * 2048 + k * 1024); } while (0)
; #define PG8_LDB(dst, b, h) do { _Pragma("unroll") for (int n = 0; n < 2; ++n) _Pragma("unroll") for (int k = 0; k < 2; ++k) dst[n][k] = *(const LAS bf16x8*)(lds + PG8_SB(b, h) + boff + n * 2048 + k * 1024); } while (0)
; #define PG8_MMA(ai, bj, At, Bt) do { __builtin_amdgcn_s_setprio(1); _Pragma("unroll") for (int m = 0; m < 4; ++m) _Pragma("unroll") for (int n = 0; n < 2; ++n) _Pragma("unroll") for (int k = 0; k < 2; ++k) \
;         acc[ai][bj][m][n] = __builtin_amdgcn_mfma_f32_16x16x32_bf16(Bt[n][k], At[m][k], acc[ai][bj][m][n], 0, 0, 0); __builtin_amdgcn_s_setprio(0); } while (0)
; #define PG8_WAIT_V(n) asm volatile("s_waitcnt vmcnt(" #n ")" ::: "memory")
; #define PG8_WAIT_L(n) asm volatile("s_waitcnt lgkmcnt(" #n ")" ::: "memory")
; #define PG8_BAR __builtin_amdgcn_s_barrier()
; #define PG8_SCHED __builtin_amdgcn_sched_barrier(0)
; template <class Epi, class Sched, bool ALIGN_EPI>
; __device__ __forceinline__ void gemm_phase(LAS unsigned char* lds, const Gemm g, const Sched& S, const Epi& E, int wave_id) {
;     ...
;             PG8_WAIT_V(8); PG8_WAIT_L(0); PG8_BAR; PG8_MMA(1, 0, At, B0); PG8_MMA(1, 1, At, B1); PG8_BAR; PG8_SCHED;
;             PG8_LDB(B0, 1, 0); PG8_LDB(B1, 1, 1); PG8_SCHED; PG8_LDA(At, 1, 0); PG8_STAGE(PG8_SA(0, 1), a2 + hsA, voffA);
;             PG8_WAIT_V(8); PG8_WAIT_L(0); PG8_BAR; PG8_MMA(0, 0, At, B0); PG8_MMA(0, 1, At, B1); PG8_BAR; PG8_SCHED;
	v_mfma_f32_16x16x32_bf16 v[94:97], v[114:117], v[172:175], v[94:97]
	v_mfma_f32_16x16x32_bf16 v[90:93], v[130:133], v[172:175], v[90:93]
	v_mfma_f32_16x16x32_bf16 v[86:89], v[114:117], v[180:183], v[86:89]
	v_mfma_f32_16x16x32_bf16 v[82:85], v[130:133], v[180:183], v[82:85]
	v_mfma_f32_16x16x32_bf16 v[78:81], v[114:117], v[188:191], v[78:81]
	v_mfma_f32_16x16x32_bf16 v[74:77], v[130:133], v[188:191], v[74:77]
	v_mfma_f32_16x16x32_bf16 v[70:73], v[114:117], v[200:203], v[70:73]
	v_mfma_f32_16x16x32_bf16 v[66:69], v[130:133], v[200:203], v[66:69]
	s_setprio 0
	s_setprio 1
	v_mfma_f32_16x16x32_bf16 v[94:97], v[118:121], v[176:179], v[94:97]
	v_mfma_f32_16x16x32_bf16 v[90:93], v[134:137], v[176:179], v[90:93]
	v_mfma_f32_16x16x32_bf16 v[86:89], v[118:121], v[184:187], v[86:89]
	v_mfma_f32_16x16x32_bf16 v[82:85], v[134:137], v[184:187], v[82:85]
	v_mfma_f32_16x16x32_bf16 v[78:81], v[118:121], v[196:199], v[78:81]
	v_mfma_f32_16x16x32_bf16 v[74:77], v[134:137], v[196:199], v[74:77]
	v_mfma_f32_16x16x32_bf16 v[70:73], v[118:121], v[204:207], v[70:73]
	v_mfma_f32_16x16x32_bf16 v[66:69], v[134:137], v[204:207], v[66:69]
	s_setprio 0
	s_setprio 1
	v_mfma_f32_16x16x32_bf16 v[30:33], v[146:149], v[172:175], v[30:33]
	v_mfma_f32_16x16x32_bf16 v[26:29], v[154:157], v[172:175], v[26:29]
	v_mfma_f32_16x16x32_bf16 v[22:25], v[146:149], v[180:183], v[22:25]
	v_mfma_f32_16x16x32_bf16 v[18:21], v[154:157], v[180:183], v[18:21]
	v_mfma_f32_16x16x32_bf16 v[14:17], v[146:149], v[188:191], v[14:17]
	v_mfma_f32_16x16x32_bf16 v[10:13], v[154:157], v[188:191], v[10:13]
	v_mfma_f32_16x16x32_bf16 v[6:9], v[146:149], v[200:203], v[6:9]
	v_mfma_f32_16x16x32_bf16 v[2:5], v[154:157], v[200:203], v[2:5]
	s_setprio 0
	s_setprio 1
	v_mfma_f32_16x16x32_bf16 v[30:33], v[150:153], v[176:179], v[30:33]
	v_mfma_f32_16x16x32_bf16 v[26:29], v[158:161], v[176:179], v[26:29]
	v_mfma_f32_16x16x32_bf16 v[22:25], v[150:153], v[184:187], v[22:25]
	v_mfma_f32_16x16x32_bf16 v[18:21], v[158:161], v[184:187], v[18:21]
	v_mfma_f32_16x16x32_bf16 v[14:17], v[150:153], v[196:199], v[14:17]
	v_mfma_f32_16x16x32_bf16 v[10:13], v[158:161], v[196:199], v[10:13]
	v_mfma_f32_16x16x32_bf16 v[6:9], v[150:153], v[204:207], v[6:9]
	v_mfma_f32_16x16x32_bf16 v[2:5], v[158:161], v[204:207], v[2:5]
	s_setprio 0
	s_barrier
	s_add_u32 s18, s24, 0x18000
	s_addc_u32 s19, s25, 0
	s_mov_b32 m0, s40
	v_lshl_add_u64 v[214:215], s[18:19], 0, v[166:167]
	global_load_lds_dwordx4 v[214:215], off
	v_lshl_add_u64 v[214:215], s[18:19], 0, v[164:165]
	s_mov_b32 m0, s41
	s_nop 0
	global_load_lds_dwordx4 v[214:215], off
	v_add_u32_e32 v134, 0x18400, v195
	v_add_u32_e32 v158, 0x1c400, v195
	ds_read_b128 v[114:117], v134
	ds_read_b128 v[118:121], v134 offset:1024
	ds_read_b128 v[130:133], v134 offset:2048
	ds_read_b128 v[134:137], v134 offset:3072
	ds_read_b128 v[146:149], v158
	ds_read_b128 v[150:153], v158 offset:1024
	ds_read_b128 v[154:157], v158 offset:2048
	ds_read_b128 v[158:161], v158 offset:3072
	ds_read_b128 v[172:175], v194 offset:33792
	ds_read_b128 v[176:179], v194 offset:34816
	ds_read_b128 v[180:183], v194 offset:35840
	ds_read_b128 v[184:187], v194 offset:36864
	ds_read_b128 v[188:191], v194 offset:37888
	ds_read_b128 v[196:199], v194 offset:38912
	ds_read_b128 v[200:203], v194 offset:39936
	ds_read_b128 v[204:207], v194 offset:40960
	s_waitcnt vmcnt(8)
	s_waitcnt lgkmcnt(0)
	s_setprio 1
	s_barrier
	v_mfma_f32_16x16x32_bf16 v[142:145], v[114:117], v[172:175], v[142:145]
	v_mfma_f32_16x16x32_bf16 v[138:141], v[130:133], v[172:175], v[138:141]
	v_mfma_f32_16x16x32_bf16 v[126:129], v[114:117], v[180:183], v[126:129]
	v_mfma_f32_16x16x32_bf16 v[122:125], v[130:133], v[180:183], v[122:125]
	v_mfma_f32_16x16x32_bf16 v[110:113], v[114:117], v[188:191], v[110:113]
	v_mfma_f32_16x16x32_bf16 v[106:109], v[130:133], v[188:191], v[106:109]
	v_mfma_f32_16x16x32_bf16 v[102:105], v[114:117], v[200:203], v[102:105]
	v_mfma_f32_16x16x32_bf16 v[98:101], v[130:133], v[200:203], v[98:101]
	s_setprio 0
	s_setprio 1
	v_mfma_f32_16x16x32_bf16 v[142:145], v[118:121], v[176:179], v[142:145]
	v_mfma_f32_16x16x32_bf16 v[138:141], v[134:137], v[176:179], v[138:141]
	v_mfma_f32_16x16x32_bf16 v[126:129], v[118:121], v[184:187], v[126:129]
	v_mfma_f32_16x16x32_bf16 v[122:125], v[134:137], v[184:187], v[122:125]
	v_mfma_f32_16x16x32_bf16 v[110:113], v[118:121], v[196:199], v[110:113]
	v_mfma_f32_16x16x32_bf16 v[106:109], v[134:137], v[196:199], v[106:109]
	v_mfma_f32_16x16x32_bf16 v[102:105], v[118:121], v[204:207], v[102:105]
	v_mfma_f32_16x16x32_bf16 v[98:101], v[134:137], v[204:207], v[98:101]
	s_setprio 0
	s_setprio 1
	v_mfma_f32_16x16x32_bf16 v[62:65], v[146:149], v[172:175], v[62:65]
	v_mfma_f32_16x16x32_bf16 v[58:61], v[154:157], v[172:175], v[58:61]
	v_mfma_f32_16x16x32_bf16 v[54:57], v[146:149], v[180:183], v[54:57]
	v_mfma_f32_16x16x32_bf16 v[50:53], v[154:157], v[180:183], v[50:53]
	v_mfma_f32_16x16x32_bf16 v[46:49], v[146:149], v[188:191], v[46:49]
	v_mfma_f32_16x16x32_bf16 v[42:45], v[154:157], v[188:191], v[42:45]
	v_mfma_f32_16x16x32_bf16 v[38:41], v[146:149], v[200:203], v[38:41]
	v_mfma_f32_16x16x32_bf16 v[34:37], v[154:157], v[200:203], v[34:37]
	s_setprio 0
	s_setprio 1
	v_mfma_f32_16x16x32_bf16 v[62:65], v[150:153], v[176:179], v[62:65]
	v_mfma_f32_16x16x32_bf16 v[58:61], v[158:161], v[176:179], v[58:61]
	v_mfma_f32_16x16x32_bf16 v[54:57], v[150:153], v[184:187], v[54:57]
	v_mfma_f32_16x16x32_bf16 v[50:53], v[158:161], v[184:187], v[50:53]
	v_mfma_f32_16x16x32_bf16 v[46:49], v[150:153], v[196:199], v[46:49]
	v_mfma_f32_16x16x32_bf16 v[42:45], v[158:161], v[196:199], v[42:45]
	v_mfma_f32_16x16x32_bf16 v[38:41], v[150:153], v[204:207], v[38:41]
	v_mfma_f32_16x16x32_bf16 v[34:37], v[158:161], v[204:207], v[34:37]
	s_setprio 0
	s_barrier
; #define PG8_STAGE(bufoff, gbase, voff) do { _Pragma("unroll") for (int _i = 0; _i < 2; ++_i) \
;         __builtin_amdgcn_global_load_lds((const GAS unsigned*)((const GAS char*)(gbase) + (voff)[_i]), (LAS unsigned*)(lds + (bufoff) + ldsw + _i * 8192), 16, 0, 0); } while (0)
; #define PG8_LDA(dst, b, h) do { _Pragma("unroll") for (int m = 0; m < 4; ++m) _Pragma("unroll") for (int k = 0; k < 2; ++k) dst[m][k] = *(const LAS bf16x8*)(lds + PG8_SA(b, h) + aoff + m * 2048 + k * 1024); } while (0)
; #define PG8_MMA(ai, bj, At, Bt) do { __builtin_amdgcn_s_setprio(1); _Pragma("unroll") for (int m = 0; m < 4; ++m) _Pragma("unroll") for (int n = 0; n < 2; ++n) _Pragma("unroll") for (int k = 0; k < 2; ++k) \
;         acc[ai][bj][m][n] = __builtin_amdgcn_mfma_f32_16x16x32_bf16(Bt[n][k], At[m][k], acc[ai][bj][m][n], 0, 0, 0); __builtin_amdgcn_s_setprio(0); } while (0)
; #define PG8_WAIT_V(n) asm volatile("s_waitcnt vmcnt(" #n ")" ::: "memory")
; #define PG8_WAIT_L(n) asm volatile("s_waitcnt lgkmcnt(" #n ")" ::: "memory")
; #define PG8_BAR __builtin_amdgcn_s_barrier()
; #define PG8_SCHED __builtin_amdgcn_sched_barrier(0)
; template <class Epi, class Sched, bool ALIGN_EPI>
; __device__ __forceinline__ void gemm_phase(LAS unsigned char* lds, const Gemm g, const Sched& S, const Epi& E, int wave_id) {
;     ...
;             PG8_LDA(At, 1, 1); PG8_STAGE(PG8_SB(1, 0), b3, voffB); PG8_STAGE(PG8_SB(1, 1), b3 + hsB, voffB); PG8_STAGE(PG8_SA(1, 0), a3, voffA);
;             PG8_WAIT_V(8); PG8_WAIT_L(0); PG8_BAR; PG8_MMA(1, 0, At, B0); PG8_MMA(1, 1, At, B1); PG8_BAR; PG8_SCHED;
;         }
;         if constexpr (ALIGN_EPI) { if (wr == 0) PG8_BAR; }
	s_mov_b32 m0, s44
	v_lshl_add_u64 v[192:193], v[192:193], 0, s[92:93]
	s_add_u32 s18, s22, 0x18080
	global_load_lds_dwordx4 v[192:193], off
	v_lshl_add_u64 v[192:193], v[208:209], 0, s[92:93]
	s_mov_b32 m0, s45
	s_addc_u32 s19, s23, 0
	global_load_lds_dwordx4 v[192:193], off
	v_lshl_add_u64 v[192:193], s[18:19], 0, v[0:1]
	s_mov_b32 m0, s48
	s_nop 0
	global_load_lds_dwordx4 v[192:193], off
	v_lshl_add_u64 v[192:193], s[18:19], 0, v[162:163]
	s_mov_b32 m0, s49
	s_nop 0
	global_load_lds_dwordx4 v[192:193], off
	v_lshl_add_u64 v[192:193], v[210:211], 0, s[92:93]
	s_mov_b32 m0, s46
	s_nop 0
	global_load_lds_dwordx4 v[192:193], off
	v_lshl_add_u64 v[192:193], v[212:213], 0, s[92:93]
	s_mov_b32 m0, s47
	s_nop 0
	global_load_lds_dwordx4 v[192:193], off
	ds_read_b128 v[172:175], v194 offset:50176
	ds_read_b128 v[176:179], v194 offset:51200
	ds_read_b128 v[180:183], v194 offset:52224
	ds_read_b128 v[184:187], v194 offset:53248
	ds_read_b128 v[188:191], v194 offset:54272
	ds_read_b128 v[196:199], v194 offset:55296
	ds_read_b128 v[200:203], v194 offset:56320
	ds_read_b128 v[204:207], v194 offset:57344
	s_waitcnt vmcnt(8)
	s_waitcnt lgkmcnt(0)
	s_setprio 1
	s_barrier
	v_mfma_f32_16x16x32_bf16 v[94:97], v[114:117], v[172:175], v[94:97]
	v_mfma_f32_16x16x32_bf16 v[90:93], v[130:133], v[172:175], v[90:93]
	v_mfma_f32_16x16x32_bf16 v[86:89], v[114:117], v[180:183], v[86:89]
	v_mfma_f32_16x16x32_bf16 v[82:85], v[130:133], v[180:183], v[82:85]
	v_mfma_f32_16x16x32_bf16 v[78:81], v[114:117], v[188:191], v[78:81]
	v_mfma_f32_16x16x32_bf16 v[74:77], v[130:133], v[188:191], v[74:77]
	v_mfma_f32_16x16x32_bf16 v[70:73], v[114:117], v[200:203], v[70:73]
	v_mfma_f32_16x16x32_bf16 v[66:69], v[130:133], v[200:203], v[66:69]
	s_setprio 0
	s_setprio 1
	v_mfma_f32_16x16x32_bf16 v[94:97], v[118:121], v[176:179], v[94:97]
	v_mfma_f32_16x16x32_bf16 v[90:93], v[134:137], v[176:179], v[90:93]
	v_mfma_f32_16x16x32_bf16 v[86:89], v[118:121], v[184:187], v[86:89]
	v_mfma_f32_16x16x32_bf16 v[82:85], v[134:137], v[184:187], v[82:85]
	v_mfma_f32_16x16x32_bf16 v[78:81], v[118:121], v[196:199], v[78:81]
	v_mfma_f32_16x16x32_bf16 v[74:77], v[134:137], v[196:199], v[74:77]
	v_mfma_f32_16x16x32_bf16 v[70:73], v[118:121], v[204:207], v[70:73]
	v_mfma_f32_16x16x32_bf16 v[66:69], v[134:137], v[204:207], v[66:69]
	s_setprio 0
	s_setprio 1
	v_mfma_f32_16x16x32_bf16 v[30:33], v[146:149], v[172:175], v[30:33]
	v_mfma_f32_16x16x32_bf16 v[26:29], v[154:157], v[172:175], v[26:29]
	v_mfma_f32_16x16x32_bf16 v[22:25], v[146:149], v[180:183], v[22:25]
	v_mfma_f32_16x16x32_bf16 v[18:21], v[154:157], v[180:183], v[18:21]
	v_mfma_f32_16x16x32_bf16 v[14:17], v[146:149], v[188:191], v[14:17]
	v_mfma_f32_16x16x32_bf16 v[10:13], v[154:157], v[188:191], v[10:13]
	v_mfma_f32_16x16x32_bf16 v[6:9], v[146:149], v[200:203], v[6:9]
	v_mfma_f32_16x16x32_bf16 v[2:5], v[154:157], v[200:203], v[2:5]
	s_setprio 0
	s_setprio 1
	v_mfma_f32_16x16x32_bf16 v[30:33], v[150:153], v[176:179], v[30:33]
	v_mfma_f32_16x16x32_bf16 v[26:29], v[158:161], v[176:179], v[26:29]
	v_mfma_f32_16x16x32_bf16 v[22:25], v[150:153], v[184:187], v[22:25]
	v_mfma_f32_16x16x32_bf16 v[18:21], v[158:161], v[184:187], v[18:21]
	v_mfma_f32_16x16x32_bf16 v[14:17], v[150:153], v[196:199], v[14:17]
	v_mfma_f32_16x16x32_bf16 v[10:13], v[158:161], v[196:199], v[10:13]
	v_mfma_f32_16x16x32_bf16 v[6:9], v[150:153], v[204:207], v[6:9]
	v_mfma_f32_16x16x32_bf16 v[2:5], v[158:161], v[204:207], v[2:5]
	s_setprio 0
	s_barrier
	s_add_i32 s55, s55, 2
	s_add_u32 s53, s53, 0x100
	s_addc_u32 s54, s54, 0
	s_cmp_gt_u32 s55, 3
	s_mov_b64 s[18:19], s[20:21]
	s_cbranch_scc0 .LBB0_1645
	s_and_b64 vcc, exec, s[12:13]
	s_cbranch_vccz .LBB0_1648
	s_barrier

; #define GAS __attribute__((address_space(1)))
; #define PG8_STAGE(bufoff, gbase, voff) do { _Pragma("unroll") for (int _i = 0; _i < 2; ++_i) \
;         __builtin_amdgcn_global_load_lds((const GAS unsigned*)((const GAS char*)(gbase) + (voff)[_i]), (LAS unsigned*)(lds + (bufoff) + ldsw + _i * 8192), 16, 0, 0); } while (0)
; #define PG8_LDA(dst, b, h) do { _Pragma("unroll") for (int m = 0; m < 4; ++m) _Pragma("unroll") for (int k = 0; k < 2; ++k) dst[m][k] = *(const LAS bf16x8*)(lds + PG8_SA(b, h) + aoff + m * 2048 + k * 1024); } while (0)
; #define PG8_LDB(dst, b, h) do { _Pragma("unroll") for (int n = 0; n < 2; ++n) _Pragma("unroll") for (int k = 0; k < 2; ++k) dst[n][k] = *(const LAS bf16x8*)(lds + PG8_SB(b, h) + boff + n * 2048 + k * 1024); } while (0)
; #define PG8_MMA(ai, bj, At, Bt) do { __builtin_amdgcn_s_setprio(1); _Pragma("unroll") for (int m = 0; m < 4; ++m) _Pragma("unroll") for (int n = 0; n < 2; ++n) _Pragma("unroll") for (int k = 0; k < 2; ++k) \
;         acc[ai][bj][m][n] = __builtin_amdgcn_mfma_f32_16x16x32_bf16(Bt[n][k], At[m][k], acc[ai][bj][m][n], 0, 0, 0); __builtin_amdgcn_s_setprio(0); } while (0)
; #define PG8_WAIT_V(n) asm volatile("s_waitcnt vmcnt(" #n ")" ::: "memory")
; #define PG8_WAIT_L(n) asm volatile("s_waitcnt lgkmcnt(" #n ")" ::: "memory")
; #define PG8_BAR __builtin_amdgcn_s_barrier()
; template <class Epi, class Sched, bool ALIGN_EPI>
; __device__ __forceinline__ void gemm_phase(LAS unsigned char* lds, const Gemm g, const Sched& S, const Epi& E, int wave_id) {
;     ...
;             const bool last = (t == nt - 2);
;             const GAS char* a1 = cA + (size_t)(t + 1) * kstep;
;             const GAS char* a2 = last ? nA : cA + (size_t)(t + 2) * kstep; const GAS char* b2 = last ? nB : cB + (size_t)(t + 2) * kstep;
;             const GAS char* a3 = a2 + kstep; const GAS char* b3 = b2 + kstep;
;             PG8_LDB(B0, 0, 0); PG8_LDB(B1, 0, 1); PG8_SCHED; PG8_LDA(At, 0, 0); PG8_STAGE(PG8_SA(1, 1), a1 + hsA, voffA);
;             PG8_WAIT_V(8); PG8_WAIT_L(0); PG8_BAR; PG8_MMA(0, 0, At, B0); PG8_MMA(0, 1, At, B1); PG8_BAR; PG8_SCHED;
;             PG8_LDA(At, 0, 1); PG8_STAGE(PG8_SB(0, 0), b2, voffB); PG8_STAGE(PG8_SB(0, 1), b2 + hsB, voffB); PG8_STAGE(PG8_SA(0, 0), a2, voffA);
;             PG8_WAIT_V(8); PG8_WAIT_L(0); PG8_BAR; PG8_MMA(1, 0, At, B0); PG8_MMA(1, 1, At, B1); PG8_BAR; PG8_SCHED;
.LBB0_1837:
	s_add_u32 s42, s40, 0xfffc0080
	s_addc_u32 s43, s41, -1
	s_cmp_eq_u32 s67, 12
	s_cselect_b32 s45, s5, s43
	s_cselect_b32 s44, s25, s42
	s_cselect_b32 s43, s27, s66
	s_cselect_b32 s42, s37, s39
	v_lshl_add_u64 v[196:197], s[40:41], 0, v[182:183]
	s_add_i32 m0, s1, 0xc400
	s_nop 0
	global_load_lds_dwordx4 v[196:197], off
	v_lshl_add_u64 v[196:197], s[40:41], 0, v[180:181]
	s_add_i32 m0, s1, 0xe400
	s_nop 0
	global_load_lds_dwordx4 v[196:197], off
	v_add_u32_e32 v142, 0x10400, v199
	v_add_u32_e32 v158, 0x14400, v199
	ds_read_b128 v[130:133], v142
	ds_read_b128 v[134:137], v142 offset:1024
	ds_read_b128 v[138:141], v142 offset:2048
	ds_read_b128 v[142:145], v142 offset:3072
	ds_read_b128 v[146:149], v158
	ds_read_b128 v[150:153], v158 offset:1024
	ds_read_b128 v[154:157], v158 offset:2048
	ds_read_b128 v[158:161], v158 offset:3072
	ds_read_b128 v[162:165], v198 offset:1024
	ds_read_b128 v[166:169], v198 offset:2048
	ds_read_b128 v[170:173], v198 offset:3072
	ds_read_b128 v[184:187], v198 offset:4096
	ds_read_b128 v[188:191], v198 offset:5120
	ds_read_b128 v[192:195], v198 offset:6144
	ds_read_b128 v[200:203], v198 offset:7168
	ds_read_b128 v[204:207], v198 offset:8192
	s_waitcnt vmcnt(8)
	s_waitcnt lgkmcnt(0)
	s_setprio 1
	s_barrier
	v_mfma_f32_16x16x32_bf16 v[126:129], v[130:133], v[162:165], v[126:129]
	v_mfma_f32_16x16x32_bf16 v[122:125], v[138:141], v[162:165], v[122:125]
	v_mfma_f32_16x16x32_bf16 v[114:117], v[130:133], v[170:173], v[114:117]
	v_mfma_f32_16x16x32_bf16 v[106:109], v[138:141], v[170:173], v[106:109]
	v_mfma_f32_16x16x32_bf16 v[98:101], v[130:133], v[188:191], v[98:101]
	v_mfma_f32_16x16x32_bf16 v[90:93], v[138:141], v[188:191], v[90:93]
	v_mfma_f32_16x16x32_bf16 v[82:85], v[130:133], v[200:203], v[82:85]
	v_mfma_f32_16x16x32_bf16 v[74:77], v[138:141], v[200:203], v[74:77]
	s_setprio 0
	s_setprio 1
	v_mfma_f32_16x16x32_bf16 v[126:129], v[134:137], v[166:169], v[126:129]
	v_mfma_f32_16x16x32_bf16 v[122:125], v[142:145], v[166:169], v[122:125]
	v_mfma_f32_16x16x32_bf16 v[114:117], v[134:137], v[184:187], v[114:117]
	v_mfma_f32_16x16x32_bf16 v[106:109], v[142:145], v[184:187], v[106:109]
	v_mfma_f32_16x16x32_bf16 v[98:101], v[134:137], v[192:195], v[98:101]
	v_mfma_f32_16x16x32_bf16 v[90:93], v[142:145], v[192:195], v[90:93]
	v_mfma_f32_16x16x32_bf16 v[82:85], v[134:137], v[204:207], v[82:85]
	v_mfma_f32_16x16x32_bf16 v[74:77], v[142:145], v[204:207], v[74:77]
	s_setprio 0
	s_setprio 1
	v_mfma_f32_16x16x32_bf16 v[118:121], v[146:149], v[162:165], v[118:121]
	v_mfma_f32_16x16x32_bf16 v[110:113], v[154:157], v[162:165], v[110:113]
	v_mfma_f32_16x16x32_bf16 v[102:105], v[146:149], v[170:173], v[102:105]
	v_mfma_f32_16x16x32_bf16 v[94:97], v[154:157], v[170:173], v[94:97]
	v_mfma_f32_16x16x32_bf16 v[86:89], v[146:149], v[188:191], v[86:89]
	v_mfma_f32_16x16x32_bf16 v[78:81], v[154:157], v[188:191], v[78:81]
	v_mfma_f32_16x16x32_bf16 v[70:73], v[146:149], v[200:203], v[70:73]
	v_mfma_f32_16x16x32_bf16 v[66:69], v[154:157], v[200:203], v[66:69]
	s_setprio 0
	s_setprio 1
	v_mfma_f32_16x16x32_bf16 v[118:121], v[150:153], v[166:169], v[118:121]
	v_mfma_f32_16x16x32_bf16 v[110:113], v[158:161], v[166:169], v[110:113]
	v_mfma_f32_16x16x32_bf16 v[102:105], v[150:153], v[184:187], v[102:105]
	v_mfma_f32_16x16x32_bf16 v[94:97], v[158:161], v[184:187], v[94:97]
	v_mfma_f32_16x16x32_bf16 v[86:89], v[150:153], v[192:195], v[86:89]
	v_mfma_f32_16x16x32_bf16 v[78:81], v[158:161], v[192:195], v[78:81]
	v_mfma_f32_16x16x32_bf16 v[70:73], v[150:153], v[204:207], v[70:73]
	v_mfma_f32_16x16x32_bf16 v[66:69], v[158:161], v[204:207], v[66:69]
	s_setprio 0
	s_barrier
	s_mov_b32 m0, s48
	v_lshl_add_u64 v[196:197], s[42:43], 0, v[0:1]
	s_add_u32 s68, s42, 0x40000
	global_load_lds_dwordx4 v[196:197], off
	v_lshl_add_u64 v[208:209], s[42:43], 0, v[178:179]
	s_mov_b32 m0, s49
	s_addc_u32 s69, s43, 0
	global_load_lds_dwordx4 v[208:209], off
	v_lshl_add_u64 v[210:211], s[68:69], 0, v[0:1]
	s_mov_b32 m0, s50
	v_lshl_add_u64 v[212:213], s[44:45], 0, v[176:177]
	global_load_lds_dwordx4 v[210:211], off
	v_lshl_add_u64 v[210:211], s[68:69], 0, v[178:179]
	s_mov_b32 m0, s51
	s_nop 0
	global_load_lds_dwordx4 v[210:211], off
	v_lshl_add_u64 v[210:211], s[44:45], 0, v[174:175]
	s_mov_b32 m0, s52
	s_nop 0
	global_load_lds_dwordx4 v[210:211], off
	s_mov_b32 m0, s53
	s_nop 0
	global_load_lds_dwordx4 v[212:213], off
	ds_read_b128 v[162:165], v198 offset:17408
	ds_read_b128 v[166:169], v198 offset:18432
	ds_read_b128 v[170:173], v198 offset:19456
	ds_read_b128 v[184:187], v198 offset:20480
	ds_read_b128 v[188:191], v198 offset:21504
	ds_read_b128 v[192:195], v198 offset:22528
	ds_read_b128 v[200:203], v198 offset:23552
	ds_read_b128 v[204:207], v198 offset:24576
	s_waitcnt vmcnt(8)
	s_waitcnt lgkmcnt(0)
	s_setprio 1
	s_barrier
; #define PG8_STAGE(bufoff, gbase, voff) do { _Pragma("unroll") for (int _i = 0; _i < 2; ++_i) \
;         __builtin_amdgcn_global_load_lds((const GAS unsigned*)((const GAS char*)(gbase) + (voff)[_i]), (LAS unsigned*)(lds + (bufoff) + ldsw + _i * 8192), 16, 0, 0); } while (0)
; #define PG8_LDA(dst, b, h) do { _Pragma("unroll") for (int m = 0; m < 4; ++m) _Pragma("unroll") for (int k = 0; k < 2; ++k) dst[m][k] = *(const LAS bf16x8*)(lds + PG8_SA(b, h) + aoff + m * 2048 + k * 1024); } while (0)
; #define PG8_LDB(dst, b, h) do { _Pragma("unroll") for (int n = 0; n < 2; ++n) _Pragma("unroll") for (int k = 0; k < 2; ++k) dst[n][k] = *(const LAS bf16x8*)(lds + PG8_SB(b, h) + boff + n * 2048 + k * 1024); } while (0)
; #define PG8_MMA(ai, bj, At, Bt) do { __builtin_amdgcn_s_setprio(1); _Pragma("unroll") for (int m = 0; m < 4; ++m) _Pragma("unroll") for (int n = 0; n < 2; ++n) _Pragma("unroll") for (int k = 0; k < 2; ++k) \
;         acc[ai][bj][m][n] = __builtin_amdgcn_mfma_f32_16x16x32_bf16(Bt[n][k], At[m][k], acc[ai][bj][m][n], 0, 0, 0); __builtin_amdgcn_s_setprio(0); } while (0)
; #define PG8_WAIT_V(n) asm volatile("s_waitcnt vmcnt(" #n ")" ::: "memory")
; #define PG8_WAIT_L(n) asm volatile("s_waitcnt lgkmcnt(" #n ")" ::: "memory")
; #define PG8_BAR __builtin_amdgcn_s_barrier()
; #define PG8_SCHED __builtin_amdgcn_sched_barrier(0)
; template <class Epi, class Sched, bool ALIGN_EPI>
; __device__ __forceinline__ void gemm_phase(LAS unsigned char* lds, const Gemm g, const Sched& S, const Epi& E, int wave_id) {
;     ...
;             PG8_WAIT_V(8); PG8_WAIT_L(0); PG8_BAR; PG8_MMA(1, 0, At, B0); PG8_MMA(1, 1, At, B1); PG8_BAR; PG8_SCHED;
;             PG8_LDB(B0, 1, 0); PG8_LDB(B1, 1, 1); PG8_SCHED; PG8_LDA(At, 1, 0); PG8_STAGE(PG8_SA(0, 1), a2 + hsA, voffA);
;             PG8_WAIT_V(8); PG8_WAIT_L(0); PG8_BAR; PG8_MMA(0, 0, At, B0); PG8_MMA(0, 1, At, B1); PG8_BAR; PG8_SCHED;
	v_mfma_f32_16x16x32_bf16 v[62:65], v[130:133], v[162:165], v[62:65]
	v_mfma_f32_16x16x32_bf16 v[58:61], v[138:141], v[162:165], v[58:61]
	v_mfma_f32_16x16x32_bf16 v[50:53], v[130:133], v[170:173], v[50:53]
	v_mfma_f32_16x16x32_bf16 v[42:45], v[138:141], v[170:173], v[42:45]
	v_mfma_f32_16x16x32_bf16 v[34:37], v[130:133], v[188:191], v[34:37]
	v_mfma_f32_16x16x32_bf16 v[26:29], v[138:141], v[188:191], v[26:29]
	v_mfma_f32_16x16x32_bf16 v[18:21], v[130:133], v[200:203], v[18:21]
	v_mfma_f32_16x16x32_bf16 v[10:13], v[138:141], v[200:203], v[10:13]
	s_setprio 0
	s_setprio 1
	v_mfma_f32_16x16x32_bf16 v[62:65], v[134:137], v[166:169], v[62:65]
	v_mfma_f32_16x16x32_bf16 v[58:61], v[142:145], v[166:169], v[58:61]
	v_mfma_f32_16x16x32_bf16 v[50:53], v[134:137], v[184:187], v[50:53]
	v_mfma_f32_16x16x32_bf16 v[42:45], v[142:145], v[184:187], v[42:45]
	v_mfma_f32_16x16x32_bf16 v[34:37], v[134:137], v[192:195], v[34:37]
	v_mfma_f32_16x16x32_bf16 v[26:29], v[142:145], v[192:195], v[26:29]
	v_mfma_f32_16x16x32_bf16 v[18:21], v[134:137], v[204:207], v[18:21]
	v_mfma_f32_16x16x32_bf16 v[10:13], v[142:145], v[204:207], v[10:13]
	s_setprio 0
	s_setprio 1
	v_mfma_f32_16x16x32_bf16 v[54:57], v[146:149], v[162:165], v[54:57]
	v_mfma_f32_16x16x32_bf16 v[46:49], v[154:157], v[162:165], v[46:49]
	v_mfma_f32_16x16x32_bf16 v[38:41], v[146:149], v[170:173], v[38:41]
	v_mfma_f32_16x16x32_bf16 v[30:33], v[154:157], v[170:173], v[30:33]
	v_mfma_f32_16x16x32_bf16 v[22:25], v[146:149], v[188:191], v[22:25]
	v_mfma_f32_16x16x32_bf16 v[14:17], v[154:157], v[188:191], v[14:17]
	v_mfma_f32_16x16x32_bf16 v[6:9], v[146:149], v[200:203], v[6:9]
	v_mfma_f32_16x16x32_bf16 v[2:5], v[154:157], v[200:203], v[2:5]
	s_setprio 0
	s_setprio 1
	v_mfma_f32_16x16x32_bf16 v[54:57], v[150:153], v[166:169], v[54:57]
	v_mfma_f32_16x16x32_bf16 v[46:49], v[158:161], v[166:169], v[46:49]
	v_mfma_f32_16x16x32_bf16 v[38:41], v[150:153], v[184:187], v[38:41]
	v_mfma_f32_16x16x32_bf16 v[30:33], v[158:161], v[184:187], v[30:33]
	v_mfma_f32_16x16x32_bf16 v[22:25], v[150:153], v[192:195], v[22:25]
	v_mfma_f32_16x16x32_bf16 v[14:17], v[158:161], v[192:195], v[14:17]
	v_mfma_f32_16x16x32_bf16 v[6:9], v[150:153], v[204:207], v[6:9]
	v_mfma_f32_16x16x32_bf16 v[2:5], v[158:161], v[204:207], v[2:5]
	s_setprio 0
	s_barrier
	s_add_u32 s44, s44, 0x40000
	s_addc_u32 s45, s45, 0
	s_mov_b32 m0, s54
	v_lshl_add_u64 v[214:215], s[44:45], 0, v[174:175]
	global_load_lds_dwordx4 v[214:215], off
	v_lshl_add_u64 v[214:215], s[44:45], 0, v[176:177]
	s_mov_b32 m0, s55
	s_nop 0
	global_load_lds_dwordx4 v[214:215], off
	v_add_u32_e32 v142, 0x18400, v199
	v_add_u32_e32 v158, 0x1c400, v199
	ds_read_b128 v[130:133], v142
	ds_read_b128 v[134:137], v142 offset:1024
	ds_read_b128 v[138:141], v142 offset:2048
	ds_read_b128 v[142:145], v142 offset:3072
	ds_read_b128 v[146:149], v158
	ds_read_b128 v[150:153], v158 offset:1024
	ds_read_b128 v[154:157], v158 offset:2048
	ds_read_b128 v[158:161], v158 offset:3072
	ds_read_b128 v[162:165], v198 offset:33792
	ds_read_b128 v[166:169], v198 offset:34816
	ds_read_b128 v[170:173], v198 offset:35840
	ds_read_b128 v[184:187], v198 offset:36864
	ds_read_b128 v[188:191], v198 offset:37888
	ds_read_b128 v[192:195], v198 offset:38912
	ds_read_b128 v[200:203], v198 offset:39936
	ds_read_b128 v[204:207], v198 offset:40960
	s_waitcnt vmcnt(8)
	s_waitcnt lgkmcnt(0)
	s_setprio 1
	s_barrier
	v_mfma_f32_16x16x32_bf16 v[126:129], v[130:133], v[162:165], v[126:129]
	v_mfma_f32_16x16x32_bf16 v[122:125], v[138:141], v[162:165], v[122:125]
	v_mfma_f32_16x16x32_bf16 v[114:117], v[130:133], v[170:173], v[114:117]
	v_mfma_f32_16x16x32_bf16 v[106:109], v[138:141], v[170:173], v[106:109]
	v_mfma_f32_16x16x32_bf16 v[98:101], v[130:133], v[188:191], v[98:101]
	v_mfma_f32_16x16x32_bf16 v[90:93], v[138:141], v[188:191], v[90:93]
	v_mfma_f32_16x16x32_bf16 v[82:85], v[130:133], v[200:203], v[82:85]
	v_mfma_f32_16x16x32_bf16 v[74:77], v[138:141], v[200:203], v[74:77]
	s_setprio 0
	s_setprio 1
	v_mfma_f32_16x16x32_bf16 v[126:129], v[134:137], v[166:169], v[126:129]
	v_mfma_f32_16x16x32_bf16 v[122:125], v[142:145], v[166:169], v[122:125]
	v_mfma_f32_16x16x32_bf16 v[114:117], v[134:137], v[184:187], v[114:117]
	v_mfma_f32_16x16x32_bf16 v[106:109], v[142:145], v[184:187], v[106:109]
	v_mfma_f32_16x16x32_bf16 v[98:101], v[134:137], v[192:195], v[98:101]
	v_mfma_f32_16x16x32_bf16 v[90:93], v[142:145], v[192:195], v[90:93]
	v_mfma_f32_16x16x32_bf16 v[82:85], v[134:137], v[204:207], v[82:85]
	v_mfma_f32_16x16x32_bf16 v[74:77], v[142:145], v[204:207], v[74:77]
	s_setprio 0
	s_setprio 1
	v_mfma_f32_16x16x32_bf16 v[118:121], v[146:149], v[162:165], v[118:121]
	v_mfma_f32_16x16x32_bf16 v[110:113], v[154:157], v[162:165], v[110:113]
	v_mfma_f32_16x16x32_bf16 v[102:105], v[146:149], v[170:173], v[102:105]
	v_mfma_f32_16x16x32_bf16 v[94:97], v[154:157], v[170:173], v[94:97]
	v_mfma_f32_16x16x32_bf16 v[86:89], v[146:149], v[188:191], v[86:89]
	v_mfma_f32_16x16x32_bf16 v[78:81], v[154:157], v[188:191], v[78:81]
	v_mfma_f32_16x16x32_bf16 v[70:73], v[146:149], v[200:203], v[70:73]
	v_mfma_f32_16x16x32_bf16 v[66:69], v[154:157], v[200:203], v[66:69]
	s_setprio 0
	s_setprio 1
	v_mfma_f32_16x16x32_bf16 v[118:121], v[150:153], v[166:169], v[118:121]
	v_mfma_f32_16x16x32_bf16 v[110:113], v[158:161], v[166:169], v[110:113]
	v_mfma_f32_16x16x32_bf16 v[102:105], v[150:153], v[184:187], v[102:105]
	v_mfma_f32_16x16x32_bf16 v[94:97], v[158:161], v[184:187], v[94:97]
	v_mfma_f32_16x16x32_bf16 v[86:89], v[150:153], v[192:195], v[86:89]
	v_mfma_f32_16x16x32_bf16 v[78:81], v[158:161], v[192:195], v[78:81]
	v_mfma_f32_16x16x32_bf16 v[70:73], v[150:153], v[204:207], v[70:73]
	v_mfma_f32_16x16x32_bf16 v[66:69], v[158:161], v[204:207], v[66:69]
	s_setprio 0
	s_barrier
; #define PG8_STAGE(bufoff, gbase, voff) do { _Pragma("unroll") for (int _i = 0; _i < 2; ++_i) \
;         __builtin_amdgcn_global_load_lds((const GAS unsigned*)((const GAS char*)(gbase) + (voff)[_i]), (LAS unsigned*)(lds + (bufoff) + ldsw + _i * 8192), 16, 0, 0); } while (0)
; #define PG8_LDA(dst, b, h) do { _Pragma("unroll") for (int m = 0; m < 4; ++m) _Pragma("unroll") for (int k = 0; k < 2; ++k) dst[m][k] = *(const LAS bf16x8*)(lds + PG8_SA(b, h) + aoff + m * 2048 + k * 1024); } while (0)
; #define PG8_MMA(ai, bj, At, Bt) do { __builtin_amdgcn_s_setprio(1); _Pragma("unroll") for (int m = 0; m < 4; ++m) _Pragma("unroll") for (int n = 0; n < 2; ++n) _Pragma("unroll") for (int k = 0; k < 2; ++k) \
;         acc[ai][bj][m][n] = __builtin_amdgcn_mfma_f32_16x16x32_bf16(Bt[n][k], At[m][k], acc[ai][bj][m][n], 0, 0, 0); __builtin_amdgcn_s_setprio(0); } while (0)
; #define PG8_WAIT_V(n) asm volatile("s_waitcnt vmcnt(" #n ")" ::: "memory")
; #define PG8_WAIT_L(n) asm volatile("s_waitcnt lgkmcnt(" #n ")" ::: "memory")
; #define PG8_BAR __builtin_amdgcn_s_barrier()
; #define PG8_SCHED __builtin_amdgcn_sched_barrier(0)
; template <class Epi, class Sched, bool ALIGN_EPI>
; __device__ __forceinline__ void gemm_phase(LAS unsigned char* lds, const Gemm g, const Sched& S, const Epi& E, int wave_id) {
;     ...
;             PG8_LDA(At, 1, 1); PG8_STAGE(PG8_SB(1, 0), b3, voffB); PG8_STAGE(PG8_SB(1, 1), b3 + hsB, voffB); PG8_STAGE(PG8_SA(1, 0), a3, voffA);
;             PG8_WAIT_V(8); PG8_WAIT_L(0); PG8_BAR; PG8_MMA(1, 0, At, B0); PG8_MMA(1, 1, At, B1); PG8_BAR; PG8_SCHED;
;         }
;         if constexpr (ALIGN_EPI) { if (wr == 0) PG8_BAR; }
	s_mov_b32 m0, s58
	v_lshl_add_u64 v[196:197], v[196:197], 0, s[92:93]
	s_add_u32 s42, s42, 0x40080
	global_load_lds_dwordx4 v[196:197], off
	v_lshl_add_u64 v[196:197], v[208:209], 0, s[92:93]
	s_mov_b32 m0, s59
	s_addc_u32 s43, s43, 0
	global_load_lds_dwordx4 v[196:197], off
	v_lshl_add_u64 v[196:197], s[42:43], 0, v[0:1]
	s_mov_b32 m0, s62
	s_nop 0
	global_load_lds_dwordx4 v[196:197], off
	v_lshl_add_u64 v[196:197], s[42:43], 0, v[178:179]
	s_mov_b32 m0, s63
	s_nop 0
	global_load_lds_dwordx4 v[196:197], off
	v_lshl_add_u64 v[196:197], v[210:211], 0, s[92:93]
	s_mov_b32 m0, s60
	s_nop 0
	global_load_lds_dwordx4 v[196:197], off
	v_lshl_add_u64 v[196:197], v[212:213], 0, s[92:93]
	s_mov_b32 m0, s61
	s_nop 0
	global_load_lds_dwordx4 v[196:197], off
	ds_read_b128 v[162:165], v198 offset:50176
	ds_read_b128 v[166:169], v198 offset:51200
	ds_read_b128 v[170:173], v198 offset:52224
	ds_read_b128 v[184:187], v198 offset:53248
	ds_read_b128 v[188:191], v198 offset:54272
	ds_read_b128 v[192:195], v198 offset:55296
	ds_read_b128 v[200:203], v198 offset:56320
	ds_read_b128 v[204:207], v198 offset:57344
	s_waitcnt vmcnt(8)
	s_waitcnt lgkmcnt(0)
	s_setprio 1
	s_barrier
	v_mfma_f32_16x16x32_bf16 v[62:65], v[130:133], v[162:165], v[62:65]
	v_mfma_f32_16x16x32_bf16 v[58:61], v[138:141], v[162:165], v[58:61]
	v_mfma_f32_16x16x32_bf16 v[50:53], v[130:133], v[170:173], v[50:53]
	v_mfma_f32_16x16x32_bf16 v[42:45], v[138:141], v[170:173], v[42:45]
	v_mfma_f32_16x16x32_bf16 v[34:37], v[130:133], v[188:191], v[34:37]
	v_mfma_f32_16x16x32_bf16 v[26:29], v[138:141], v[188:191], v[26:29]
	v_mfma_f32_16x16x32_bf16 v[18:21], v[130:133], v[200:203], v[18:21]
	v_mfma_f32_16x16x32_bf16 v[10:13], v[138:141], v[200:203], v[10:13]
	s_setprio 0
	s_setprio 1
	v_mfma_f32_16x16x32_bf16 v[62:65], v[134:137], v[166:169], v[62:65]
	v_mfma_f32_16x16x32_bf16 v[58:61], v[142:145], v[166:169], v[58:61]
	v_mfma_f32_16x16x32_bf16 v[50:53], v[134:137], v[184:187], v[50:53]
	v_mfma_f32_16x16x32_bf16 v[42:45], v[142:145], v[184:187], v[42:45]
	v_mfma_f32_16x16x32_bf16 v[34:37], v[134:137], v[192:195], v[34:37]
	v_mfma_f32_16x16x32_bf16 v[26:29], v[142:145], v[192:195], v[26:29]
	v_mfma_f32_16x16x32_bf16 v[18:21], v[134:137], v[204:207], v[18:21]
	v_mfma_f32_16x16x32_bf16 v[10:13], v[142:145], v[204:207], v[10:13]
	s_setprio 0
	s_setprio 1
	v_mfma_f32_16x16x32_bf16 v[54:57], v[146:149], v[162:165], v[54:57]
	v_mfma_f32_16x16x32_bf16 v[46:49], v[154:157], v[162:165], v[46:49]
	v_mfma_f32_16x16x32_bf16 v[38:41], v[146:149], v[170:173], v[38:41]
	v_mfma_f32_16x16x32_bf16 v[30:33], v[154:157], v[170:173], v[30:33]
	v_mfma_f32_16x16x32_bf16 v[22:25], v[146:149], v[188:191], v[22:25]
	v_mfma_f32_16x16x32_bf16 v[14:17], v[154:157], v[188:191], v[14:17]
	v_mfma_f32_16x16x32_bf16 v[6:9], v[146:149], v[200:203], v[6:9]
	v_mfma_f32_16x16x32_bf16 v[2:5], v[154:157], v[200:203], v[2:5]
	s_setprio 0
	s_setprio 1
	v_mfma_f32_16x16x32_bf16 v[54:57], v[150:153], v[166:169], v[54:57]
	v_mfma_f32_16x16x32_bf16 v[46:49], v[158:161], v[166:169], v[46:49]
	v_mfma_f32_16x16x32_bf16 v[38:41], v[150:153], v[184:187], v[38:41]
	v_mfma_f32_16x16x32_bf16 v[30:33], v[158:161], v[184:187], v[30:33]
	v_mfma_f32_16x16x32_bf16 v[22:25], v[150:153], v[192:195], v[22:25]
	v_mfma_f32_16x16x32_bf16 v[14:17], v[158:161], v[192:195], v[14:17]
	v_mfma_f32_16x16x32_bf16 v[6:9], v[150:153], v[204:207], v[6:9]
	v_mfma_f32_16x16x32_bf16 v[2:5], v[158:161], v[204:207], v[2:5]
	s_setprio 0
	s_barrier
	s_add_i32 s67, s67, 2
	s_add_u32 s39, s39, 0x100
	s_addc_u32 s66, s66, 0
	s_add_u32 s40, s40, 0x100
	s_addc_u32 s41, s41, 0
	s_cmp_gt_u32 s67, 13
	s_cbranch_scc0 .LBB0_1837
	s_and_b64 vcc, exec, s[22:23]
	s_cbranch_vccz .LBB0_1840
	s_barrier

; #define GAS __attribute__((address_space(1)))
; #define PG8_STAGE(bufoff, gbase, voff) do { _Pragma("unroll") for (int _i = 0; _i < 2; ++_i) \
;         __builtin_amdgcn_global_load_lds((const GAS unsigned*)((const GAS char*)(gbase) + (voff)[_i]), (LAS unsigned*)(lds + (bufoff) + ldsw + _i * 8192), 16, 0, 0); } while (0)
; #define PG8_LDA(dst, b, h) do { _Pragma("unroll") for (int m = 0; m < 4; ++m) _Pragma("unroll") for (int k = 0; k < 2; ++k) dst[m][k] = *(const LAS bf16x8*)(lds + PG8_SA(b, h) + aoff + m * 2048 + k * 1024); } while (0)
; #define PG8_LDB(dst, b, h) do { _Pragma("unroll") for (int n = 0; n < 2; ++n) _Pragma("unroll") for (int k = 0; k < 2; ++k) dst[n][k] = *(const LAS bf16x8*)(lds + PG8_SB(b, h) + boff + n * 2048 + k * 1024); } while (0)
; #define PG8_MMA(ai, bj, At, Bt) do { __builtin_amdgcn_s_setprio(1); _Pragma("unroll") for (int m = 0; m < 4; ++m) _Pragma("unroll") for (int n = 0; n < 2; ++n) _Pragma("unroll") for (int k = 0; k < 2; ++k) \
;         acc[ai][bj][m][n] = __builtin_amdgcn_mfma_f32_16x16x32_bf16(Bt[n][k], At[m][k], acc[ai][bj][m][n], 0, 0, 0); __builtin_amdgcn_s_setprio(0); } while (0)
; #define PG8_WAIT_V(n) asm volatile("s_waitcnt vmcnt(" #n ")" ::: "memory")
; #define PG8_WAIT_L(n) asm volatile("s_waitcnt lgkmcnt(" #n ")" ::: "memory")
; #define PG8_BAR __builtin_amdgcn_s_barrier()
; template <class Epi, class Sched, bool ALIGN_EPI>
; __device__ __forceinline__ void gemm_phase(LAS unsigned char* lds, const Gemm g, const Sched& S, const Epi& E, int wave_id) {
;     ...
;             const bool last = (t == nt - 2);
;             const GAS char* a1 = cA + (size_t)(t + 1) * kstep;
;             const GAS char* a2 = last ? nA : cA + (size_t)(t + 2) * kstep; const GAS char* b2 = last ? nB : cB + (size_t)(t + 2) * kstep;
;             const GAS char* a3 = a2 + kstep; const GAS char* b3 = b2 + kstep;
;             PG8_LDB(B0, 0, 0); PG8_LDB(B1, 0, 1); PG8_SCHED; PG8_LDA(At, 0, 0); PG8_STAGE(PG8_SA(1, 1), a1 + hsA, voffA);
;             PG8_WAIT_V(8); PG8_WAIT_L(0); PG8_BAR; PG8_MMA(0, 0, At, B0); PG8_MMA(0, 1, At, B1); PG8_BAR; PG8_SCHED;
;             PG8_LDA(At, 0, 1); PG8_STAGE(PG8_SB(0, 0), b2, voffB); PG8_STAGE(PG8_SB(0, 1), b2 + hsB, voffB); PG8_STAGE(PG8_SA(0, 0), a2, voffA);
;             PG8_WAIT_V(8); PG8_WAIT_L(0); PG8_BAR; PG8_MMA(1, 0, At, B0); PG8_MMA(1, 1, At, B1); PG8_BAR; PG8_SCHED;
.LBB0_2565:
	s_add_u32 s28, s26, 0xfffc0080
	s_addc_u32 s29, s27, -1
	s_cmp_eq_u32 s60, 12
	s_cselect_b32 s31, s19, s29
	s_cselect_b32 s30, s33, s28
	s_cselect_b32 s29, s17, s59
	s_cselect_b32 s28, s57, s58
	v_lshl_add_u64 v[206:207], s[26:27], 0, v[138:139]
	s_add_i32 m0, s40, 0xc400
	s_nop 0
	global_load_lds_dwordx4 v[206:207], off
	v_lshl_add_u64 v[206:207], s[26:27], 0, v[136:137]
	s_add_i32 m0, s40, 0xe400
	s_nop 0
	global_load_lds_dwordx4 v[206:207], off
	v_add_u32_e32 v154, 0x10400, v153
	v_add_u32_e32 v170, 0x14400, v153
	ds_read_b128 v[140:143], v154
	ds_read_b128 v[144:147], v154 offset:1024
	ds_read_b128 v[148:151], v154 offset:2048
	ds_read_b128 v[154:157], v154 offset:3072
	ds_read_b128 v[158:161], v170
	ds_read_b128 v[162:165], v170 offset:1024
	ds_read_b128 v[166:169], v170 offset:2048
	ds_read_b128 v[170:173], v170 offset:3072
	ds_read_b128 v[174:177], v152 offset:1024
	ds_read_b128 v[178:181], v152 offset:2048
	ds_read_b128 v[182:185], v152 offset:3072
	ds_read_b128 v[186:189], v152 offset:4096
	ds_read_b128 v[190:193], v152 offset:5120
	ds_read_b128 v[194:197], v152 offset:6144
	ds_read_b128 v[198:201], v152 offset:7168
	ds_read_b128 v[202:205], v152 offset:8192
	s_waitcnt vmcnt(8)
	s_waitcnt lgkmcnt(0)
	s_setprio 1
	s_barrier
	v_mfma_f32_16x16x32_bf16 v[126:129], v[140:143], v[174:177], v[126:129]
	v_mfma_f32_16x16x32_bf16 v[122:125], v[148:151], v[174:177], v[122:125]
	v_mfma_f32_16x16x32_bf16 v[110:113], v[140:143], v[182:185], v[110:113]
	v_mfma_f32_16x16x32_bf16 v[106:109], v[148:151], v[182:185], v[106:109]
	v_mfma_f32_16x16x32_bf16 v[94:97], v[140:143], v[190:193], v[94:97]
	v_mfma_f32_16x16x32_bf16 v[90:93], v[148:151], v[190:193], v[90:93]
	v_mfma_f32_16x16x32_bf16 v[78:81], v[140:143], v[198:201], v[78:81]
	v_mfma_f32_16x16x32_bf16 v[74:77], v[148:151], v[198:201], v[74:77]
	s_setprio 0
	s_setprio 1
	v_mfma_f32_16x16x32_bf16 v[126:129], v[144:147], v[178:181], v[126:129]
	v_mfma_f32_16x16x32_bf16 v[122:125], v[154:157], v[178:181], v[122:125]
	v_mfma_f32_16x16x32_bf16 v[110:113], v[144:147], v[186:189], v[110:113]
	v_mfma_f32_16x16x32_bf16 v[106:109], v[154:157], v[186:189], v[106:109]
	v_mfma_f32_16x16x32_bf16 v[94:97], v[144:147], v[194:197], v[94:97]
	v_mfma_f32_16x16x32_bf16 v[90:93], v[154:157], v[194:197], v[90:93]
	v_mfma_f32_16x16x32_bf16 v[78:81], v[144:147], v[202:205], v[78:81]
	v_mfma_f32_16x16x32_bf16 v[74:77], v[154:157], v[202:205], v[74:77]
	s_setprio 0
	s_setprio 1
	v_mfma_f32_16x16x32_bf16 v[118:121], v[158:161], v[174:177], v[118:121]
	v_mfma_f32_16x16x32_bf16 v[114:117], v[166:169], v[174:177], v[114:117]
	v_mfma_f32_16x16x32_bf16 v[102:105], v[158:161], v[182:185], v[102:105]
	v_mfma_f32_16x16x32_bf16 v[98:101], v[166:169], v[182:185], v[98:101]
	v_mfma_f32_16x16x32_bf16 v[86:89], v[158:161], v[190:193], v[86:89]
	v_mfma_f32_16x16x32_bf16 v[82:85], v[166:169], v[190:193], v[82:85]
	v_mfma_f32_16x16x32_bf16 v[70:73], v[158:161], v[198:201], v[70:73]
	v_mfma_f32_16x16x32_bf16 v[66:69], v[166:169], v[198:201], v[66:69]
	s_setprio 0
	s_setprio 1
	v_mfma_f32_16x16x32_bf16 v[118:121], v[162:165], v[178:181], v[118:121]
	v_mfma_f32_16x16x32_bf16 v[114:117], v[170:173], v[178:181], v[114:117]
	v_mfma_f32_16x16x32_bf16 v[102:105], v[162:165], v[186:189], v[102:105]
	v_mfma_f32_16x16x32_bf16 v[98:101], v[170:173], v[186:189], v[98:101]
	v_mfma_f32_16x16x32_bf16 v[86:89], v[162:165], v[194:197], v[86:89]
	v_mfma_f32_16x16x32_bf16 v[82:85], v[170:173], v[194:197], v[82:85]
	v_mfma_f32_16x16x32_bf16 v[70:73], v[162:165], v[202:205], v[70:73]
	v_mfma_f32_16x16x32_bf16 v[66:69], v[170:173], v[202:205], v[66:69]
	s_setprio 0
	s_barrier
	s_mov_b32 m0, s25
	v_lshl_add_u64 v[206:207], s[28:29], 0, v[0:1]
	s_add_u32 s62, s28, 0x40000
	global_load_lds_dwordx4 v[206:207], off
	v_lshl_add_u64 v[208:209], s[28:29], 0, v[130:131]
	s_mov_b32 m0, s41
	s_addc_u32 s63, s29, 0
	global_load_lds_dwordx4 v[208:209], off
	v_lshl_add_u64 v[210:211], s[62:63], 0, v[0:1]
	s_mov_b32 m0, s42
	v_lshl_add_u64 v[212:213], s[30:31], 0, v[132:133]
	global_load_lds_dwordx4 v[210:211], off
	v_lshl_add_u64 v[210:211], s[62:63], 0, v[130:131]
	s_mov_b32 m0, s43
	s_nop 0
	global_load_lds_dwordx4 v[210:211], off
	v_lshl_add_u64 v[210:211], s[30:31], 0, v[134:135]
	s_mov_b32 m0, s44
	s_nop 0
	global_load_lds_dwordx4 v[210:211], off
	s_mov_b32 m0, s45
	s_nop 0
	global_load_lds_dwordx4 v[212:213], off
	ds_read_b128 v[174:177], v152 offset:17408
	ds_read_b128 v[178:181], v152 offset:18432
	ds_read_b128 v[182:185], v152 offset:19456
	ds_read_b128 v[186:189], v152 offset:20480
	ds_read_b128 v[190:193], v152 offset:21504
	ds_read_b128 v[194:197], v152 offset:22528
	ds_read_b128 v[198:201], v152 offset:23552
	ds_read_b128 v[202:205], v152 offset:24576
	s_waitcnt vmcnt(8)
	s_waitcnt lgkmcnt(0)
	s_setprio 1
	s_barrier
; #define PG8_STAGE(bufoff, gbase, voff) do { _Pragma("unroll") for (int _i = 0; _i < 2; ++_i) \
;         __builtin_amdgcn_global_load_lds((const GAS unsigned*)((const GAS char*)(gbase) + (voff)[_i]), (LAS unsigned*)(lds + (bufoff) + ldsw + _i * 8192), 16, 0, 0); } while (0)
; #define PG8_LDA(dst, b, h) do { _Pragma("unroll") for (int m = 0; m < 4; ++m) _Pragma("unroll") for (int k = 0; k < 2; ++k) dst[m][k] = *(const LAS bf16x8*)(lds + PG8_SA(b, h) + aoff + m * 2048 + k * 1024); } while (0)
; #define PG8_LDB(dst, b, h) do { _Pragma("unroll") for (int n = 0; n < 2; ++n) _Pragma("unroll") for (int k = 0; k < 2; ++k) dst[n][k] = *(const LAS bf16x8*)(lds + PG8_SB(b, h) + boff + n * 2048 + k * 1024); } while (0)
; #define PG8_MMA(ai, bj, At, Bt) do { __builtin_amdgcn_s_setprio(1); _Pragma("unroll") for (int m = 0; m < 4; ++m) _Pragma("unroll") for (int n = 0; n < 2; ++n) _Pragma("unroll") for (int k = 0; k < 2; ++k) \
;         acc[ai][bj][m][n] = __builtin_amdgcn_mfma_f32_16x16x32_bf16(Bt[n][k], At[m][k], acc[ai][bj][m][n], 0, 0, 0); __builtin_amdgcn_s_setprio(0); } while (0)
; #define PG8_WAIT_V(n) asm volatile("s_waitcnt vmcnt(" #n ")" ::: "memory")
; #define PG8_WAIT_L(n) asm volatile("s_waitcnt lgkmcnt(" #n ")" ::: "memory")
; #define PG8_BAR __builtin_amdgcn_s_barrier()
; #define PG8_SCHED __builtin_amdgcn_sched_barrier(0)
; template <class Epi, class Sched, bool ALIGN_EPI>
; __device__ __forceinline__ void gemm_phase(LAS unsigned char* lds, const Gemm g, const Sched& S, const Epi& E, int wave_id) {
;     ...
;             PG8_WAIT_V(8); PG8_WAIT_L(0); PG8_BAR; PG8_MMA(1, 0, At, B0); PG8_MMA(1, 1, At, B1); PG8_BAR; PG8_SCHED;
;             PG8_LDB(B0, 1, 0); PG8_LDB(B1, 1, 1); PG8_SCHED; PG8_LDA(At, 1, 0); PG8_STAGE(PG8_SA(0, 1), a2 + hsA, voffA);
;             PG8_WAIT_V(8); PG8_WAIT_L(0); PG8_BAR; PG8_MMA(0, 0, At, B0); PG8_MMA(0, 1, At, B1); PG8_BAR; PG8_SCHED;
	v_mfma_f32_16x16x32_bf16 v[62:65], v[140:143], v[174:177], v[62:65]
	v_mfma_f32_16x16x32_bf16 v[58:61], v[148:151], v[174:177], v[58:61]
	v_mfma_f32_16x16x32_bf16 v[46:49], v[140:143], v[182:185], v[46:49]
	v_mfma_f32_16x16x32_bf16 v[42:45], v[148:151], v[182:185], v[42:45]
	v_mfma_f32_16x16x32_bf16 v[30:33], v[140:143], v[190:193], v[30:33]
	v_mfma_f32_16x16x32_bf16 v[26:29], v[148:151], v[190:193], v[26:29]
	v_mfma_f32_16x16x32_bf16 v[14:17], v[140:143], v[198:201], v[14:17]
	v_mfma_f32_16x16x32_bf16 v[10:13], v[148:151], v[198:201], v[10:13]
	s_setprio 0
	s_setprio 1
	v_mfma_f32_16x16x32_bf16 v[62:65], v[144:147], v[178:181], v[62:65]
	v_mfma_f32_16x16x32_bf16 v[58:61], v[154:157], v[178:181], v[58:61]
	v_mfma_f32_16x16x32_bf16 v[46:49], v[144:147], v[186:189], v[46:49]
	v_mfma_f32_16x16x32_bf16 v[42:45], v[154:157], v[186:189], v[42:45]
	v_mfma_f32_16x16x32_bf16 v[30:33], v[144:147], v[194:197], v[30:33]
	v_mfma_f32_16x16x32_bf16 v[26:29], v[154:157], v[194:197], v[26:29]
	v_mfma_f32_16x16x32_bf16 v[14:17], v[144:147], v[202:205], v[14:17]
	v_mfma_f32_16x16x32_bf16 v[10:13], v[154:157], v[202:205], v[10:13]
	s_setprio 0
	s_setprio 1
	v_mfma_f32_16x16x32_bf16 v[54:57], v[158:161], v[174:177], v[54:57]
	v_mfma_f32_16x16x32_bf16 v[50:53], v[166:169], v[174:177], v[50:53]
	v_mfma_f32_16x16x32_bf16 v[38:41], v[158:161], v[182:185], v[38:41]
	v_mfma_f32_16x16x32_bf16 v[34:37], v[166:169], v[182:185], v[34:37]
	v_mfma_f32_16x16x32_bf16 v[22:25], v[158:161], v[190:193], v[22:25]
	v_mfma_f32_16x16x32_bf16 v[18:21], v[166:169], v[190:193], v[18:21]
	v_mfma_f32_16x16x32_bf16 v[6:9], v[158:161], v[198:201], v[6:9]
	v_mfma_f32_16x16x32_bf16 v[2:5], v[166:169], v[198:201], v[2:5]
	s_setprio 0
	s_setprio 1
	v_mfma_f32_16x16x32_bf16 v[54:57], v[162:165], v[178:181], v[54:57]
	v_mfma_f32_16x16x32_bf16 v[50:53], v[170:173], v[178:181], v[50:53]
	v_mfma_f32_16x16x32_bf16 v[38:41], v[162:165], v[186:189], v[38:41]
	v_mfma_f32_16x16x32_bf16 v[34:37], v[170:173], v[186:189], v[34:37]
	v_mfma_f32_16x16x32_bf16 v[22:25], v[162:165], v[194:197], v[22:25]
	v_mfma_f32_16x16x32_bf16 v[18:21], v[170:173], v[194:197], v[18:21]
	v_mfma_f32_16x16x32_bf16 v[6:9], v[162:165], v[202:205], v[6:9]
	v_mfma_f32_16x16x32_bf16 v[2:5], v[170:173], v[202:205], v[2:5]
	s_setprio 0
	s_barrier
	s_add_u32 s30, s30, 0x40000
	s_addc_u32 s31, s31, 0
	s_mov_b32 m0, s46
	v_lshl_add_u64 v[214:215], s[30:31], 0, v[134:135]
	global_load_lds_dwordx4 v[214:215], off
	v_lshl_add_u64 v[214:215], s[30:31], 0, v[132:133]
	s_mov_b32 m0, s47
	s_nop 0
	global_load_lds_dwordx4 v[214:215], off
	v_add_u32_e32 v154, 0x18400, v153
	v_add_u32_e32 v170, 0x1c400, v153
	ds_read_b128 v[140:143], v154
	ds_read_b128 v[144:147], v154 offset:1024
	ds_read_b128 v[148:151], v154 offset:2048
	ds_read_b128 v[154:157], v154 offset:3072
	ds_read_b128 v[158:161], v170
	ds_read_b128 v[162:165], v170 offset:1024
	ds_read_b128 v[166:169], v170 offset:2048
	ds_read_b128 v[170:173], v170 offset:3072
	ds_read_b128 v[174:177], v152 offset:33792
	ds_read_b128 v[178:181], v152 offset:34816
	ds_read_b128 v[182:185], v152 offset:35840
	ds_read_b128 v[186:189], v152 offset:36864
	ds_read_b128 v[190:193], v152 offset:37888
	ds_read_b128 v[194:197], v152 offset:38912
	ds_read_b128 v[198:201], v152 offset:39936
	ds_read_b128 v[202:205], v152 offset:40960
	s_waitcnt vmcnt(8)
	s_waitcnt lgkmcnt(0)
	s_setprio 1
	s_barrier
	v_mfma_f32_16x16x32_bf16 v[126:129], v[140:143], v[174:177], v[126:129]
	v_mfma_f32_16x16x32_bf16 v[122:125], v[148:151], v[174:177], v[122:125]
	v_mfma_f32_16x16x32_bf16 v[110:113], v[140:143], v[182:185], v[110:113]
	v_mfma_f32_16x16x32_bf16 v[106:109], v[148:151], v[182:185], v[106:109]
	v_mfma_f32_16x16x32_bf16 v[94:97], v[140:143], v[190:193], v[94:97]
	v_mfma_f32_16x16x32_bf16 v[90:93], v[148:151], v[190:193], v[90:93]
	v_mfma_f32_16x16x32_bf16 v[78:81], v[140:143], v[198:201], v[78:81]
	v_mfma_f32_16x16x32_bf16 v[74:77], v[148:151], v[198:201], v[74:77]
	s_setprio 0
	s_setprio 1
	v_mfma_f32_16x16x32_bf16 v[126:129], v[144:147], v[178:181], v[126:129]
	v_mfma_f32_16x16x32_bf16 v[122:125], v[154:157], v[178:181], v[122:125]
	v_mfma_f32_16x16x32_bf16 v[110:113], v[144:147], v[186:189], v[110:113]
	v_mfma_f32_16x16x32_bf16 v[106:109], v[154:157], v[186:189], v[106:109]
	v_mfma_f32_16x16x32_bf16 v[94:97], v[144:147], v[194:197], v[94:97]
	v_mfma_f32_16x16x32_bf16 v[90:93], v[154:157], v[194:197], v[90:93]
	v_mfma_f32_16x16x32_bf16 v[78:81], v[144:147], v[202:205], v[78:81]
	v_mfma_f32_16x16x32_bf16 v[74:77], v[154:157], v[202:205], v[74:77]
	s_setprio 0
	s_setprio 1
	v_mfma_f32_16x16x32_bf16 v[118:121], v[158:161], v[174:177], v[118:121]
	v_mfma_f32_16x16x32_bf16 v[114:117], v[166:169], v[174:177], v[114:117]
	v_mfma_f32_16x16x32_bf16 v[102:105], v[158:161], v[182:185], v[102:105]
	v_mfma_f32_16x16x32_bf16 v[98:101], v[166:169], v[182:185], v[98:101]
	v_mfma_f32_16x16x32_bf16 v[86:89], v[158:161], v[190:193], v[86:89]
	v_mfma_f32_16x16x32_bf16 v[82:85], v[166:169], v[190:193], v[82:85]
	v_mfma_f32_16x16x32_bf16 v[70:73], v[158:161], v[198:201], v[70:73]
	v_mfma_f32_16x16x32_bf16 v[66:69], v[166:169], v[198:201], v[66:69]
	s_setprio 0
	s_setprio 1
	v_mfma_f32_16x16x32_bf16 v[118:121], v[162:165], v[178:181], v[118:121]
	v_mfma_f32_16x16x32_bf16 v[114:117], v[170:173], v[178:181], v[114:117]
	v_mfma_f32_16x16x32_bf16 v[102:105], v[162:165], v[186:189], v[102:105]
	v_mfma_f32_16x16x32_bf16 v[98:101], v[170:173], v[186:189], v[98:101]
	v_mfma_f32_16x16x32_bf16 v[86:89], v[162:165], v[194:197], v[86:89]
	v_mfma_f32_16x16x32_bf16 v[82:85], v[170:173], v[194:197], v[82:85]
	v_mfma_f32_16x16x32_bf16 v[70:73], v[162:165], v[202:205], v[70:73]
	v_mfma_f32_16x16x32_bf16 v[66:69], v[170:173], v[202:205], v[66:69]
	s_setprio 0
	s_barrier
; #define PG8_STAGE(bufoff, gbase, voff) do { _Pragma("unroll") for (int _i = 0; _i < 2; ++_i) \
;         __builtin_amdgcn_global_load_lds((const GAS unsigned*)((const GAS char*)(gbase) + (voff)[_i]), (LAS unsigned*)(lds + (bufoff) + ldsw + _i * 8192), 16, 0, 0); } while (0)
; #define PG8_LDA(dst, b, h) do { _Pragma("unroll") for (int m = 0; m < 4; ++m) _Pragma("unroll") for (int k = 0; k < 2; ++k) dst[m][k] = *(const LAS bf16x8*)(lds + PG8_SA(b, h) + aoff + m * 2048 + k * 1024); } while (0)
; #define PG8_MMA(ai, bj, At, Bt) do { __builtin_amdgcn_s_setprio(1); _Pragma("unroll") for (int m = 0; m < 4; ++m) _Pragma("unroll") for (int n = 0; n < 2; ++n) _Pragma("unroll") for (int k = 0; k < 2; ++k) \
;         acc[ai][bj][m][n] = __builtin_amdgcn_mfma_f32_16x16x32_bf16(Bt[n][k], At[m][k], acc[ai][bj][m][n], 0, 0, 0); __builtin_amdgcn_s_setprio(0); } while (0)
; #define PG8_WAIT_V(n) asm volatile("s_waitcnt vmcnt(" #n ")" ::: "memory")
; #define PG8_WAIT_L(n) asm volatile("s_waitcnt lgkmcnt(" #n ")" ::: "memory")
; #define PG8_BAR __builtin_amdgcn_s_barrier()
; #define PG8_SCHED __builtin_amdgcn_sched_barrier(0)
; template <class Epi, class Sched, bool ALIGN_EPI>
; __device__ __forceinline__ void gemm_phase(LAS unsigned char* lds, const Gemm g, const Sched& S, const Epi& E, int wave_id) {
;     ...
;             PG8_LDA(At, 1, 1); PG8_STAGE(PG8_SB(1, 0), b3, voffB); PG8_STAGE(PG8_SB(1, 1), b3 + hsB, voffB); PG8_STAGE(PG8_SA(1, 0), a3, voffA);
;             PG8_WAIT_V(8); PG8_WAIT_L(0); PG8_BAR; PG8_MMA(1, 0, At, B0); PG8_MMA(1, 1, At, B1); PG8_BAR; PG8_SCHED;
;         }
;         if constexpr (ALIGN_EPI) { if (wr == 0) PG8_BAR; }
	s_mov_b32 m0, s50
	v_lshl_add_u64 v[206:207], v[206:207], 0, s[92:93]
	s_add_u32 s28, s28, 0x40080
	global_load_lds_dwordx4 v[206:207], off
	v_lshl_add_u64 v[206:207], v[208:209], 0, s[92:93]
	s_mov_b32 m0, s51
	s_addc_u32 s29, s29, 0
	global_load_lds_dwordx4 v[206:207], off
	v_lshl_add_u64 v[206:207], s[28:29], 0, v[0:1]
	s_mov_b32 m0, s54
	s_nop 0
	global_load_lds_dwordx4 v[206:207], off
	v_lshl_add_u64 v[206:207], s[28:29], 0, v[130:131]
	s_mov_b32 m0, s55
	s_nop 0
	global_load_lds_dwordx4 v[206:207], off
	v_lshl_add_u64 v[206:207], v[210:211], 0, s[92:93]
	s_mov_b32 m0, s52
	s_nop 0
	global_load_lds_dwordx4 v[206:207], off
	v_lshl_add_u64 v[206:207], v[212:213], 0, s[92:93]
	s_mov_b32 m0, s53
	s_nop 0
	global_load_lds_dwordx4 v[206:207], off
	ds_read_b128 v[174:177], v152 offset:50176
	ds_read_b128 v[178:181], v152 offset:51200
	ds_read_b128 v[182:185], v152 offset:52224
	ds_read_b128 v[186:189], v152 offset:53248
	ds_read_b128 v[190:193], v152 offset:54272
	ds_read_b128 v[194:197], v152 offset:55296
	ds_read_b128 v[198:201], v152 offset:56320
	ds_read_b128 v[202:205], v152 offset:57344
	s_waitcnt vmcnt(8)
	s_waitcnt lgkmcnt(0)
	s_setprio 1
	s_barrier
	v_mfma_f32_16x16x32_bf16 v[62:65], v[140:143], v[174:177], v[62:65]
	v_mfma_f32_16x16x32_bf16 v[58:61], v[148:151], v[174:177], v[58:61]
	v_mfma_f32_16x16x32_bf16 v[46:49], v[140:143], v[182:185], v[46:49]
	v_mfma_f32_16x16x32_bf16 v[42:45], v[148:151], v[182:185], v[42:45]
	v_mfma_f32_16x16x32_bf16 v[30:33], v[140:143], v[190:193], v[30:33]
	v_mfma_f32_16x16x32_bf16 v[26:29], v[148:151], v[190:193], v[26:29]
	v_mfma_f32_16x16x32_bf16 v[14:17], v[140:143], v[198:201], v[14:17]
	v_mfma_f32_16x16x32_bf16 v[10:13], v[148:151], v[198:201], v[10:13]
	s_setprio 0
	s_setprio 1
	v_mfma_f32_16x16x32_bf16 v[62:65], v[144:147], v[178:181], v[62:65]
	v_mfma_f32_16x16x32_bf16 v[58:61], v[154:157], v[178:181], v[58:61]
	v_mfma_f32_16x16x32_bf16 v[46:49], v[144:147], v[186:189], v[46:49]
	v_mfma_f32_16x16x32_bf16 v[42:45], v[154:157], v[186:189], v[42:45]
	v_mfma_f32_16x16x32_bf16 v[30:33], v[144:147], v[194:197], v[30:33]
	v_mfma_f32_16x16x32_bf16 v[26:29], v[154:157], v[194:197], v[26:29]
	v_mfma_f32_16x16x32_bf16 v[14:17], v[144:147], v[202:205], v[14:17]
	v_mfma_f32_16x16x32_bf16 v[10:13], v[154:157], v[202:205], v[10:13]
	s_setprio 0
	s_setprio 1
	v_mfma_f32_16x16x32_bf16 v[54:57], v[158:161], v[174:177], v[54:57]
	v_mfma_f32_16x16x32_bf16 v[50:53], v[166:169], v[174:177], v[50:53]
	v_mfma_f32_16x16x32_bf16 v[38:41], v[158:161], v[182:185], v[38:41]
	v_mfma_f32_16x16x32_bf16 v[34:37], v[166:169], v[182:185], v[34:37]
	v_mfma_f32_16x16x32_bf16 v[22:25], v[158:161], v[190:193], v[22:25]
	v_mfma_f32_16x16x32_bf16 v[18:21], v[166:169], v[190:193], v[18:21]
	v_mfma_f32_16x16x32_bf16 v[6:9], v[158:161], v[198:201], v[6:9]
	v_mfma_f32_16x16x32_bf16 v[2:5], v[166:169], v[198:201], v[2:5]
	s_setprio 0
	s_setprio 1
	v_mfma_f32_16x16x32_bf16 v[54:57], v[162:165], v[178:181], v[54:57]
	v_mfma_f32_16x16x32_bf16 v[50:53], v[170:173], v[178:181], v[50:53]
	v_mfma_f32_16x16x32_bf16 v[38:41], v[162:165], v[186:189], v[38:41]
	v_mfma_f32_16x16x32_bf16 v[34:37], v[170:173], v[186:189], v[34:37]
	v_mfma_f32_16x16x32_bf16 v[22:25], v[162:165], v[194:197], v[22:25]
	v_mfma_f32_16x16x32_bf16 v[18:21], v[170:173], v[194:197], v[18:21]
	v_mfma_f32_16x16x32_bf16 v[6:9], v[162:165], v[202:205], v[6:9]
	v_mfma_f32_16x16x32_bf16 v[2:5], v[170:173], v[202:205], v[2:5]
	s_setprio 0
	s_barrier
	s_add_i32 s60, s60, 2
	s_add_u32 s58, s58, 0x100
	s_addc_u32 s59, s59, 0
	s_add_u32 s26, s26, 0x100
	s_addc_u32 s27, s27, 0
	s_cmp_gt_u32 s60, 13
	s_cbranch_scc0 .LBB0_2565
	s_and_b64 vcc, exec, s[14:15]
	s_cbranch_vccz .LBB0_2568
	s_barrier

; #define GAS __attribute__((address_space(1)))
; #define PG8_STAGE(bufoff, gbase, voff) do { _Pragma("unroll") for (int _i = 0; _i < 2; ++_i) \
;         __builtin_amdgcn_global_load_lds((const GAS unsigned*)((const GAS char*)(gbase) + (voff)[_i]), (LAS unsigned*)(lds + (bufoff) + ldsw + _i * 8192), 16, 0, 0); } while (0)
; #define PG8_LDA(dst, b, h) do { _Pragma("unroll") for (int m = 0; m < 4; ++m) _Pragma("unroll") for (int k = 0; k < 2; ++k) dst[m][k] = *(const LAS bf16x8*)(lds + PG8_SA(b, h) + aoff + m * 2048 + k * 1024); } while (0)
; #define PG8_LDB(dst, b, h) do { _Pragma("unroll") for (int n = 0; n < 2; ++n) _Pragma("unroll") for (int k = 0; k < 2; ++k) dst[n][k] = *(const LAS bf16x8*)(lds + PG8_SB(b, h) + boff + n * 2048 + k * 1024); } while (0)
; #define PG8_MMA(ai, bj, At, Bt) do { __builtin_amdgcn_s_setprio(1); _Pragma("unroll") for (int m = 0; m < 4; ++m) _Pragma("unroll") for (int n = 0; n < 2; ++n) _Pragma("unroll") for (int k = 0; k < 2; ++k) \
;         acc[ai][bj][m][n] = __builtin_amdgcn_mfma_f32_16x16x32_bf16(Bt[n][k], At[m][k], acc[ai][bj][m][n], 0, 0, 0); __builtin_amdgcn_s_setprio(0); } while (0)
; #define PG8_WAIT_V(n) asm volatile("s_waitcnt vmcnt(" #n ")" ::: "memory")
; #define PG8_WAIT_L(n) asm volatile("s_waitcnt lgkmcnt(" #n ")" ::: "memory")
; #define PG8_BAR __builtin_amdgcn_s_barrier()
; template <class Epi, class Sched, bool ALIGN_EPI>
; __device__ __forceinline__ void gemm_phase(LAS unsigned char* lds, const Gemm g, const Sched& S, const Epi& E, int wave_id) {
;     ...
;             const bool last = (t == nt - 2);
;             const GAS char* a1 = cA + (size_t)(t + 1) * kstep;
;             const GAS char* a2 = last ? nA : cA + (size_t)(t + 2) * kstep; const GAS char* b2 = last ? nB : cB + (size_t)(t + 2) * kstep;
;             const GAS char* a3 = a2 + kstep; const GAS char* b3 = b2 + kstep;
;             PG8_LDB(B0, 0, 0); PG8_LDB(B1, 0, 1); PG8_SCHED; PG8_LDA(At, 0, 0); PG8_STAGE(PG8_SA(1, 1), a1 + hsA, voffA);
;             PG8_WAIT_V(8); PG8_WAIT_L(0); PG8_BAR; PG8_MMA(0, 0, At, B0); PG8_MMA(0, 1, At, B1); PG8_BAR; PG8_SCHED;
;             PG8_LDA(At, 0, 1); PG8_STAGE(PG8_SB(0, 0), b2, voffB); PG8_STAGE(PG8_SB(0, 1), b2 + hsB, voffB); PG8_STAGE(PG8_SA(0, 0), a2, voffA);
;             PG8_WAIT_V(8); PG8_WAIT_L(0); PG8_BAR; PG8_MMA(1, 0, At, B0); PG8_MMA(1, 1, At, B1); PG8_BAR; PG8_SCHED;
.LBB0_2620:
	s_add_u32 s38, s36, 0xfff80080
	s_addc_u32 s39, s37, -1
	s_cmp_eq_u32 s65, 28
	s_cselect_b32 s41, s1, s39
	s_cselect_b32 s40, s5, s38
	s_cselect_b32 s39, s7, s33
	s_cselect_b32 s38, s27, s29
	v_lshl_add_u64 v[194:195], s[36:37], 0, v[218:219]
	s_add_i32 m0, s43, 0xc400
	s_nop 0
	global_load_lds_dwordx4 v[194:195], off
	v_lshl_add_u64 v[194:195], s[36:37], 0, v[216:217]
	s_add_i32 m0, s43, 0xe400
	s_nop 0
	global_load_lds_dwordx4 v[194:195], off
	v_add_u32_e32 v46, 0x10400, v235
	v_add_u32_e32 v62, 0x14400, v235
	ds_read_b128 v[34:37], v46
	ds_read_b128 v[38:41], v46 offset:1024
	ds_read_b128 v[42:45], v46 offset:2048
	ds_read_b128 v[46:49], v46 offset:3072
	ds_read_b128 v[50:53], v62
	ds_read_b128 v[54:57], v62 offset:1024
	ds_read_b128 v[58:61], v62 offset:2048
	ds_read_b128 v[62:65], v62 offset:3072
	ds_read_b128 v[82:85], v234 offset:1024
	ds_read_b128 v[94:97], v234 offset:2048
	ds_read_b128 v[170:173], v234 offset:3072
	ds_read_b128 v[174:177], v234 offset:4096
	ds_read_b128 v[178:181], v234 offset:5120
	ds_read_b128 v[182:185], v234 offset:6144
	ds_read_b128 v[186:189], v234 offset:7168
	ds_read_b128 v[190:193], v234 offset:8192
	s_waitcnt vmcnt(8)
	s_waitcnt lgkmcnt(0)
	s_setprio 1
	s_barrier
	v_mfma_f32_16x16x32_bf16 v[166:169], v[34:37], v[82:85], v[166:169]
	v_mfma_f32_16x16x32_bf16 v[162:165], v[42:45], v[82:85], v[162:165]
	v_mfma_f32_16x16x32_bf16 v[150:153], v[34:37], v[170:173], v[150:153]
	v_mfma_f32_16x16x32_bf16 v[146:149], v[42:45], v[170:173], v[146:149]
	v_mfma_f32_16x16x32_bf16 v[134:137], v[34:37], v[178:181], v[134:137]
	v_mfma_f32_16x16x32_bf16 v[130:133], v[42:45], v[178:181], v[130:133]
	v_mfma_f32_16x16x32_bf16 v[118:121], v[34:37], v[186:189], v[118:121]
	v_mfma_f32_16x16x32_bf16 v[114:117], v[42:45], v[186:189], v[114:117]
	s_setprio 0
	s_setprio 1
	v_mfma_f32_16x16x32_bf16 v[166:169], v[38:41], v[94:97], v[166:169]
	v_mfma_f32_16x16x32_bf16 v[162:165], v[46:49], v[94:97], v[162:165]
	v_mfma_f32_16x16x32_bf16 v[150:153], v[38:41], v[174:177], v[150:153]
	v_mfma_f32_16x16x32_bf16 v[146:149], v[46:49], v[174:177], v[146:149]
	v_mfma_f32_16x16x32_bf16 v[134:137], v[38:41], v[182:185], v[134:137]
	v_mfma_f32_16x16x32_bf16 v[130:133], v[46:49], v[182:185], v[130:133]
	v_mfma_f32_16x16x32_bf16 v[118:121], v[38:41], v[190:193], v[118:121]
	v_mfma_f32_16x16x32_bf16 v[114:117], v[46:49], v[190:193], v[114:117]
	s_setprio 0
	s_setprio 1
	v_mfma_f32_16x16x32_bf16 v[158:161], v[50:53], v[82:85], v[158:161]
	v_mfma_f32_16x16x32_bf16 v[82:85], v[58:61], v[82:85], v[154:157]
	v_mfma_f32_16x16x32_bf16 v[138:141], v[58:61], v[170:173], v[138:141]
	v_mfma_f32_16x16x32_bf16 v[126:129], v[50:53], v[178:181], v[126:129]
	v_mfma_f32_16x16x32_bf16 v[122:125], v[58:61], v[178:181], v[122:125]
	v_mfma_f32_16x16x32_bf16 v[110:113], v[50:53], v[186:189], v[110:113]
	v_mfma_f32_16x16x32_bf16 v[106:109], v[58:61], v[186:189], v[106:109]
	v_mfma_f32_16x16x32_bf16 v[158:161], v[54:57], v[94:97], v[158:161]
	s_setprio 0
	s_setprio 1
	v_mfma_f32_16x16x32_bf16 v[82:85], v[62:65], v[94:97], v[82:85]
	v_mfma_f32_16x16x32_bf16 v[94:97], v[50:53], v[170:173], v[142:145]
	v_mfma_f32_16x16x32_bf16 v[138:141], v[62:65], v[174:177], v[138:141]
	v_mfma_f32_16x16x32_bf16 v[126:129], v[54:57], v[182:185], v[126:129]
	v_mfma_f32_16x16x32_bf16 v[122:125], v[62:65], v[182:185], v[122:125]
	v_mfma_f32_16x16x32_bf16 v[110:113], v[54:57], v[190:193], v[110:113]
	v_mfma_f32_16x16x32_bf16 v[106:109], v[62:65], v[190:193], v[106:109]
	v_mfma_f32_16x16x32_bf16 v[94:97], v[54:57], v[174:177], v[94:97]
	s_setprio 0
	s_barrier
	s_mov_b32 m0, s48
	v_lshl_add_u64 v[202:203], s[38:39], 0, v[0:1]
	s_add_u32 s66, s38, 0x80000
	global_load_lds_dwordx4 v[202:203], off
	v_lshl_add_u64 v[204:205], s[38:39], 0, v[210:211]
	s_mov_b32 m0, s49
	s_addc_u32 s67, s39, 0
	global_load_lds_dwordx4 v[204:205], off
	v_lshl_add_u64 v[194:195], s[66:67], 0, v[0:1]
	s_mov_b32 m0, s50
	v_lshl_add_u64 v[220:221], s[40:41], 0, v[206:207]
	global_load_lds_dwordx4 v[194:195], off
	v_lshl_add_u64 v[194:195], s[66:67], 0, v[210:211]
	s_mov_b32 m0, s51
	v_lshl_add_u64 v[224:225], s[40:41], 0, v[208:209]
	global_load_lds_dwordx4 v[194:195], off
	s_mov_b32 m0, s52
	s_nop 0
	global_load_lds_dwordx4 v[220:221], off
	s_mov_b32 m0, s53
	s_nop 0
	global_load_lds_dwordx4 v[224:225], off
	ds_read_b128 v[142:145], v234 offset:17408
	ds_read_b128 v[154:157], v234 offset:18432
	ds_read_b128 v[170:173], v234 offset:19456
	ds_read_b128 v[174:177], v234 offset:20480
	ds_read_b128 v[178:181], v234 offset:21504
	ds_read_b128 v[182:185], v234 offset:22528
	ds_read_b128 v[186:189], v234 offset:23552
	ds_read_b128 v[190:193], v234 offset:24576
	s_waitcnt vmcnt(8)
	s_waitcnt lgkmcnt(0)
	s_setprio 1
	s_barrier
; #define PG8_STAGE(bufoff, gbase, voff) do { _Pragma("unroll") for (int _i = 0; _i < 2; ++_i) \
;         __builtin_amdgcn_global_load_lds((const GAS unsigned*)((const GAS char*)(gbase) + (voff)[_i]), (LAS unsigned*)(lds + (bufoff) + ldsw + _i * 8192), 16, 0, 0); } while (0)
; #define PG8_LDA(dst, b, h) do { _Pragma("unroll") for (int m = 0; m < 4; ++m) _Pragma("unroll") for (int k = 0; k < 2; ++k) dst[m][k] = *(const LAS bf16x8*)(lds + PG8_SA(b, h) + aoff + m * 2048 + k * 1024); } while (0)
; #define PG8_LDB(dst, b, h) do { _Pragma("unroll") for (int n = 0; n < 2; ++n) _Pragma("unroll") for (int k = 0; k < 2; ++k) dst[n][k] = *(const LAS bf16x8*)(lds + PG8_SB(b, h) + boff + n * 2048 + k * 1024); } while (0)
; #define PG8_MMA(ai, bj, At, Bt) do { __builtin_amdgcn_s_setprio(1); _Pragma("unroll") for (int m = 0; m < 4; ++m) _Pragma("unroll") for (int n = 0; n < 2; ++n) _Pragma("unroll") for (int k = 0; k < 2; ++k) \
;         acc[ai][bj][m][n] = __builtin_amdgcn_mfma_f32_16x16x32_bf16(Bt[n][k], At[m][k], acc[ai][bj][m][n], 0, 0, 0); __builtin_amdgcn_s_setprio(0); } while (0)
; #define PG8_WAIT_V(n) asm volatile("s_waitcnt vmcnt(" #n ")" ::: "memory")
; #define PG8_WAIT_L(n) asm volatile("s_waitcnt lgkmcnt(" #n ")" ::: "memory")
; #define PG8_BAR __builtin_amdgcn_s_barrier()
; #define PG8_SCHED __builtin_amdgcn_sched_barrier(0)
; template <class Epi, class Sched, bool ALIGN_EPI>
; __device__ __forceinline__ void gemm_phase(LAS unsigned char* lds, const Gemm g, const Sched& S, const Epi& E, int wave_id) {
;     ...
;             PG8_WAIT_V(8); PG8_WAIT_L(0); PG8_BAR; PG8_MMA(1, 0, At, B0); PG8_MMA(1, 1, At, B1); PG8_BAR; PG8_SCHED;
;             PG8_LDB(B0, 1, 0); PG8_LDB(B1, 1, 1); PG8_SCHED; PG8_LDA(At, 1, 0); PG8_STAGE(PG8_SA(0, 1), a2 + hsA, voffA);
;             PG8_WAIT_V(8); PG8_WAIT_L(0); PG8_BAR; PG8_MMA(0, 0, At, B0); PG8_MMA(0, 1, At, B1); PG8_BAR; PG8_SCHED;
	v_mfma_f32_16x16x32_bf16 v[102:105], v[34:37], v[142:145], v[102:105]
	v_mfma_f32_16x16x32_bf16 v[98:101], v[42:45], v[142:145], v[98:101]
	v_mfma_f32_16x16x32_bf16 v[78:81], v[34:37], v[170:173], v[78:81]
	v_mfma_f32_16x16x32_bf16 v[74:77], v[42:45], v[170:173], v[74:77]
	v_mfma_f32_16x16x32_bf16 v[30:33], v[34:37], v[178:181], v[30:33]
	v_mfma_f32_16x16x32_bf16 v[26:29], v[42:45], v[178:181], v[26:29]
	v_mfma_f32_16x16x32_bf16 v[14:17], v[34:37], v[186:189], v[14:17]
	v_mfma_f32_16x16x32_bf16 v[10:13], v[42:45], v[186:189], v[10:13]
	s_setprio 0
	s_setprio 1
	v_mfma_f32_16x16x32_bf16 v[102:105], v[38:41], v[154:157], v[102:105]
	v_mfma_f32_16x16x32_bf16 v[98:101], v[46:49], v[154:157], v[98:101]
	v_mfma_f32_16x16x32_bf16 v[78:81], v[38:41], v[174:177], v[78:81]
	v_mfma_f32_16x16x32_bf16 v[74:77], v[46:49], v[174:177], v[74:77]
	v_mfma_f32_16x16x32_bf16 v[30:33], v[38:41], v[182:185], v[30:33]
	v_mfma_f32_16x16x32_bf16 v[26:29], v[46:49], v[182:185], v[26:29]
	v_mfma_f32_16x16x32_bf16 v[14:17], v[38:41], v[190:193], v[14:17]
	v_mfma_f32_16x16x32_bf16 v[10:13], v[46:49], v[190:193], v[10:13]
	s_setprio 0
	s_setprio 1
	v_mfma_f32_16x16x32_bf16 v[22:25], v[50:53], v[178:181], v[22:25]
	v_mfma_f32_16x16x32_bf16 v[18:21], v[58:61], v[178:181], v[18:21]
	v_mfma_f32_16x16x32_bf16 v[6:9], v[50:53], v[186:189], v[6:9]
	v_mfma_f32_16x16x32_bf16 v[2:5], v[58:61], v[186:189], v[2:5]
	v_mfma_f32_16x16x32_bf16 v[34:37], v[50:53], v[142:145], v[90:93]
	v_mfma_f32_16x16x32_bf16 v[38:41], v[58:61], v[142:145], v[86:89]
	v_mfma_f32_16x16x32_bf16 v[42:45], v[50:53], v[170:173], v[70:73]
	v_mfma_f32_16x16x32_bf16 v[46:49], v[58:61], v[170:173], v[66:69]
	s_setprio 0
	s_setprio 1
	v_mfma_f32_16x16x32_bf16 v[22:25], v[54:57], v[182:185], v[22:25]
	v_mfma_f32_16x16x32_bf16 v[18:21], v[62:65], v[182:185], v[18:21]
	v_mfma_f32_16x16x32_bf16 v[6:9], v[54:57], v[190:193], v[6:9]
	v_mfma_f32_16x16x32_bf16 v[2:5], v[62:65], v[190:193], v[2:5]
	v_mfma_f32_16x16x32_bf16 v[34:37], v[54:57], v[154:157], v[34:37]
	v_mfma_f32_16x16x32_bf16 v[38:41], v[62:65], v[154:157], v[38:41]
	v_mfma_f32_16x16x32_bf16 v[42:45], v[54:57], v[174:177], v[42:45]
	v_mfma_f32_16x16x32_bf16 v[46:49], v[62:65], v[174:177], v[46:49]
	s_setprio 0
	s_barrier
	s_add_u32 s40, s40, 0x80000
	s_addc_u32 s41, s41, 0
	s_mov_b32 m0, s54
	v_lshl_add_u64 v[142:143], s[40:41], 0, v[206:207]
	global_load_lds_dwordx4 v[142:143], off
	v_lshl_add_u64 v[142:143], s[40:41], 0, v[208:209]
	s_mov_b32 m0, s55
	s_nop 0
	global_load_lds_dwordx4 v[142:143], off
	v_add_u32_e32 v62, 0x18400, v235
	v_add_u32_e32 v66, 0x1c400, v235
	ds_read_b128 v[50:53], v62
	ds_read_b128 v[54:57], v62 offset:1024
	ds_read_b128 v[58:61], v62 offset:2048
	ds_read_b128 v[62:65], v62 offset:3072
	ds_read_b128 v[170:173], v66
	ds_read_b128 v[174:177], v66 offset:1024
	ds_read_b128 v[178:181], v66 offset:2048
	ds_read_b128 v[182:185], v66 offset:3072
	ds_read_b128 v[66:69], v234 offset:33792
	ds_read_b128 v[70:73], v234 offset:34816
	ds_read_b128 v[86:89], v234 offset:35840
	ds_read_b128 v[90:93], v234 offset:36864
	ds_read_b128 v[186:189], v234 offset:37888
	ds_read_b128 v[190:193], v234 offset:38912
	ds_read_b128 v[194:197], v234 offset:39936
	ds_read_b128 v[198:201], v234 offset:40960
	s_waitcnt vmcnt(8)
	s_waitcnt lgkmcnt(0)
	s_setprio 1
	s_barrier
	v_mfma_f32_16x16x32_bf16 v[142:145], v[50:53], v[66:69], v[166:169]
	v_mfma_f32_16x16x32_bf16 v[166:169], v[54:57], v[70:73], v[142:145]
	v_mfma_f32_16x16x32_bf16 v[142:145], v[58:61], v[66:69], v[162:165]
	v_mfma_f32_16x16x32_bf16 v[162:165], v[62:65], v[70:73], v[142:145]
	v_mfma_f32_16x16x32_bf16 v[142:145], v[50:53], v[86:89], v[150:153]
	v_mfma_f32_16x16x32_bf16 v[150:153], v[54:57], v[90:93], v[142:145]
	v_mfma_f32_16x16x32_bf16 v[142:145], v[58:61], v[86:89], v[146:149]
	v_mfma_f32_16x16x32_bf16 v[134:137], v[50:53], v[186:189], v[134:137]
	s_setprio 0
	s_setprio 1
	v_mfma_f32_16x16x32_bf16 v[130:133], v[58:61], v[186:189], v[130:133]
	v_mfma_f32_16x16x32_bf16 v[118:121], v[50:53], v[194:197], v[118:121]
	v_mfma_f32_16x16x32_bf16 v[114:117], v[58:61], v[194:197], v[114:117]
	v_mfma_f32_16x16x32_bf16 v[146:149], v[62:65], v[90:93], v[142:145]
	v_mfma_f32_16x16x32_bf16 v[134:137], v[54:57], v[190:193], v[134:137]
	v_mfma_f32_16x16x32_bf16 v[130:133], v[62:65], v[190:193], v[130:133]
	v_mfma_f32_16x16x32_bf16 v[118:121], v[54:57], v[198:201], v[118:121]
	v_mfma_f32_16x16x32_bf16 v[114:117], v[62:65], v[198:201], v[114:117]
	s_setprio 0
	s_setprio 1
	v_mfma_f32_16x16x32_bf16 v[142:145], v[170:173], v[66:69], v[158:161]
	v_mfma_f32_16x16x32_bf16 v[66:69], v[178:181], v[66:69], v[82:85]
	v_mfma_f32_16x16x32_bf16 v[154:157], v[182:185], v[70:73], v[66:69]
	v_mfma_f32_16x16x32_bf16 v[66:69], v[170:173], v[86:89], v[94:97]
	v_mfma_f32_16x16x32_bf16 v[158:161], v[174:177], v[70:73], v[142:145]
	v_mfma_f32_16x16x32_bf16 v[142:145], v[174:177], v[90:93], v[66:69]
	v_mfma_f32_16x16x32_bf16 v[66:69], v[178:181], v[86:89], v[138:141]
	v_mfma_f32_16x16x32_bf16 v[138:141], v[182:185], v[90:93], v[66:69]
	s_setprio 0
	s_setprio 1
	v_mfma_f32_16x16x32_bf16 v[66:69], v[170:173], v[186:189], v[126:129]
	v_mfma_f32_16x16x32_bf16 v[126:129], v[174:177], v[190:193], v[66:69]
	v_mfma_f32_16x16x32_bf16 v[66:69], v[178:181], v[186:189], v[122:125]
	v_mfma_f32_16x16x32_bf16 v[122:125], v[182:185], v[190:193], v[66:69]
	v_mfma_f32_16x16x32_bf16 v[66:69], v[170:173], v[194:197], v[110:113]
	v_mfma_f32_16x16x32_bf16 v[110:113], v[174:177], v[198:201], v[66:69]
	v_mfma_f32_16x16x32_bf16 v[66:69], v[178:181], v[194:197], v[106:109]
	v_mfma_f32_16x16x32_bf16 v[106:109], v[182:185], v[198:201], v[66:69]
	s_setprio 0
	s_barrier
; #define PG8_STAGE(bufoff, gbase, voff) do { _Pragma("unroll") for (int _i = 0; _i < 2; ++_i) \
;         __builtin_amdgcn_global_load_lds((const GAS unsigned*)((const GAS char*)(gbase) + (voff)[_i]), (LAS unsigned*)(lds + (bufoff) + ldsw + _i * 8192), 16, 0, 0); } while (0)
; #define PG8_LDA(dst, b, h) do { _Pragma("unroll") for (int m = 0; m < 4; ++m) _Pragma("unroll") for (int k = 0; k < 2; ++k) dst[m][k] = *(const LAS bf16x8*)(lds + PG8_SA(b, h) + aoff + m * 2048 + k * 1024); } while (0)
; #define PG8_MMA(ai, bj, At, Bt) do { __builtin_amdgcn_s_setprio(1); _Pragma("unroll") for (int m = 0; m < 4; ++m) _Pragma("unroll") for (int n = 0; n < 2; ++n) _Pragma("unroll") for (int k = 0; k < 2; ++k) \
;         acc[ai][bj][m][n] = __builtin_amdgcn_mfma_f32_16x16x32_bf16(Bt[n][k], At[m][k], acc[ai][bj][m][n], 0, 0, 0); __builtin_amdgcn_s_setprio(0); } while (0)
; #define PG8_WAIT_V(n) asm volatile("s_waitcnt vmcnt(" #n ")" ::: "memory")
; #define PG8_WAIT_L(n) asm volatile("s_waitcnt lgkmcnt(" #n ")" ::: "memory")
; #define PG8_BAR __builtin_amdgcn_s_barrier()
; #define PG8_SCHED __builtin_amdgcn_sched_barrier(0)
; template <class Epi, class Sched, bool ALIGN_EPI>
; __device__ __forceinline__ void gemm_phase(LAS unsigned char* lds, const Gemm g, const Sched& S, const Epi& E, int wave_id) {
;     ...
;             PG8_LDA(At, 1, 1); PG8_STAGE(PG8_SB(1, 0), b3, voffB); PG8_STAGE(PG8_SB(1, 1), b3 + hsB, voffB); PG8_STAGE(PG8_SA(1, 0), a3, voffA);
;             PG8_WAIT_V(8); PG8_WAIT_L(0); PG8_BAR; PG8_MMA(1, 0, At, B0); PG8_MMA(1, 1, At, B1); PG8_BAR; PG8_SCHED;
;         }
;         if constexpr (ALIGN_EPI) { if (wr == 0) PG8_BAR; }
	s_mov_b32 m0, s58
	v_lshl_add_u64 v[86:87], v[202:203], 0, s[92:93]
	s_add_u32 s38, s38, 0x80080
	s_nop 1
	global_load_lds_dwordx4 v[86:87], off
	v_lshl_add_u64 v[86:87], v[204:205], 0, s[92:93]
	s_mov_b32 m0, s59
	s_addc_u32 s39, s39, 0
	global_load_lds_dwordx4 v[86:87], off
	v_lshl_add_u64 v[86:87], s[38:39], 0, v[0:1]
	s_mov_b32 m0, s62
	s_nop 0
	global_load_lds_dwordx4 v[86:87], off
	v_lshl_add_u64 v[86:87], s[38:39], 0, v[210:211]
	s_mov_b32 m0, s63
	s_nop 0
	global_load_lds_dwordx4 v[86:87], off
	v_lshl_add_u64 v[86:87], v[220:221], 0, s[92:93]
	s_mov_b32 m0, s60
	s_nop 0
	global_load_lds_dwordx4 v[86:87], off
	v_lshl_add_u64 v[86:87], v[224:225], 0, s[92:93]
	s_mov_b32 m0, s61
	s_nop 0
	global_load_lds_dwordx4 v[86:87], off
	ds_read_b128 v[66:69], v234 offset:50176
	ds_read_b128 v[70:73], v234 offset:51200
	ds_read_b128 v[82:85], v234 offset:52224
	ds_read_b128 v[94:97], v234 offset:53248
	ds_read_b128 v[186:189], v234 offset:54272
	ds_read_b128 v[190:193], v234 offset:55296
	ds_read_b128 v[194:197], v234 offset:56320
	ds_read_b128 v[198:201], v234 offset:57344
	s_waitcnt vmcnt(8)
	s_waitcnt lgkmcnt(0)
	s_setprio 1
	s_barrier
	v_mfma_f32_16x16x32_bf16 v[86:89], v[50:53], v[66:69], v[102:105]
	v_mfma_f32_16x16x32_bf16 v[102:105], v[54:57], v[70:73], v[86:89]
	v_mfma_f32_16x16x32_bf16 v[86:89], v[58:61], v[66:69], v[98:101]
	v_mfma_f32_16x16x32_bf16 v[78:81], v[50:53], v[82:85], v[78:81]
	v_mfma_f32_16x16x32_bf16 v[74:77], v[58:61], v[82:85], v[74:77]
	v_mfma_f32_16x16x32_bf16 v[30:33], v[50:53], v[186:189], v[30:33]
	v_mfma_f32_16x16x32_bf16 v[26:29], v[58:61], v[186:189], v[26:29]
	v_mfma_f32_16x16x32_bf16 v[14:17], v[50:53], v[194:197], v[14:17]
	s_setprio 0
	s_setprio 1
	v_mfma_f32_16x16x32_bf16 v[10:13], v[58:61], v[194:197], v[10:13]
	v_mfma_f32_16x16x32_bf16 v[98:101], v[62:65], v[70:73], v[86:89]
	v_mfma_f32_16x16x32_bf16 v[78:81], v[54:57], v[94:97], v[78:81]
	v_mfma_f32_16x16x32_bf16 v[74:77], v[62:65], v[94:97], v[74:77]
	v_mfma_f32_16x16x32_bf16 v[30:33], v[54:57], v[190:193], v[30:33]
	v_mfma_f32_16x16x32_bf16 v[26:29], v[62:65], v[190:193], v[26:29]
	v_mfma_f32_16x16x32_bf16 v[14:17], v[54:57], v[198:201], v[14:17]
	v_mfma_f32_16x16x32_bf16 v[10:13], v[62:65], v[198:201], v[10:13]
	s_setprio 0
	s_setprio 1
	v_mfma_f32_16x16x32_bf16 v[34:37], v[170:173], v[66:69], v[34:37]
	v_mfma_f32_16x16x32_bf16 v[90:93], v[174:177], v[70:73], v[34:37]
	v_mfma_f32_16x16x32_bf16 v[34:37], v[178:181], v[66:69], v[38:41]
	v_mfma_f32_16x16x32_bf16 v[86:89], v[182:185], v[70:73], v[34:37]
	v_mfma_f32_16x16x32_bf16 v[34:37], v[170:173], v[82:85], v[42:45]
	v_mfma_f32_16x16x32_bf16 v[70:73], v[174:177], v[94:97], v[34:37]
	v_mfma_f32_16x16x32_bf16 v[34:37], v[178:181], v[82:85], v[46:49]
	v_mfma_f32_16x16x32_bf16 v[22:25], v[170:173], v[186:189], v[22:25]
	s_setprio 0
	s_setprio 1
	v_mfma_f32_16x16x32_bf16 v[18:21], v[178:181], v[186:189], v[18:21]
	v_mfma_f32_16x16x32_bf16 v[6:9], v[170:173], v[194:197], v[6:9]
	v_mfma_f32_16x16x32_bf16 v[2:5], v[178:181], v[194:197], v[2:5]
	v_mfma_f32_16x16x32_bf16 v[66:69], v[182:185], v[94:97], v[34:37]
	v_mfma_f32_16x16x32_bf16 v[22:25], v[174:177], v[190:193], v[22:25]
	v_mfma_f32_16x16x32_bf16 v[18:21], v[182:185], v[190:193], v[18:21]
	v_mfma_f32_16x16x32_bf16 v[6:9], v[174:177], v[198:201], v[6:9]
	v_mfma_f32_16x16x32_bf16 v[2:5], v[182:185], v[198:201], v[2:5]
	s_setprio 0
	s_barrier
	s_add_i32 s65, s65, 2
	s_add_u32 s29, s29, 0x100
	s_addc_u32 s33, s33, 0
	s_add_u32 s36, s36, 0x100
	s_addc_u32 s37, s37, 0
	s_cmp_gt_u32 s65, 29
	s_cbranch_scc0 .LBB0_2620
	s_and_b64 vcc, exec, s[22:23]
	s_cbranch_vccz .LBB0_2623
	s_barrier

; #define GAS __attribute__((address_space(1)))
; #define PG8_STAGE(bufoff, gbase, voff) do { _Pragma("unroll") for (int _i = 0; _i < 2; ++_i) \
;         __builtin_amdgcn_global_load_lds((const GAS unsigned*)((const GAS char*)(gbase) + (voff)[_i]), (LAS unsigned*)(lds + (bufoff) + ldsw + _i * 8192), 16, 0, 0); } while (0)
; #define PG8_LDA(dst, b, h) do { _Pragma("unroll") for (int m = 0; m < 4; ++m) _Pragma("unroll") for (int k = 0; k < 2; ++k) dst[m][k] = *(const LAS bf16x8*)(lds + PG8_SA(b, h) + aoff + m * 2048 + k * 1024); } while (0)
; #define PG8_LDB(dst, b, h) do { _Pragma("unroll") for (int n = 0; n < 2; ++n) _Pragma("unroll") for (int k = 0; k < 2; ++k) dst[n][k] = *(const LAS bf16x8*)(lds + PG8_SB(b, h) + boff + n * 2048 + k * 1024); } while (0)
; #define PG8_MMA(ai, bj, At, Bt) do { __builtin_amdgcn_s_setprio(1); _Pragma("unroll") for (int m = 0; m < 4; ++m) _Pragma("unroll") for (int n = 0; n < 2; ++n) _Pragma("unroll") for (int k = 0; k < 2; ++k) \
;         acc[ai][bj][m][n] = __builtin_amdgcn_mfma_f32_16x16x32_bf16(Bt[n][k], At[m][k], acc[ai][bj][m][n], 0, 0, 0); __builtin_amdgcn_s_setprio(0); } while (0)
; #define PG8_WAIT_V(n) asm volatile("s_waitcnt vmcnt(" #n ")" ::: "memory")
; #define PG8_WAIT_L(n) asm volatile("s_waitcnt lgkmcnt(" #n ")" ::: "memory")
; #define PG8_BAR __builtin_amdgcn_s_barrier()
; template <class Epi, class Sched, bool ALIGN_EPI>
; __device__ __forceinline__ void gemm_phase(LAS unsigned char* lds, const Gemm g, const Sched& S, const Epi& E, int wave_id) {
;     ...
;             const bool last = (t == nt - 2);
;             const GAS char* a1 = cA + (size_t)(t + 1) * kstep;
;             const GAS char* a2 = last ? nA : cA + (size_t)(t + 2) * kstep; const GAS char* b2 = last ? nB : cB + (size_t)(t + 2) * kstep;
;             const GAS char* a3 = a2 + kstep; const GAS char* b3 = b2 + kstep;
;             PG8_LDB(B0, 0, 0); PG8_LDB(B1, 0, 1); PG8_SCHED; PG8_LDA(At, 0, 0); PG8_STAGE(PG8_SA(1, 1), a1 + hsA, voffA);
;             PG8_WAIT_V(8); PG8_WAIT_L(0); PG8_BAR; PG8_MMA(0, 0, At, B0); PG8_MMA(0, 1, At, B1); PG8_BAR; PG8_SCHED;
;             PG8_LDA(At, 0, 1); PG8_STAGE(PG8_SB(0, 0), b2, voffB); PG8_STAGE(PG8_SB(0, 1), b2 + hsB, voffB); PG8_STAGE(PG8_SA(0, 0), a2, voffA);
;             PG8_WAIT_V(8); PG8_WAIT_L(0); PG8_BAR; PG8_MMA(1, 0, At, B0); PG8_MMA(1, 1, At, B1); PG8_BAR; PG8_SCHED;
.LBB0_2874:
	s_add_u32 s28, s2, 0xfff80080
	s_addc_u32 s29, s3, -1
	s_cmp_eq_u32 s67, 28
	s_cselect_b32 s31, s23, s29
	s_cselect_b32 s30, s22, s28
	s_cselect_b32 s29, s21, s66
	s_cselect_b32 s28, s27, s33
	v_lshl_add_u64 v[208:209], s[2:3], 0, v[232:233]
	s_add_i32 m0, s40, 0xc400
	s_nop 0
	global_load_lds_dwordx4 v[208:209], off
	v_lshl_add_u64 v[208:209], s[2:3], 0, v[230:231]
	s_add_i32 m0, s40, 0xe400
	s_nop 0
	global_load_lds_dwordx4 v[208:209], off
	v_add_u32_e32 v82, 0x10400, v240
	ds_read_b128 v[18:21], v82
	ds_read_b128 v[88:91], v82 offset:1024
	ds_read_b128 v[108:111], v82 offset:2048
	ds_read_b128 v[112:115], v82 offset:3072
	v_add_u32_e32 v82, 0x14400, v240
	ds_read_b128 v[116:119], v82
	ds_read_b128 v[120:123], v82 offset:1024
	ds_read_b128 v[128:131], v82 offset:2048
	ds_read_b128 v[132:135], v82 offset:3072
	ds_read_b128 v[136:139], v239 offset:1024
	ds_read_b128 v[140:143], v239 offset:2048
	ds_read_b128 v[144:147], v239 offset:3072
	ds_read_b128 v[164:167], v239 offset:4096
	ds_read_b128 v[180:183], v239 offset:5120
	ds_read_b128 v[184:187], v239 offset:6144
	ds_read_b128 v[188:191], v239 offset:7168
	ds_read_b128 v[192:195], v239 offset:8192
	s_waitcnt vmcnt(8)
	s_waitcnt lgkmcnt(0)
	s_setprio 1
	s_barrier
	v_mfma_f32_16x16x32_bf16 v[176:179], v[18:21], v[136:139], v[176:179]
	v_mfma_f32_16x16x32_bf16 v[30:33], v[108:111], v[136:139], v[30:33]
	v_mfma_f32_16x16x32_bf16 v[172:175], v[18:21], v[144:147], v[172:175]
	v_mfma_f32_16x16x32_bf16 v[50:53], v[108:111], v[144:147], v[50:53]
	v_mfma_f32_16x16x32_bf16 v[156:159], v[18:21], v[180:183], v[156:159]
	v_mfma_f32_16x16x32_bf16 v[78:81], v[108:111], v[180:183], v[78:81]
	v_mfma_f32_16x16x32_bf16 v[124:127], v[18:21], v[188:191], v[124:127]
	v_mfma_f32_16x16x32_bf16 v[104:107], v[108:111], v[188:191], v[104:107]
	s_setprio 0
	s_setprio 1
	v_mfma_f32_16x16x32_bf16 v[176:179], v[88:91], v[140:143], v[176:179]
	v_mfma_f32_16x16x32_bf16 v[30:33], v[112:115], v[140:143], v[30:33]
	v_mfma_f32_16x16x32_bf16 v[172:175], v[88:91], v[164:167], v[172:175]
	v_mfma_f32_16x16x32_bf16 v[50:53], v[112:115], v[164:167], v[50:53]
	v_mfma_f32_16x16x32_bf16 v[156:159], v[88:91], v[184:187], v[156:159]
	v_mfma_f32_16x16x32_bf16 v[78:81], v[112:115], v[184:187], v[78:81]
	v_mfma_f32_16x16x32_bf16 v[124:127], v[88:91], v[192:195], v[124:127]
	v_mfma_f32_16x16x32_bf16 v[104:107], v[112:115], v[192:195], v[104:107]
	s_setprio 0
	s_setprio 1
	v_mfma_f32_16x16x32_bf16 v[160:163], v[116:119], v[136:139], v[160:163]
	v_mfma_f32_16x16x32_bf16 v[62:65], v[128:131], v[136:139], v[62:65]
	v_mfma_f32_16x16x32_bf16 v[92:95], v[128:131], v[144:147], v[92:95]
	v_mfma_f32_16x16x32_bf16 v[100:103], v[116:119], v[188:191], v[100:103]
	v_mfma_f32_16x16x32_bf16 v[96:99], v[128:131], v[188:191], v[96:99]
	v_mfma_f32_16x16x32_bf16 v[160:163], v[120:123], v[140:143], v[160:163]
	v_mfma_f32_16x16x32_bf16 v[62:65], v[132:135], v[140:143], v[62:65]
	v_mfma_f32_16x16x32_bf16 v[136:139], v[116:119], v[144:147], v[168:171]
	s_setprio 0
	s_setprio 1
	v_mfma_f32_16x16x32_bf16 v[92:95], v[132:135], v[164:167], v[92:95]
	v_mfma_f32_16x16x32_bf16 v[140:143], v[116:119], v[180:183], v[152:155]
	v_mfma_f32_16x16x32_bf16 v[144:147], v[128:131], v[180:183], v[148:151]
	v_mfma_f32_16x16x32_bf16 v[100:103], v[120:123], v[192:195], v[100:103]
	v_mfma_f32_16x16x32_bf16 v[96:99], v[132:135], v[192:195], v[96:99]
	v_mfma_f32_16x16x32_bf16 v[136:139], v[120:123], v[164:167], v[136:139]
	v_mfma_f32_16x16x32_bf16 v[140:143], v[120:123], v[184:187], v[140:143]
	v_mfma_f32_16x16x32_bf16 v[144:147], v[132:135], v[184:187], v[144:147]
	s_setprio 0
	s_barrier
	s_mov_b32 m0, s41
	v_lshl_add_u64 v[200:201], s[28:29], 0, v[0:1]
	s_add_u32 s68, s28, 0x80000
	global_load_lds_dwordx4 v[200:201], off
	v_lshl_add_u64 v[202:203], s[28:29], 0, v[228:229]
	s_mov_b32 m0, s42
	s_addc_u32 s69, s29, 0
	global_load_lds_dwordx4 v[202:203], off
	v_lshl_add_u64 v[82:83], s[68:69], 0, v[0:1]
	s_mov_b32 m0, s43
	v_lshl_add_u64 v[204:205], s[30:31], 0, v[224:225]
	global_load_lds_dwordx4 v[82:83], off
	v_lshl_add_u64 v[82:83], s[68:69], 0, v[228:229]
	s_mov_b32 m0, s44
	v_lshl_add_u64 v[206:207], s[30:31], 0, v[226:227]
	global_load_lds_dwordx4 v[82:83], off
	s_mov_b32 m0, s45
	s_nop 0
	global_load_lds_dwordx4 v[204:205], off
	s_mov_b32 m0, s46
	s_nop 0
	global_load_lds_dwordx4 v[206:207], off
	ds_read_b128 v[148:151], v239 offset:17408
	ds_read_b128 v[152:155], v239 offset:18432
	ds_read_b128 v[164:167], v239 offset:19456
	ds_read_b128 v[168:171], v239 offset:20480
	ds_read_b128 v[180:183], v239 offset:21504
	ds_read_b128 v[184:187], v239 offset:22528
	ds_read_b128 v[188:191], v239 offset:23552
	ds_read_b128 v[192:195], v239 offset:24576
	s_waitcnt vmcnt(8)
	s_waitcnt lgkmcnt(0)
	s_setprio 1
	s_barrier
; #define PG8_STAGE(bufoff, gbase, voff) do { _Pragma("unroll") for (int _i = 0; _i < 2; ++_i) \
;         __builtin_amdgcn_global_load_lds((const GAS unsigned*)((const GAS char*)(gbase) + (voff)[_i]), (LAS unsigned*)(lds + (bufoff) + ldsw + _i * 8192), 16, 0, 0); } while (0)
; #define PG8_LDA(dst, b, h) do { _Pragma("unroll") for (int m = 0; m < 4; ++m) _Pragma("unroll") for (int k = 0; k < 2; ++k) dst[m][k] = *(const LAS bf16x8*)(lds + PG8_SA(b, h) + aoff + m * 2048 + k * 1024); } while (0)
; #define PG8_LDB(dst, b, h) do { _Pragma("unroll") for (int n = 0; n < 2; ++n) _Pragma("unroll") for (int k = 0; k < 2; ++k) dst[n][k] = *(const LAS bf16x8*)(lds + PG8_SB(b, h) + boff + n * 2048 + k * 1024); } while (0)
; #define PG8_MMA(ai, bj, At, Bt) do { __builtin_amdgcn_s_setprio(1); _Pragma("unroll") for (int m = 0; m < 4; ++m) _Pragma("unroll") for (int n = 0; n < 2; ++n) _Pragma("unroll") for (int k = 0; k < 2; ++k) \
;         acc[ai][bj][m][n] = __builtin_amdgcn_mfma_f32_16x16x32_bf16(Bt[n][k], At[m][k], acc[ai][bj][m][n], 0, 0, 0); __builtin_amdgcn_s_setprio(0); } while (0)
; #define PG8_WAIT_V(n) asm volatile("s_waitcnt vmcnt(" #n ")" ::: "memory")
; #define PG8_WAIT_L(n) asm volatile("s_waitcnt lgkmcnt(" #n ")" ::: "memory")
; #define PG8_BAR __builtin_amdgcn_s_barrier()
; #define PG8_SCHED __builtin_amdgcn_sched_barrier(0)
; template <class Epi, class Sched, bool ALIGN_EPI>
; __device__ __forceinline__ void gemm_phase(LAS unsigned char* lds, const Gemm g, const Sched& S, const Epi& E, int wave_id) {
;     ...
;             PG8_WAIT_V(8); PG8_WAIT_L(0); PG8_BAR; PG8_MMA(1, 0, At, B0); PG8_MMA(1, 1, At, B1); PG8_BAR; PG8_SCHED;
;             PG8_LDB(B0, 1, 0); PG8_LDB(B1, 1, 1); PG8_SCHED; PG8_LDA(At, 1, 0); PG8_STAGE(PG8_SA(0, 1), a2 + hsA, voffA);
;             PG8_WAIT_V(8); PG8_WAIT_L(0); PG8_BAR; PG8_MMA(0, 0, At, B0); PG8_MMA(0, 1, At, B1); PG8_BAR; PG8_SCHED;
	v_mfma_f32_16x16x32_bf16 v[82:85], v[18:21], v[148:151], v[84:87]
	v_mfma_f32_16x16x32_bf16 v[70:73], v[108:111], v[148:151], v[70:73]
	v_mfma_f32_16x16x32_bf16 v[58:61], v[18:21], v[164:167], v[58:61]
	v_mfma_f32_16x16x32_bf16 v[54:57], v[108:111], v[164:167], v[54:57]
	v_mfma_f32_16x16x32_bf16 v[38:41], v[18:21], v[180:183], v[38:41]
	v_mfma_f32_16x16x32_bf16 v[34:37], v[108:111], v[180:183], v[34:37]
	v_mfma_f32_16x16x32_bf16 v[14:17], v[18:21], v[188:191], v[14:17]
	v_mfma_f32_16x16x32_bf16 v[10:13], v[108:111], v[188:191], v[10:13]
	s_setprio 0
	s_setprio 1
	v_mfma_f32_16x16x32_bf16 v[82:85], v[88:91], v[152:155], v[82:85]
	v_mfma_f32_16x16x32_bf16 v[70:73], v[112:115], v[152:155], v[70:73]
	v_mfma_f32_16x16x32_bf16 v[58:61], v[88:91], v[168:171], v[58:61]
	v_mfma_f32_16x16x32_bf16 v[54:57], v[112:115], v[168:171], v[54:57]
	v_mfma_f32_16x16x32_bf16 v[38:41], v[88:91], v[184:187], v[38:41]
	v_mfma_f32_16x16x32_bf16 v[34:37], v[112:115], v[184:187], v[34:37]
	v_mfma_f32_16x16x32_bf16 v[14:17], v[88:91], v[192:195], v[14:17]
	v_mfma_f32_16x16x32_bf16 v[10:13], v[112:115], v[192:195], v[10:13]
	s_setprio 0
	s_setprio 1
	v_mfma_f32_16x16x32_bf16 v[66:69], v[128:131], v[148:151], v[66:69]
	v_mfma_f32_16x16x32_bf16 v[46:49], v[116:119], v[164:167], v[46:49]
	v_mfma_f32_16x16x32_bf16 v[42:45], v[128:131], v[164:167], v[42:45]
	v_mfma_f32_16x16x32_bf16 v[26:29], v[116:119], v[180:183], v[26:29]
	v_mfma_f32_16x16x32_bf16 v[22:25], v[128:131], v[180:183], v[22:25]
	v_mfma_f32_16x16x32_bf16 v[6:9], v[116:119], v[188:191], v[6:9]
	v_mfma_f32_16x16x32_bf16 v[2:5], v[128:131], v[188:191], v[2:5]
	v_mfma_f32_16x16x32_bf16 v[18:21], v[116:119], v[148:151], v[74:77]
	s_setprio 0
	s_setprio 1
	v_mfma_f32_16x16x32_bf16 v[66:69], v[132:135], v[152:155], v[66:69]
	v_mfma_f32_16x16x32_bf16 v[46:49], v[120:123], v[168:171], v[46:49]
	v_mfma_f32_16x16x32_bf16 v[42:45], v[132:135], v[168:171], v[42:45]
	v_mfma_f32_16x16x32_bf16 v[26:29], v[120:123], v[184:187], v[26:29]
	v_mfma_f32_16x16x32_bf16 v[22:25], v[132:135], v[184:187], v[22:25]
	v_mfma_f32_16x16x32_bf16 v[6:9], v[120:123], v[192:195], v[6:9]
	v_mfma_f32_16x16x32_bf16 v[2:5], v[132:135], v[192:195], v[2:5]
	v_mfma_f32_16x16x32_bf16 v[18:21], v[120:123], v[152:155], v[18:21]
	s_setprio 0
	s_barrier
	s_add_u32 s30, s30, 0x80000
	s_addc_u32 s31, s31, 0
	s_mov_b32 m0, s47
	v_lshl_add_u64 v[210:211], s[30:31], 0, v[224:225]
	global_load_lds_dwordx4 v[210:211], off
	v_lshl_add_u64 v[210:211], s[30:31], 0, v[226:227]
	s_mov_b32 m0, s48
	s_nop 0
	global_load_lds_dwordx4 v[210:211], off
	v_add_u32_e32 v86, 0x18400, v240
	ds_read_b128 v[74:77], v86
	ds_read_b128 v[88:91], v86 offset:1024
	ds_read_b128 v[108:111], v86 offset:2048
	ds_read_b128 v[112:115], v86 offset:3072
	v_add_u32_e32 v86, 0x1c400, v240
	ds_read_b128 v[116:119], v86
	ds_read_b128 v[120:123], v86 offset:1024
	ds_read_b128 v[128:131], v86 offset:2048
	ds_read_b128 v[132:135], v86 offset:3072
	ds_read_b128 v[148:151], v239 offset:33792
	ds_read_b128 v[152:155], v239 offset:34816
	ds_read_b128 v[164:167], v239 offset:35840
	ds_read_b128 v[180:183], v239 offset:36864
	ds_read_b128 v[184:187], v239 offset:37888
	ds_read_b128 v[188:191], v239 offset:38912
	ds_read_b128 v[192:195], v239 offset:39936
	ds_read_b128 v[196:199], v239 offset:40960
	s_waitcnt vmcnt(8)
	s_waitcnt lgkmcnt(0)
	s_setprio 1
	s_barrier
	v_mfma_f32_16x16x32_bf16 v[168:171], v[74:77], v[148:151], v[176:179]
	v_mfma_f32_16x16x32_bf16 v[176:179], v[88:91], v[152:155], v[168:171]
	v_mfma_f32_16x16x32_bf16 v[30:33], v[108:111], v[148:151], v[30:33]
	v_mfma_f32_16x16x32_bf16 v[168:171], v[74:77], v[164:167], v[172:175]
	v_mfma_f32_16x16x32_bf16 v[50:53], v[108:111], v[164:167], v[50:53]
	v_mfma_f32_16x16x32_bf16 v[156:159], v[74:77], v[184:187], v[156:159]
	v_mfma_f32_16x16x32_bf16 v[78:81], v[108:111], v[184:187], v[78:81]
	v_mfma_f32_16x16x32_bf16 v[124:127], v[74:77], v[192:195], v[124:127]
	s_setprio 0
	s_setprio 1
	v_mfma_f32_16x16x32_bf16 v[104:107], v[108:111], v[192:195], v[104:107]
	v_mfma_f32_16x16x32_bf16 v[30:33], v[112:115], v[152:155], v[30:33]
	v_mfma_f32_16x16x32_bf16 v[172:175], v[88:91], v[180:183], v[168:171]
	v_mfma_f32_16x16x32_bf16 v[50:53], v[112:115], v[180:183], v[50:53]
	v_mfma_f32_16x16x32_bf16 v[156:159], v[88:91], v[188:191], v[156:159]
	v_mfma_f32_16x16x32_bf16 v[78:81], v[112:115], v[188:191], v[78:81]
	v_mfma_f32_16x16x32_bf16 v[124:127], v[88:91], v[196:199], v[124:127]
	v_mfma_f32_16x16x32_bf16 v[104:107], v[112:115], v[196:199], v[104:107]
	s_setprio 0
	s_setprio 1
	v_mfma_f32_16x16x32_bf16 v[136:139], v[116:119], v[164:167], v[136:139]
	v_mfma_f32_16x16x32_bf16 v[160:163], v[116:119], v[148:151], v[160:163]
	v_mfma_f32_16x16x32_bf16 v[62:65], v[128:131], v[148:151], v[62:65]
	v_mfma_f32_16x16x32_bf16 v[168:171], v[120:123], v[180:183], v[136:139]
	v_mfma_f32_16x16x32_bf16 v[136:139], v[116:119], v[184:187], v[140:143]
	v_mfma_f32_16x16x32_bf16 v[160:163], v[120:123], v[152:155], v[160:163]
	v_mfma_f32_16x16x32_bf16 v[62:65], v[132:135], v[152:155], v[62:65]
	v_mfma_f32_16x16x32_bf16 v[92:95], v[128:131], v[164:167], v[92:95]
	s_setprio 0
	s_setprio 1
	v_mfma_f32_16x16x32_bf16 v[152:155], v[120:123], v[188:191], v[136:139]
	v_mfma_f32_16x16x32_bf16 v[136:139], v[128:131], v[184:187], v[144:147]
	v_mfma_f32_16x16x32_bf16 v[100:103], v[116:119], v[192:195], v[100:103]
	v_mfma_f32_16x16x32_bf16 v[96:99], v[128:131], v[192:195], v[96:99]
	v_mfma_f32_16x16x32_bf16 v[92:95], v[132:135], v[180:183], v[92:95]
	v_mfma_f32_16x16x32_bf16 v[148:151], v[132:135], v[188:191], v[136:139]
	v_mfma_f32_16x16x32_bf16 v[100:103], v[120:123], v[196:199], v[100:103]
	v_mfma_f32_16x16x32_bf16 v[96:99], v[132:135], v[196:199], v[96:99]
	s_setprio 0
	s_barrier
; #define PG8_STAGE(bufoff, gbase, voff) do { _Pragma("unroll") for (int _i = 0; _i < 2; ++_i) \
;         __builtin_amdgcn_global_load_lds((const GAS unsigned*)((const GAS char*)(gbase) + (voff)[_i]), (LAS unsigned*)(lds + (bufoff) + ldsw + _i * 8192), 16, 0, 0); } while (0)
; #define PG8_LDA(dst, b, h) do { _Pragma("unroll") for (int m = 0; m < 4; ++m) _Pragma("unroll") for (int k = 0; k < 2; ++k) dst[m][k] = *(const LAS bf16x8*)(lds + PG8_SA(b, h) + aoff + m * 2048 + k * 1024); } while (0)
; #define PG8_MMA(ai, bj, At, Bt) do { __builtin_amdgcn_s_setprio(1); _Pragma("unroll") for (int m = 0; m < 4; ++m) _Pragma("unroll") for (int n = 0; n < 2; ++n) _Pragma("unroll") for (int k = 0; k < 2; ++k) \
;         acc[ai][bj][m][n] = __builtin_amdgcn_mfma_f32_16x16x32_bf16(Bt[n][k], At[m][k], acc[ai][bj][m][n], 0, 0, 0); __builtin_amdgcn_s_setprio(0); } while (0)
; #define PG8_WAIT_V(n) asm volatile("s_waitcnt vmcnt(" #n ")" ::: "memory")
; #define PG8_WAIT_L(n) asm volatile("s_waitcnt lgkmcnt(" #n ")" ::: "memory")
; #define PG8_BAR __builtin_amdgcn_s_barrier()
; #define PG8_SCHED __builtin_amdgcn_sched_barrier(0)
; template <class Epi, class Sched, bool ALIGN_EPI>
; __device__ __forceinline__ void gemm_phase(LAS unsigned char* lds, const Gemm g, const Sched& S, const Epi& E, int wave_id) {
;     ...
;             PG8_LDA(At, 1, 1); PG8_STAGE(PG8_SB(1, 0), b3, voffB); PG8_STAGE(PG8_SB(1, 1), b3 + hsB, voffB); PG8_STAGE(PG8_SA(1, 0), a3, voffA);
;             PG8_WAIT_V(8); PG8_WAIT_L(0); PG8_BAR; PG8_MMA(1, 0, At, B0); PG8_MMA(1, 1, At, B1); PG8_BAR; PG8_SCHED;
;         }
;         if constexpr (ALIGN_EPI) { if (wr == 0) PG8_BAR; }
	s_mov_b32 m0, s52
	v_lshl_add_u64 v[86:87], v[200:201], 0, s[92:93]
	s_add_u32 s28, s28, 0x80080
	global_load_lds_dwordx4 v[86:87], off
	v_lshl_add_u64 v[86:87], v[202:203], 0, s[92:93]
	s_mov_b32 m0, s53
	s_addc_u32 s29, s29, 0
	global_load_lds_dwordx4 v[86:87], off
	v_lshl_add_u64 v[86:87], s[28:29], 0, v[0:1]
	s_mov_b32 m0, s56
	s_nop 0
	global_load_lds_dwordx4 v[86:87], off
	v_lshl_add_u64 v[86:87], s[28:29], 0, v[228:229]
	s_mov_b32 m0, s57
	s_nop 0
	global_load_lds_dwordx4 v[86:87], off
	v_lshl_add_u64 v[86:87], v[204:205], 0, s[92:93]
	s_mov_b32 m0, s54
	s_nop 0
	global_load_lds_dwordx4 v[86:87], off
	v_lshl_add_u64 v[86:87], v[206:207], 0, s[92:93]
	s_mov_b32 m0, s55
	s_nop 0
	global_load_lds_dwordx4 v[86:87], off
	ds_read_b128 v[136:139], v239 offset:50176
	ds_read_b128 v[140:143], v239 offset:51200
	ds_read_b128 v[144:147], v239 offset:52224
	ds_read_b128 v[164:167], v239 offset:53248
	ds_read_b128 v[180:183], v239 offset:54272
	ds_read_b128 v[184:187], v239 offset:55296
	ds_read_b128 v[188:191], v239 offset:56320
	ds_read_b128 v[192:195], v239 offset:57344
	s_waitcnt vmcnt(8)
	s_waitcnt lgkmcnt(0)
	s_setprio 1
	s_barrier
	v_mfma_f32_16x16x32_bf16 v[82:85], v[74:77], v[136:139], v[82:85]
	v_mfma_f32_16x16x32_bf16 v[70:73], v[108:111], v[136:139], v[70:73]
	v_mfma_f32_16x16x32_bf16 v[58:61], v[74:77], v[144:147], v[58:61]
	v_mfma_f32_16x16x32_bf16 v[54:57], v[108:111], v[144:147], v[54:57]
	v_mfma_f32_16x16x32_bf16 v[38:41], v[74:77], v[180:183], v[38:41]
	v_mfma_f32_16x16x32_bf16 v[34:37], v[108:111], v[180:183], v[34:37]
	v_mfma_f32_16x16x32_bf16 v[14:17], v[74:77], v[188:191], v[14:17]
	v_mfma_f32_16x16x32_bf16 v[10:13], v[108:111], v[188:191], v[10:13]
	s_setprio 0
	s_setprio 1
	v_mfma_f32_16x16x32_bf16 v[84:87], v[88:91], v[140:143], v[82:85]
	v_mfma_f32_16x16x32_bf16 v[70:73], v[112:115], v[140:143], v[70:73]
	v_mfma_f32_16x16x32_bf16 v[58:61], v[88:91], v[164:167], v[58:61]
	v_mfma_f32_16x16x32_bf16 v[54:57], v[112:115], v[164:167], v[54:57]
	v_mfma_f32_16x16x32_bf16 v[38:41], v[88:91], v[184:187], v[38:41]
	v_mfma_f32_16x16x32_bf16 v[34:37], v[112:115], v[184:187], v[34:37]
	v_mfma_f32_16x16x32_bf16 v[14:17], v[88:91], v[192:195], v[14:17]
	v_mfma_f32_16x16x32_bf16 v[10:13], v[112:115], v[192:195], v[10:13]
	s_setprio 0
	s_setprio 1
	v_mfma_f32_16x16x32_bf16 v[18:21], v[116:119], v[136:139], v[18:21]
	v_mfma_f32_16x16x32_bf16 v[74:77], v[120:123], v[140:143], v[18:21]
	v_mfma_f32_16x16x32_bf16 v[18:21], v[128:131], v[136:139], v[66:69]
	v_mfma_f32_16x16x32_bf16 v[66:69], v[132:135], v[140:143], v[18:21]
	v_mfma_f32_16x16x32_bf16 v[18:21], v[116:119], v[144:147], v[46:49]
	v_mfma_f32_16x16x32_bf16 v[46:49], v[120:123], v[164:167], v[18:21]
	v_mfma_f32_16x16x32_bf16 v[18:21], v[128:131], v[144:147], v[42:45]
	v_mfma_f32_16x16x32_bf16 v[42:45], v[132:135], v[164:167], v[18:21]
	s_setprio 0
	s_setprio 1
	v_mfma_f32_16x16x32_bf16 v[18:21], v[116:119], v[180:183], v[26:29]
	v_mfma_f32_16x16x32_bf16 v[26:29], v[120:123], v[184:187], v[18:21]
	v_mfma_f32_16x16x32_bf16 v[18:21], v[128:131], v[180:183], v[22:25]
	v_mfma_f32_16x16x32_bf16 v[6:9], v[116:119], v[188:191], v[6:9]
	v_mfma_f32_16x16x32_bf16 v[2:5], v[128:131], v[188:191], v[2:5]
	v_mfma_f32_16x16x32_bf16 v[22:25], v[132:135], v[184:187], v[18:21]
	v_mfma_f32_16x16x32_bf16 v[6:9], v[120:123], v[192:195], v[6:9]
	v_mfma_f32_16x16x32_bf16 v[2:5], v[132:135], v[192:195], v[2:5]
	s_setprio 0
	s_barrier
	s_add_i32 s67, s67, 2
	s_add_u32 s33, s33, 0x100
	s_addc_u32 s66, s66, 0
	s_add_u32 s2, s2, 0x100
	s_addc_u32 s3, s3, 0
	s_cmp_gt_u32 s67, 29
	s_cbranch_scc0 .LBB0_2874
	s_and_b64 vcc, exec, s[16:17]
	s_cbranch_vccz .LBB0_2877
	s_barrier

; #define GAS __attribute__((address_space(1)))
; #define PG8_STAGE(bufoff, gbase, voff) do { _Pragma("unroll") for (int _i = 0; _i < 2; ++_i) \
;         __builtin_amdgcn_global_load_lds((const GAS unsigned*)((const GAS char*)(gbase) + (voff)[_i]), (LAS unsigned*)(lds + (bufoff) + ldsw + _i * 8192), 16, 0, 0); } while (0)
; #define PG8_LDA(dst, b, h) do { _Pragma("unroll") for (int m = 0; m < 4; ++m) _Pragma("unroll") for (int k = 0; k < 2; ++k) dst[m][k] = *(const LAS bf16x8*)(lds + PG8_SA(b, h) + aoff + m * 2048 + k * 1024); } while (0)
; #define PG8_LDB(dst, b, h) do { _Pragma("unroll") for (int n = 0; n < 2; ++n) _Pragma("unroll") for (int k = 0; k < 2; ++k) dst[n][k] = *(const LAS bf16x8*)(lds + PG8_SB(b, h) + boff + n * 2048 + k * 1024); } while (0)
; #define PG8_MMA(ai, bj, At, Bt) do { __builtin_amdgcn_s_setprio(1); _Pragma("unroll") for (int m = 0; m < 4; ++m) _Pragma("unroll") for (int n = 0; n < 2; ++n) _Pragma("unroll") for (int k = 0; k < 2; ++k) \
;         acc[ai][bj][m][n] = __builtin_amdgcn_mfma_f32_16x16x32_bf16(Bt[n][k], At[m][k], acc[ai][bj][m][n], 0, 0, 0); __builtin_amdgcn_s_setprio(0); } while (0)
; #define PG8_WAIT_V(n) asm volatile("s_waitcnt vmcnt(" #n ")" ::: "memory")
; #define PG8_WAIT_L(n) asm volatile("s_waitcnt lgkmcnt(" #n ")" ::: "memory")
; #define PG8_BAR __builtin_amdgcn_s_barrier()
; template <class Epi, class Sched, bool ALIGN_EPI>
; __device__ __forceinline__ void gemm_phase(LAS unsigned char* lds, const Gemm g, const Sched& S, const Epi& E, int wave_id) {
;     ...
;             const bool last = (t == nt - 2);
;             const GAS char* a1 = cA + (size_t)(t + 1) * kstep;
;             const GAS char* a2 = last ? nA : cA + (size_t)(t + 2) * kstep; const GAS char* b2 = last ? nB : cB + (size_t)(t + 2) * kstep;
;             const GAS char* a3 = a2 + kstep; const GAS char* b3 = b2 + kstep;
;             PG8_LDB(B0, 0, 0); PG8_LDB(B1, 0, 1); PG8_SCHED; PG8_LDA(At, 0, 0); PG8_STAGE(PG8_SA(1, 1), a1 + hsA, voffA);
;             PG8_WAIT_V(8); PG8_WAIT_L(0); PG8_BAR; PG8_MMA(0, 0, At, B0); PG8_MMA(0, 1, At, B1); PG8_BAR; PG8_SCHED;
;             PG8_LDA(At, 0, 1); PG8_STAGE(PG8_SB(0, 0), b2, voffB); PG8_STAGE(PG8_SB(0, 1), b2 + hsB, voffB); PG8_STAGE(PG8_SA(0, 0), a2, voffA);
;             PG8_WAIT_V(8); PG8_WAIT_L(0); PG8_BAR; PG8_MMA(1, 0, At, B0); PG8_MMA(1, 1, At, B1); PG8_BAR; PG8_SCHED;
.LBB0_3681:
	s_add_u32 s0, s28, 0x100
	s_addc_u32 s1, s29, 0
	s_cmpk_eq_i32 s63, 0x54
	s_cselect_b32 s35, s25, s1
	s_cselect_b32 s34, s24, s0
	s_cselect_b32 s31, s27, s62
	s_cselect_b32 s30, s26, s61
	v_lshl_add_u64 v[204:205], s[28:29], 0, v[190:191]
	s_add_i32 m0, s41, 0xc400
	s_nop 0
	global_load_lds_dwordx4 v[204:205], off
	v_lshl_add_u64 v[204:205], s[28:29], 0, v[188:189]
	s_add_i32 m0, s41, 0xe400
	s_nop 0
	global_load_lds_dwordx4 v[204:205], off
	v_add_u32_e32 v46, 0x10400, v208
	v_add_u32_e32 v62, 0x14400, v208
	ds_read_b128 v[34:37], v46
	ds_read_b128 v[38:41], v46 offset:1024
	ds_read_b128 v[42:45], v46 offset:2048
	ds_read_b128 v[46:49], v46 offset:3072
	ds_read_b128 v[50:53], v62
	ds_read_b128 v[54:57], v62 offset:1024
	ds_read_b128 v[58:61], v62 offset:2048
	ds_read_b128 v[62:65], v62 offset:3072
	ds_read_b128 v[162:165], v207 offset:1024
	ds_read_b128 v[166:169], v207 offset:2048
	ds_read_b128 v[170:173], v207 offset:3072
	ds_read_b128 v[174:177], v207 offset:4096
	ds_read_b128 v[178:181], v207 offset:5120
	ds_read_b128 v[192:195], v207 offset:6144
	ds_read_b128 v[196:199], v207 offset:7168
	ds_read_b128 v[200:203], v207 offset:8192
	s_waitcnt vmcnt(8)
	s_waitcnt lgkmcnt(0)
	s_setprio 1
	s_barrier
	v_mfma_f32_16x16x32_bf16 v[158:161], v[34:37], v[162:165], v[158:161]
	v_mfma_f32_16x16x32_bf16 v[154:157], v[42:45], v[162:165], v[154:157]
	v_mfma_f32_16x16x32_bf16 v[142:145], v[34:37], v[170:173], v[142:145]
	v_mfma_f32_16x16x32_bf16 v[138:141], v[42:45], v[170:173], v[138:141]
	v_mfma_f32_16x16x32_bf16 v[126:129], v[34:37], v[178:181], v[126:129]
	v_mfma_f32_16x16x32_bf16 v[122:125], v[42:45], v[178:181], v[122:125]
	v_mfma_f32_16x16x32_bf16 v[110:113], v[34:37], v[196:199], v[110:113]
	v_mfma_f32_16x16x32_bf16 v[106:109], v[42:45], v[196:199], v[106:109]
	s_setprio 0
	s_setprio 1
	v_mfma_f32_16x16x32_bf16 v[158:161], v[38:41], v[166:169], v[158:161]
	v_mfma_f32_16x16x32_bf16 v[154:157], v[46:49], v[166:169], v[154:157]
	v_mfma_f32_16x16x32_bf16 v[142:145], v[38:41], v[174:177], v[142:145]
	v_mfma_f32_16x16x32_bf16 v[138:141], v[46:49], v[174:177], v[138:141]
	v_mfma_f32_16x16x32_bf16 v[126:129], v[38:41], v[192:195], v[126:129]
	v_mfma_f32_16x16x32_bf16 v[122:125], v[46:49], v[192:195], v[122:125]
	v_mfma_f32_16x16x32_bf16 v[110:113], v[38:41], v[200:203], v[110:113]
	v_mfma_f32_16x16x32_bf16 v[106:109], v[46:49], v[200:203], v[106:109]
	s_setprio 0
	s_setprio 1
	v_mfma_f32_16x16x32_bf16 v[150:153], v[50:53], v[162:165], v[150:153]
	v_mfma_f32_16x16x32_bf16 v[146:149], v[58:61], v[162:165], v[146:149]
	v_mfma_f32_16x16x32_bf16 v[134:137], v[50:53], v[170:173], v[134:137]
	v_mfma_f32_16x16x32_bf16 v[130:133], v[58:61], v[170:173], v[130:133]
	v_mfma_f32_16x16x32_bf16 v[118:121], v[50:53], v[178:181], v[118:121]
	v_mfma_f32_16x16x32_bf16 v[114:117], v[58:61], v[178:181], v[114:117]
	v_mfma_f32_16x16x32_bf16 v[102:105], v[50:53], v[196:199], v[102:105]
	v_mfma_f32_16x16x32_bf16 v[98:101], v[58:61], v[196:199], v[98:101]
	s_setprio 0
	s_setprio 1
	v_mfma_f32_16x16x32_bf16 v[150:153], v[54:57], v[166:169], v[150:153]
	v_mfma_f32_16x16x32_bf16 v[146:149], v[62:65], v[166:169], v[146:149]
	v_mfma_f32_16x16x32_bf16 v[134:137], v[54:57], v[174:177], v[134:137]
	v_mfma_f32_16x16x32_bf16 v[130:133], v[62:65], v[174:177], v[130:133]
	v_mfma_f32_16x16x32_bf16 v[118:121], v[54:57], v[192:195], v[118:121]
	v_mfma_f32_16x16x32_bf16 v[114:117], v[62:65], v[192:195], v[114:117]
	v_mfma_f32_16x16x32_bf16 v[102:105], v[54:57], v[200:203], v[102:105]
	v_mfma_f32_16x16x32_bf16 v[98:101], v[62:65], v[200:203], v[98:101]
	s_setprio 0
	s_barrier
	s_mov_b32 m0, s42
	v_lshl_add_u64 v[204:205], s[30:31], 0, v[0:1]
	s_add_u32 s28, s30, 0x160000
	global_load_lds_dwordx4 v[204:205], off
	v_lshl_add_u64 v[218:219], s[30:31], 0, v[186:187]
	s_mov_b32 m0, s43
	s_addc_u32 s29, s31, 0
	global_load_lds_dwordx4 v[218:219], off
	v_lshl_add_u64 v[210:211], s[28:29], 0, v[0:1]
	s_mov_b32 m0, s44
	v_lshl_add_u64 v[220:221], s[34:35], 0, v[182:183]
	global_load_lds_dwordx4 v[210:211], off
	v_lshl_add_u64 v[210:211], s[28:29], 0, v[186:187]
	s_mov_b32 m0, s45
	v_lshl_add_u64 v[224:225], s[34:35], 0, v[184:185]
	global_load_lds_dwordx4 v[210:211], off
	s_mov_b32 m0, s46
	s_nop 0
	global_load_lds_dwordx4 v[220:221], off
	s_mov_b32 m0, s47
	s_nop 0
	global_load_lds_dwordx4 v[224:225], off
	ds_read_b128 v[162:165], v207 offset:17408
	ds_read_b128 v[166:169], v207 offset:18432
	ds_read_b128 v[170:173], v207 offset:19456
	ds_read_b128 v[174:177], v207 offset:20480
	ds_read_b128 v[178:181], v207 offset:21504
	ds_read_b128 v[192:195], v207 offset:22528
	ds_read_b128 v[196:199], v207 offset:23552
	ds_read_b128 v[200:203], v207 offset:24576
	s_waitcnt vmcnt(8)
	s_waitcnt lgkmcnt(0)
	s_setprio 1
	s_barrier
; #define PG8_STAGE(bufoff, gbase, voff) do { _Pragma("unroll") for (int _i = 0; _i < 2; ++_i) \
;         __builtin_amdgcn_global_load_lds((const GAS unsigned*)((const GAS char*)(gbase) + (voff)[_i]), (LAS unsigned*)(lds + (bufoff) + ldsw + _i * 8192), 16, 0, 0); } while (0)
; #define PG8_LDA(dst, b, h) do { _Pragma("unroll") for (int m = 0; m < 4; ++m) _Pragma("unroll") for (int k = 0; k < 2; ++k) dst[m][k] = *(const LAS bf16x8*)(lds + PG8_SA(b, h) + aoff + m * 2048 + k * 1024); } while (0)
; #define PG8_LDB(dst, b, h) do { _Pragma("unroll") for (int n = 0; n < 2; ++n) _Pragma("unroll") for (int k = 0; k < 2; ++k) dst[n][k] = *(const LAS bf16x8*)(lds + PG8_SB(b, h) + boff + n * 2048 + k * 1024); } while (0)
; #define PG8_MMA(ai, bj, At, Bt) do { __builtin_amdgcn_s_setprio(1); _Pragma("unroll") for (int m = 0; m < 4; ++m) _Pragma("unroll") for (int n = 0; n < 2; ++n) _Pragma("unroll") for (int k = 0; k < 2; ++k) \
;         acc[ai][bj][m][n] = __builtin_amdgcn_mfma_f32_16x16x32_bf16(Bt[n][k], At[m][k], acc[ai][bj][m][n], 0, 0, 0); __builtin_amdgcn_s_setprio(0); } while (0)
; #define PG8_WAIT_V(n) asm volatile("s_waitcnt vmcnt(" #n ")" ::: "memory")
; #define PG8_WAIT_L(n) asm volatile("s_waitcnt lgkmcnt(" #n ")" ::: "memory")
; #define PG8_BAR __builtin_amdgcn_s_barrier()
; #define PG8_SCHED __builtin_amdgcn_sched_barrier(0)
; template <class Epi, class Sched, bool ALIGN_EPI>
; __device__ __forceinline__ void gemm_phase(LAS unsigned char* lds, const Gemm g, const Sched& S, const Epi& E, int wave_id) {
;     ...
;             PG8_WAIT_V(8); PG8_WAIT_L(0); PG8_BAR; PG8_MMA(1, 0, At, B0); PG8_MMA(1, 1, At, B1); PG8_BAR; PG8_SCHED;
;             PG8_LDB(B0, 1, 0); PG8_LDB(B1, 1, 1); PG8_SCHED; PG8_LDA(At, 1, 0); PG8_STAGE(PG8_SA(0, 1), a2 + hsA, voffA);
;             PG8_WAIT_V(8); PG8_WAIT_L(0); PG8_BAR; PG8_MMA(0, 0, At, B0); PG8_MMA(0, 1, At, B1); PG8_BAR; PG8_SCHED;
	v_mfma_f32_16x16x32_bf16 v[94:97], v[34:37], v[162:165], v[94:97]
	v_mfma_f32_16x16x32_bf16 v[90:93], v[42:45], v[162:165], v[90:93]
	v_mfma_f32_16x16x32_bf16 v[78:81], v[34:37], v[170:173], v[78:81]
	v_mfma_f32_16x16x32_bf16 v[74:77], v[42:45], v[170:173], v[74:77]
	v_mfma_f32_16x16x32_bf16 v[30:33], v[34:37], v[178:181], v[30:33]
	v_mfma_f32_16x16x32_bf16 v[26:29], v[42:45], v[178:181], v[26:29]
	v_mfma_f32_16x16x32_bf16 v[14:17], v[34:37], v[196:199], v[14:17]
	v_mfma_f32_16x16x32_bf16 v[10:13], v[42:45], v[196:199], v[10:13]
	s_setprio 0
	s_setprio 1
	v_mfma_f32_16x16x32_bf16 v[94:97], v[38:41], v[166:169], v[94:97]
	v_mfma_f32_16x16x32_bf16 v[90:93], v[46:49], v[166:169], v[90:93]
	v_mfma_f32_16x16x32_bf16 v[78:81], v[38:41], v[174:177], v[78:81]
	v_mfma_f32_16x16x32_bf16 v[74:77], v[46:49], v[174:177], v[74:77]
	v_mfma_f32_16x16x32_bf16 v[30:33], v[38:41], v[192:195], v[30:33]
	v_mfma_f32_16x16x32_bf16 v[26:29], v[46:49], v[192:195], v[26:29]
	v_mfma_f32_16x16x32_bf16 v[14:17], v[38:41], v[200:203], v[14:17]
	v_mfma_f32_16x16x32_bf16 v[10:13], v[46:49], v[200:203], v[10:13]
	s_setprio 0
	s_setprio 1
	v_mfma_f32_16x16x32_bf16 v[22:25], v[50:53], v[178:181], v[22:25]
	v_mfma_f32_16x16x32_bf16 v[18:21], v[58:61], v[178:181], v[18:21]
	v_mfma_f32_16x16x32_bf16 v[6:9], v[50:53], v[196:199], v[6:9]
	v_mfma_f32_16x16x32_bf16 v[2:5], v[58:61], v[196:199], v[2:5]
	v_mfma_f32_16x16x32_bf16 v[34:37], v[50:53], v[162:165], v[86:89]
	v_mfma_f32_16x16x32_bf16 v[38:41], v[58:61], v[162:165], v[82:85]
	v_mfma_f32_16x16x32_bf16 v[42:45], v[50:53], v[170:173], v[70:73]
	v_mfma_f32_16x16x32_bf16 v[46:49], v[58:61], v[170:173], v[66:69]
	s_setprio 0
	s_setprio 1
	v_mfma_f32_16x16x32_bf16 v[22:25], v[54:57], v[192:195], v[22:25]
	v_mfma_f32_16x16x32_bf16 v[18:21], v[62:65], v[192:195], v[18:21]
	v_mfma_f32_16x16x32_bf16 v[6:9], v[54:57], v[200:203], v[6:9]
	v_mfma_f32_16x16x32_bf16 v[2:5], v[62:65], v[200:203], v[2:5]
	v_mfma_f32_16x16x32_bf16 v[34:37], v[54:57], v[166:169], v[34:37]
	v_mfma_f32_16x16x32_bf16 v[38:41], v[62:65], v[166:169], v[38:41]
	v_mfma_f32_16x16x32_bf16 v[42:45], v[54:57], v[174:177], v[42:45]
	v_mfma_f32_16x16x32_bf16 v[46:49], v[62:65], v[174:177], v[46:49]
	s_setprio 0
	s_barrier
	s_add_u32 s28, s34, 0x160000
	s_addc_u32 s29, s35, 0
	s_mov_b32 m0, s48
	v_lshl_add_u64 v[210:211], s[28:29], 0, v[182:183]
	global_load_lds_dwordx4 v[210:211], off
	v_lshl_add_u64 v[210:211], s[28:29], 0, v[184:185]
	s_mov_b32 m0, s49
	s_nop 0
	global_load_lds_dwordx4 v[210:211], off
	v_add_u32_e32 v62, 0x18400, v208
	v_add_u32_e32 v66, 0x1c400, v208
	ds_read_b128 v[50:53], v62
	ds_read_b128 v[54:57], v62 offset:1024
	ds_read_b128 v[58:61], v62 offset:2048
	ds_read_b128 v[62:65], v62 offset:3072
	ds_read_b128 v[162:165], v66
	ds_read_b128 v[166:169], v66 offset:1024
	ds_read_b128 v[170:173], v66 offset:2048
	ds_read_b128 v[174:177], v66 offset:3072
	ds_read_b128 v[66:69], v207 offset:33792
	ds_read_b128 v[70:73], v207 offset:34816
	ds_read_b128 v[82:85], v207 offset:35840
	ds_read_b128 v[86:89], v207 offset:36864
	ds_read_b128 v[178:181], v207 offset:37888
	ds_read_b128 v[192:195], v207 offset:38912
	ds_read_b128 v[196:199], v207 offset:39936
	ds_read_b128 v[200:203], v207 offset:40960
	s_waitcnt vmcnt(8)
	s_waitcnt lgkmcnt(0)
	s_setprio 1
	s_barrier
	v_mfma_f32_16x16x32_bf16 v[158:161], v[50:53], v[66:69], v[158:161]
	v_mfma_f32_16x16x32_bf16 v[154:157], v[58:61], v[66:69], v[154:157]
	v_mfma_f32_16x16x32_bf16 v[142:145], v[50:53], v[82:85], v[142:145]
	v_mfma_f32_16x16x32_bf16 v[138:141], v[58:61], v[82:85], v[138:141]
	v_mfma_f32_16x16x32_bf16 v[126:129], v[50:53], v[178:181], v[126:129]
	v_mfma_f32_16x16x32_bf16 v[122:125], v[58:61], v[178:181], v[122:125]
	v_mfma_f32_16x16x32_bf16 v[110:113], v[50:53], v[196:199], v[110:113]
	v_mfma_f32_16x16x32_bf16 v[106:109], v[58:61], v[196:199], v[106:109]
	s_setprio 0
	s_setprio 1
	v_mfma_f32_16x16x32_bf16 v[158:161], v[54:57], v[70:73], v[158:161]
	v_mfma_f32_16x16x32_bf16 v[154:157], v[62:65], v[70:73], v[154:157]
	v_mfma_f32_16x16x32_bf16 v[142:145], v[54:57], v[86:89], v[142:145]
	v_mfma_f32_16x16x32_bf16 v[138:141], v[62:65], v[86:89], v[138:141]
	v_mfma_f32_16x16x32_bf16 v[126:129], v[54:57], v[192:195], v[126:129]
	v_mfma_f32_16x16x32_bf16 v[122:125], v[62:65], v[192:195], v[122:125]
	v_mfma_f32_16x16x32_bf16 v[110:113], v[54:57], v[200:203], v[110:113]
	v_mfma_f32_16x16x32_bf16 v[106:109], v[62:65], v[200:203], v[106:109]
	s_setprio 0
	s_setprio 1
	v_mfma_f32_16x16x32_bf16 v[150:153], v[162:165], v[66:69], v[150:153]
	v_mfma_f32_16x16x32_bf16 v[66:69], v[170:173], v[66:69], v[146:149]
	v_mfma_f32_16x16x32_bf16 v[146:149], v[174:177], v[70:73], v[66:69]
	v_mfma_f32_16x16x32_bf16 v[66:69], v[162:165], v[82:85], v[134:137]
	v_mfma_f32_16x16x32_bf16 v[134:137], v[166:169], v[86:89], v[66:69]
	v_mfma_f32_16x16x32_bf16 v[66:69], v[170:173], v[82:85], v[130:133]
	v_mfma_f32_16x16x32_bf16 v[130:133], v[174:177], v[86:89], v[66:69]
	v_mfma_f32_16x16x32_bf16 v[66:69], v[162:165], v[178:181], v[118:121]
	s_setprio 0
	s_setprio 1
	v_mfma_f32_16x16x32_bf16 v[118:121], v[166:169], v[192:195], v[66:69]
	v_mfma_f32_16x16x32_bf16 v[66:69], v[170:173], v[178:181], v[114:117]
	v_mfma_f32_16x16x32_bf16 v[114:117], v[174:177], v[192:195], v[66:69]
	v_mfma_f32_16x16x32_bf16 v[66:69], v[162:165], v[196:199], v[102:105]
	v_mfma_f32_16x16x32_bf16 v[102:105], v[166:169], v[200:203], v[66:69]
	v_mfma_f32_16x16x32_bf16 v[66:69], v[170:173], v[196:199], v[98:101]
	v_mfma_f32_16x16x32_bf16 v[150:153], v[166:169], v[70:73], v[150:153]
	v_mfma_f32_16x16x32_bf16 v[98:101], v[174:177], v[200:203], v[66:69]
	s_setprio 0
	s_barrier
; #define PG8_STAGE(bufoff, gbase, voff) do { _Pragma("unroll") for (int _i = 0; _i < 2; ++_i) \
;         __builtin_amdgcn_global_load_lds((const GAS unsigned*)((const GAS char*)(gbase) + (voff)[_i]), (LAS unsigned*)(lds + (bufoff) + ldsw + _i * 8192), 16, 0, 0); } while (0)
; #define PG8_LDA(dst, b, h) do { _Pragma("unroll") for (int m = 0; m < 4; ++m) _Pragma("unroll") for (int k = 0; k < 2; ++k) dst[m][k] = *(const LAS bf16x8*)(lds + PG8_SA(b, h) + aoff + m * 2048 + k * 1024); } while (0)
; #define PG8_MMA(ai, bj, At, Bt) do { __builtin_amdgcn_s_setprio(1); _Pragma("unroll") for (int m = 0; m < 4; ++m) _Pragma("unroll") for (int n = 0; n < 2; ++n) _Pragma("unroll") for (int k = 0; k < 2; ++k) \
;         acc[ai][bj][m][n] = __builtin_amdgcn_mfma_f32_16x16x32_bf16(Bt[n][k], At[m][k], acc[ai][bj][m][n], 0, 0, 0); __builtin_amdgcn_s_setprio(0); } while (0)
; #define PG8_WAIT_V(n) asm volatile("s_waitcnt vmcnt(" #n ")" ::: "memory")
; #define PG8_WAIT_L(n) asm volatile("s_waitcnt lgkmcnt(" #n ")" ::: "memory")
; #define PG8_BAR __builtin_amdgcn_s_barrier()
; #define PG8_SCHED __builtin_amdgcn_sched_barrier(0)
; template <class Epi, class Sched, bool ALIGN_EPI>
; __device__ __forceinline__ void gemm_phase(LAS unsigned char* lds, const Gemm g, const Sched& S, const Epi& E, int wave_id) {
;     ...
;             PG8_LDA(At, 1, 1); PG8_STAGE(PG8_SB(1, 0), b3, voffB); PG8_STAGE(PG8_SB(1, 1), b3 + hsB, voffB); PG8_STAGE(PG8_SA(1, 0), a3, voffA);
;             PG8_WAIT_V(8); PG8_WAIT_L(0); PG8_BAR; PG8_MMA(1, 0, At, B0); PG8_MMA(1, 1, At, B1); PG8_BAR; PG8_SCHED;
;         }
;         if constexpr (ALIGN_EPI) { if (wr == 0) PG8_BAR; }
	s_mov_b32 m0, s52
	v_lshl_add_u64 v[82:83], v[204:205], 0, s[92:93]
	s_add_u32 s28, s30, 0x160080
	s_nop 0
	global_load_lds_dwordx4 v[82:83], off
	v_lshl_add_u64 v[82:83], v[218:219], 0, s[92:93]
	s_mov_b32 m0, s53
	s_addc_u32 s29, s31, 0
	global_load_lds_dwordx4 v[82:83], off
	v_lshl_add_u64 v[82:83], s[28:29], 0, v[0:1]
	s_mov_b32 m0, s56
	s_nop 0
	global_load_lds_dwordx4 v[82:83], off
	v_lshl_add_u64 v[82:83], s[28:29], 0, v[186:187]
	s_mov_b32 m0, s57
	s_nop 0
	global_load_lds_dwordx4 v[82:83], off
	v_lshl_add_u64 v[82:83], v[220:221], 0, s[92:93]
	s_mov_b32 m0, s54
	s_nop 0
	global_load_lds_dwordx4 v[82:83], off
	v_lshl_add_u64 v[82:83], v[224:225], 0, s[92:93]
	s_mov_b32 m0, s55
	s_nop 0
	global_load_lds_dwordx4 v[82:83], off
	ds_read_b128 v[66:69], v207 offset:50176
	ds_read_b128 v[70:73], v207 offset:51200
	ds_read_b128 v[178:181], v207 offset:52224
	ds_read_b128 v[192:195], v207 offset:53248
	ds_read_b128 v[196:199], v207 offset:54272
	ds_read_b128 v[200:203], v207 offset:55296
	ds_read_b128 v[210:213], v207 offset:56320
	ds_read_b128 v[214:217], v207 offset:57344
	s_waitcnt vmcnt(8)
	s_waitcnt lgkmcnt(0)
	s_setprio 1
	s_barrier
	v_mfma_f32_16x16x32_bf16 v[82:85], v[50:53], v[66:69], v[94:97]
	v_mfma_f32_16x16x32_bf16 v[94:97], v[54:57], v[70:73], v[82:85]
	v_mfma_f32_16x16x32_bf16 v[82:85], v[58:61], v[66:69], v[90:93]
	v_mfma_f32_16x16x32_bf16 v[78:81], v[50:53], v[178:181], v[78:81]
	v_mfma_f32_16x16x32_bf16 v[74:77], v[58:61], v[178:181], v[74:77]
	v_mfma_f32_16x16x32_bf16 v[30:33], v[50:53], v[196:199], v[30:33]
	v_mfma_f32_16x16x32_bf16 v[26:29], v[58:61], v[196:199], v[26:29]
	v_mfma_f32_16x16x32_bf16 v[14:17], v[50:53], v[210:213], v[14:17]
	s_setprio 0
	s_setprio 1
	v_mfma_f32_16x16x32_bf16 v[10:13], v[58:61], v[210:213], v[10:13]
	v_mfma_f32_16x16x32_bf16 v[90:93], v[62:65], v[70:73], v[82:85]
	v_mfma_f32_16x16x32_bf16 v[78:81], v[54:57], v[192:195], v[78:81]
	v_mfma_f32_16x16x32_bf16 v[74:77], v[62:65], v[192:195], v[74:77]
	v_mfma_f32_16x16x32_bf16 v[30:33], v[54:57], v[200:203], v[30:33]
	v_mfma_f32_16x16x32_bf16 v[26:29], v[62:65], v[200:203], v[26:29]
	v_mfma_f32_16x16x32_bf16 v[14:17], v[54:57], v[214:217], v[14:17]
	v_mfma_f32_16x16x32_bf16 v[10:13], v[62:65], v[214:217], v[10:13]
	s_setprio 0
	s_setprio 1
	v_mfma_f32_16x16x32_bf16 v[34:37], v[162:165], v[66:69], v[34:37]
	v_mfma_f32_16x16x32_bf16 v[86:89], v[166:169], v[70:73], v[34:37]
	v_mfma_f32_16x16x32_bf16 v[34:37], v[170:173], v[66:69], v[38:41]
	v_mfma_f32_16x16x32_bf16 v[82:85], v[174:177], v[70:73], v[34:37]
	v_mfma_f32_16x16x32_bf16 v[34:37], v[162:165], v[178:181], v[42:45]
	v_mfma_f32_16x16x32_bf16 v[70:73], v[166:169], v[192:195], v[34:37]
	v_mfma_f32_16x16x32_bf16 v[34:37], v[170:173], v[178:181], v[46:49]
	v_mfma_f32_16x16x32_bf16 v[22:25], v[162:165], v[196:199], v[22:25]
	s_setprio 0
	s_setprio 1
	v_mfma_f32_16x16x32_bf16 v[18:21], v[170:173], v[196:199], v[18:21]
	v_mfma_f32_16x16x32_bf16 v[6:9], v[162:165], v[210:213], v[6:9]
	v_mfma_f32_16x16x32_bf16 v[2:5], v[170:173], v[210:213], v[2:5]
	v_mfma_f32_16x16x32_bf16 v[66:69], v[174:177], v[192:195], v[34:37]
	v_mfma_f32_16x16x32_bf16 v[22:25], v[166:169], v[200:203], v[22:25]
	v_mfma_f32_16x16x32_bf16 v[18:21], v[174:177], v[200:203], v[18:21]
	v_mfma_f32_16x16x32_bf16 v[6:9], v[166:169], v[214:217], v[6:9]
	v_mfma_f32_16x16x32_bf16 v[2:5], v[174:177], v[214:217], v[2:5]
	s_setprio 0
	s_barrier
	s_add_i32 s63, s63, 2
	s_add_u32 s61, s61, 0x100
	s_addc_u32 s62, s62, 0
	s_cmpk_gt_u32 s63, 0x55
	s_mov_b64 s[28:29], s[0:1]
	s_cbranch_scc0 .LBB0_3681
	s_and_b64 vcc, exec, s[22:23]
	s_cbranch_vccz .LBB0_3684
	s_barrier
